# v13: v11 with the epilogue-overlap loop tails restructured (normal iterations fall through: no extra taken branch/compare before the last segment barrier)
# speedup vs baseline: 1.0031x; 1.0031x over previous
.LBB0_912:
	ds_read_b128 v[150:153], v161
	ds_read_b128 v[154:157], v161 offset:1024
	ds_read_b128 v[164:167], v161 offset:2048
	ds_read_b128 v[168:171], v161 offset:3072
	s_add_u32 s20, s48, 0xfff80080
	s_addc_u32 s21, s49, -1
	s_cmp_eq_u32 s47, 28
	s_cselect_b32 s21, s17, s21
	s_cselect_b32 s20, s33, s20
	s_cselect_b32 s51, s15, s45
	s_cselect_b32 s50, s34, s35
	v_lshl_add_u64 v[208:209], s[48:49], 0, v[138:139]
	s_add_i32 m0, s36, 0xc000
	ds_read_b128 v[172:175], v162
	ds_read_b128 v[176:179], v162 offset:1024
	ds_read_b128 v[180:183], v162 offset:2048
	ds_read_b128 v[184:187], v162 offset:3072
	ds_read_b128 v[188:191], v162 offset:4096
	ds_read_b128 v[196:199], v162 offset:5120
	ds_read_b128 v[200:203], v162 offset:6144
	ds_read_b128 v[204:207], v162 offset:7168
	global_load_lds_dwordx4 v[208:209], off
	s_add_i32 m0, s36, 0xe000
	v_lshl_add_u64 v[208:209], s[48:49], 0, v[140:141]
	global_load_lds_dwordx4 v[208:209], off
	s_waitcnt lgkmcnt(8)
	s_barrier
	s_waitcnt lgkmcnt(0)
	s_setprio 1
	v_mfma_f32_16x16x32_bf16 v[124:127], v[150:153], v[172:175], v[124:127]
	v_mfma_f32_16x16x32_bf16 v[120:123], v[164:167], v[172:175], v[120:123]
	v_mfma_f32_16x16x32_bf16 v[108:111], v[150:153], v[180:183], v[108:111]
	v_mfma_f32_16x16x32_bf16 v[104:107], v[164:167], v[180:183], v[104:107]
	v_mfma_f32_16x16x32_bf16 v[92:95], v[150:153], v[188:191], v[92:95]
	v_mfma_f32_16x16x32_bf16 v[88:91], v[164:167], v[188:191], v[88:91]
	v_mfma_f32_16x16x32_bf16 v[76:79], v[150:153], v[200:203], v[76:79]
	v_mfma_f32_16x16x32_bf16 v[72:75], v[164:167], v[200:203], v[72:75]
	v_mfma_f32_16x16x32_bf16 v[124:127], v[154:157], v[176:179], v[124:127]
	v_mfma_f32_16x16x32_bf16 v[120:123], v[168:171], v[176:179], v[120:123]
	v_mfma_f32_16x16x32_bf16 v[108:111], v[154:157], v[184:187], v[108:111]
	v_mfma_f32_16x16x32_bf16 v[104:107], v[168:171], v[184:187], v[104:107]
	v_mfma_f32_16x16x32_bf16 v[92:95], v[154:157], v[196:199], v[92:95]
	v_mfma_f32_16x16x32_bf16 v[88:91], v[168:171], v[196:199], v[88:91]
	v_mfma_f32_16x16x32_bf16 v[76:79], v[154:157], v[204:207], v[76:79]
	v_mfma_f32_16x16x32_bf16 v[72:75], v[168:171], v[204:207], v[72:75]
	s_setprio 0
	s_barrier
	s_add_i32 s65, s62, s23
	v_lshl_add_u64 v[224:225], s[50:51], 0, v[130:131]
	s_mov_b32 m0, s65
	ds_read_b128 v[208:211], v163
	ds_read_b128 v[212:215], v163 offset:1024
	ds_read_b128 v[216:219], v163 offset:2048
	ds_read_b128 v[220:223], v163 offset:3072
	global_load_lds_dwordx4 v[224:225], off
	s_add_i32 m0, s65, 0x2000
	v_lshl_add_u64 v[226:227], s[50:51], 0, v[134:135]
	global_load_lds_dwordx4 v[226:227], off
	s_barrier
	s_waitcnt lgkmcnt(0)
	s_setprio 1
	v_mfma_f32_16x16x32_bf16 v[116:119], v[208:211], v[172:175], v[116:119]
	v_mfma_f32_16x16x32_bf16 v[112:115], v[216:219], v[172:175], v[112:115]
	v_mfma_f32_16x16x32_bf16 v[100:103], v[208:211], v[180:183], v[100:103]
	v_mfma_f32_16x16x32_bf16 v[96:99], v[216:219], v[180:183], v[96:99]
	v_mfma_f32_16x16x32_bf16 v[84:87], v[208:211], v[188:191], v[84:87]
	v_mfma_f32_16x16x32_bf16 v[80:83], v[216:219], v[188:191], v[80:83]
	v_mfma_f32_16x16x32_bf16 v[68:71], v[208:211], v[200:203], v[68:71]
	v_mfma_f32_16x16x32_bf16 v[64:67], v[216:219], v[200:203], v[64:67]
	v_mfma_f32_16x16x32_bf16 v[116:119], v[212:215], v[176:179], v[116:119]
	v_mfma_f32_16x16x32_bf16 v[112:115], v[220:223], v[176:179], v[112:115]
	v_mfma_f32_16x16x32_bf16 v[100:103], v[212:215], v[184:187], v[100:103]
	v_mfma_f32_16x16x32_bf16 v[96:99], v[220:223], v[184:187], v[96:99]
	v_mfma_f32_16x16x32_bf16 v[84:87], v[212:215], v[196:199], v[84:87]
	v_mfma_f32_16x16x32_bf16 v[80:83], v[220:223], v[196:199], v[80:83]
	v_mfma_f32_16x16x32_bf16 v[68:71], v[212:215], v[204:207], v[68:71]
	v_mfma_f32_16x16x32_bf16 v[64:67], v[220:223], v[204:207], v[64:67]
	s_setprio 0
	s_mov_b32 m0, s36
	v_lshl_add_u64 v[228:229], s[20:21], 0, v[128:129]
	s_barrier
	ds_read_b128 v[172:175], v162 offset:16384
	ds_read_b128 v[176:179], v162 offset:17408
	ds_read_b128 v[180:183], v162 offset:18432
	ds_read_b128 v[184:187], v162 offset:19456
	ds_read_b128 v[188:191], v162 offset:20480
	ds_read_b128 v[196:199], v162 offset:21504
	ds_read_b128 v[200:203], v162 offset:22528
	ds_read_b128 v[204:207], v162 offset:23552
	global_load_lds_dwordx4 v[228:229], off
	s_mov_b32 m0, s37
	v_lshl_add_u64 v[230:231], s[20:21], 0, v[132:133]
	global_load_lds_dwordx4 v[230:231], off
	s_barrier
	s_waitcnt lgkmcnt(0)
	s_setprio 1
	v_mfma_f32_16x16x32_bf16 v[60:63], v[150:153], v[172:175], v[60:63]
	v_mfma_f32_16x16x32_bf16 v[56:59], v[164:167], v[172:175], v[56:59]
	v_mfma_f32_16x16x32_bf16 v[44:47], v[150:153], v[180:183], v[44:47]
	v_mfma_f32_16x16x32_bf16 v[40:43], v[164:167], v[180:183], v[40:43]
	v_mfma_f32_16x16x32_bf16 v[28:31], v[150:153], v[188:191], v[28:31]
	v_mfma_f32_16x16x32_bf16 v[24:27], v[164:167], v[188:191], v[24:27]
	v_mfma_f32_16x16x32_bf16 v[12:15], v[150:153], v[200:203], v[12:15]
	v_mfma_f32_16x16x32_bf16 v[8:11], v[164:167], v[200:203], v[8:11]
	v_mfma_f32_16x16x32_bf16 v[60:63], v[154:157], v[176:179], v[60:63]
	v_mfma_f32_16x16x32_bf16 v[56:59], v[168:171], v[176:179], v[56:59]
	v_mfma_f32_16x16x32_bf16 v[44:47], v[154:157], v[184:187], v[44:47]
	v_mfma_f32_16x16x32_bf16 v[40:43], v[168:171], v[184:187], v[40:43]
	v_mfma_f32_16x16x32_bf16 v[28:31], v[154:157], v[196:199], v[28:31]
	v_mfma_f32_16x16x32_bf16 v[24:27], v[168:171], v[196:199], v[24:27]
	v_mfma_f32_16x16x32_bf16 v[12:15], v[154:157], v[204:207], v[12:15]
	v_mfma_f32_16x16x32_bf16 v[8:11], v[168:171], v[204:207], v[8:11]
	s_setprio 0
	s_barrier
	s_add_u32 s66, s50, 0x80000
	s_addc_u32 s67, s51, 0
	s_add_i32 s65, s63, s23
	s_mov_b32 m0, s65
	v_lshl_add_u64 v[150:151], s[66:67], 0, v[130:131]
	global_load_lds_dwordx4 v[150:151], off
	s_add_i32 m0, s65, 0x2000
	v_lshl_add_u64 v[150:151], s[66:67], 0, v[134:135]
	global_load_lds_dwordx4 v[150:151], off
	s_waitcnt vmcnt(6)
	s_barrier
	s_setprio 1
	v_mfma_f32_16x16x32_bf16 v[52:55], v[208:211], v[172:175], v[52:55]
	v_mfma_f32_16x16x32_bf16 v[48:51], v[216:219], v[172:175], v[48:51]
	v_mfma_f32_16x16x32_bf16 v[36:39], v[208:211], v[180:183], v[36:39]
	v_mfma_f32_16x16x32_bf16 v[32:35], v[216:219], v[180:183], v[32:35]
	v_mfma_f32_16x16x32_bf16 v[20:23], v[208:211], v[188:191], v[20:23]
	v_mfma_f32_16x16x32_bf16 v[16:19], v[216:219], v[188:191], v[16:19]
	v_mfma_f32_16x16x32_bf16 v[4:7], v[208:211], v[200:203], v[4:7]
	v_mfma_f32_16x16x32_bf16 v[0:3], v[216:219], v[200:203], v[0:3]
	v_mfma_f32_16x16x32_bf16 v[52:55], v[212:215], v[176:179], v[52:55]
	v_mfma_f32_16x16x32_bf16 v[48:51], v[220:223], v[176:179], v[48:51]
	v_mfma_f32_16x16x32_bf16 v[36:39], v[212:215], v[184:187], v[36:39]
	v_mfma_f32_16x16x32_bf16 v[32:35], v[220:223], v[184:187], v[32:35]
	v_mfma_f32_16x16x32_bf16 v[20:23], v[212:215], v[196:199], v[20:23]
	v_mfma_f32_16x16x32_bf16 v[16:19], v[220:223], v[196:199], v[16:19]
	v_mfma_f32_16x16x32_bf16 v[4:7], v[212:215], v[204:207], v[4:7]
	v_mfma_f32_16x16x32_bf16 v[0:3], v[220:223], v[204:207], v[0:3]
	s_setprio 0
	s_add_i32 s65, 0, 0x18000
	v_add_u32_e32 v136, s65, v158
	s_barrier
	ds_read_b128 v[150:153], v136
	ds_read_b128 v[154:157], v136 offset:1024
	ds_read_b128 v[164:167], v136 offset:2048
	ds_read_b128 v[168:171], v136 offset:3072
	s_add_u32 s20, s20, 0x80000
	s_addc_u32 s21, s21, 0
	s_mov_b32 m0, s38
	v_lshl_add_u64 v[208:209], s[20:21], 0, v[128:129]
	ds_read_b128 v[172:175], v162 offset:32768
	ds_read_b128 v[176:179], v162 offset:33792
	ds_read_b128 v[180:183], v162 offset:34816
	ds_read_b128 v[184:187], v162 offset:35840
	ds_read_b128 v[188:191], v162 offset:36864
	ds_read_b128 v[196:199], v162 offset:37888
	ds_read_b128 v[200:203], v162 offset:38912
	ds_read_b128 v[204:207], v162 offset:39936
	global_load_lds_dwordx4 v[208:209], off
	s_mov_b32 m0, s39
	v_lshl_add_u64 v[208:209], s[20:21], 0, v[132:133]
	global_load_lds_dwordx4 v[208:209], off
	s_waitcnt lgkmcnt(8)
	s_barrier
	s_waitcnt lgkmcnt(0)
	s_setprio 1
	v_mfma_f32_16x16x32_bf16 v[124:127], v[150:153], v[172:175], v[124:127]
	v_mfma_f32_16x16x32_bf16 v[120:123], v[164:167], v[172:175], v[120:123]
	v_mfma_f32_16x16x32_bf16 v[108:111], v[150:153], v[180:183], v[108:111]
	v_mfma_f32_16x16x32_bf16 v[104:107], v[164:167], v[180:183], v[104:107]
	v_mfma_f32_16x16x32_bf16 v[92:95], v[150:153], v[188:191], v[92:95]
	v_mfma_f32_16x16x32_bf16 v[88:91], v[164:167], v[188:191], v[88:91]
	v_mfma_f32_16x16x32_bf16 v[76:79], v[150:153], v[200:203], v[76:79]
	v_mfma_f32_16x16x32_bf16 v[72:75], v[164:167], v[200:203], v[72:75]
	v_mfma_f32_16x16x32_bf16 v[124:127], v[154:157], v[176:179], v[124:127]
	v_mfma_f32_16x16x32_bf16 v[120:123], v[168:171], v[176:179], v[120:123]
	v_mfma_f32_16x16x32_bf16 v[108:111], v[154:157], v[184:187], v[108:111]
	v_mfma_f32_16x16x32_bf16 v[104:107], v[168:171], v[184:187], v[104:107]
	v_mfma_f32_16x16x32_bf16 v[92:95], v[154:157], v[196:199], v[92:95]
	v_mfma_f32_16x16x32_bf16 v[88:91], v[168:171], v[196:199], v[88:91]
	v_mfma_f32_16x16x32_bf16 v[76:79], v[154:157], v[204:207], v[76:79]
	v_mfma_f32_16x16x32_bf16 v[72:75], v[168:171], v[204:207], v[72:75]
	s_setprio 0
	s_barrier
	s_add_i32 s66, 0, 0x1c000
	s_add_i32 s20, s65, s23
	v_add_u32_e32 v136, s66, v158
	v_lshl_add_u64 v[224:225], v[224:225], 0, s[10:11]
	s_mov_b32 m0, s20
	ds_read_b128 v[208:211], v136
	ds_read_b128 v[212:215], v136 offset:1024
	ds_read_b128 v[216:219], v136 offset:2048
	ds_read_b128 v[220:223], v136 offset:3072
	global_load_lds_dwordx4 v[224:225], off
	s_add_i32 m0, s20, 0x2000
	v_lshl_add_u64 v[224:225], v[226:227], 0, s[10:11]
	global_load_lds_dwordx4 v[224:225], off
	s_barrier
	s_waitcnt lgkmcnt(0)
	s_setprio 1
	v_mfma_f32_16x16x32_bf16 v[116:119], v[208:211], v[172:175], v[116:119]
	v_mfma_f32_16x16x32_bf16 v[112:115], v[216:219], v[172:175], v[112:115]
	v_mfma_f32_16x16x32_bf16 v[100:103], v[208:211], v[180:183], v[100:103]
	v_mfma_f32_16x16x32_bf16 v[96:99], v[216:219], v[180:183], v[96:99]
	v_mfma_f32_16x16x32_bf16 v[84:87], v[208:211], v[188:191], v[84:87]
	v_mfma_f32_16x16x32_bf16 v[80:83], v[216:219], v[188:191], v[80:83]
	v_mfma_f32_16x16x32_bf16 v[68:71], v[208:211], v[200:203], v[68:71]
	v_mfma_f32_16x16x32_bf16 v[64:67], v[216:219], v[200:203], v[64:67]
	v_mfma_f32_16x16x32_bf16 v[116:119], v[212:215], v[176:179], v[116:119]
	v_mfma_f32_16x16x32_bf16 v[112:115], v[220:223], v[176:179], v[112:115]
	v_mfma_f32_16x16x32_bf16 v[100:103], v[212:215], v[184:187], v[100:103]
	v_mfma_f32_16x16x32_bf16 v[96:99], v[220:223], v[184:187], v[96:99]
	v_mfma_f32_16x16x32_bf16 v[84:87], v[212:215], v[196:199], v[84:87]
	v_mfma_f32_16x16x32_bf16 v[80:83], v[220:223], v[196:199], v[80:83]
	v_mfma_f32_16x16x32_bf16 v[68:71], v[212:215], v[204:207], v[68:71]
	v_mfma_f32_16x16x32_bf16 v[64:67], v[220:223], v[204:207], v[64:67]
	s_setprio 0
	s_mov_b32 m0, s58
	v_lshl_add_u64 v[224:225], v[228:229], 0, s[10:11]
	s_barrier
	ds_read_b128 v[172:175], v162 offset:49152
	ds_read_b128 v[176:179], v162 offset:50176
	ds_read_b128 v[180:183], v162 offset:51200
	ds_read_b128 v[184:187], v162 offset:52224
	ds_read_b128 v[188:191], v162 offset:53248
	ds_read_b128 v[196:199], v162 offset:54272
	ds_read_b128 v[200:203], v162 offset:55296
	ds_read_b128 v[204:207], v162 offset:56320
	global_load_lds_dwordx4 v[224:225], off
	s_mov_b32 m0, s59
	v_lshl_add_u64 v[224:225], v[230:231], 0, s[10:11]
	global_load_lds_dwordx4 v[224:225], off
	s_barrier
	s_waitcnt lgkmcnt(0)
	s_setprio 1
	v_mfma_f32_16x16x32_bf16 v[60:63], v[150:153], v[172:175], v[60:63]
	v_mfma_f32_16x16x32_bf16 v[56:59], v[164:167], v[172:175], v[56:59]
	v_mfma_f32_16x16x32_bf16 v[44:47], v[150:153], v[180:183], v[44:47]
	v_mfma_f32_16x16x32_bf16 v[40:43], v[164:167], v[180:183], v[40:43]
	v_mfma_f32_16x16x32_bf16 v[28:31], v[150:153], v[188:191], v[28:31]
	v_mfma_f32_16x16x32_bf16 v[24:27], v[164:167], v[188:191], v[24:27]
	v_mfma_f32_16x16x32_bf16 v[12:15], v[150:153], v[200:203], v[12:15]
	v_mfma_f32_16x16x32_bf16 v[8:11], v[164:167], v[200:203], v[8:11]
	v_mfma_f32_16x16x32_bf16 v[60:63], v[154:157], v[176:179], v[60:63]
	v_mfma_f32_16x16x32_bf16 v[56:59], v[168:171], v[176:179], v[56:59]
	v_mfma_f32_16x16x32_bf16 v[44:47], v[154:157], v[184:187], v[44:47]
	v_mfma_f32_16x16x32_bf16 v[40:43], v[168:171], v[184:187], v[40:43]
	v_mfma_f32_16x16x32_bf16 v[28:31], v[154:157], v[196:199], v[28:31]
	v_mfma_f32_16x16x32_bf16 v[24:27], v[168:171], v[196:199], v[24:27]
	v_mfma_f32_16x16x32_bf16 v[12:15], v[154:157], v[204:207], v[12:15]
	v_mfma_f32_16x16x32_bf16 v[8:11], v[168:171], v[204:207], v[8:11]
	s_setprio 0
	s_barrier
	s_add_u32 s20, s50, 0x80080
	s_addc_u32 s21, s51, 0
	s_add_i32 s50, s66, s23
	s_mov_b32 m0, s50
	v_lshl_add_u64 v[150:151], s[20:21], 0, v[130:131]
	global_load_lds_dwordx4 v[150:151], off
	s_add_i32 m0, s50, 0x2000
	v_lshl_add_u64 v[150:151], s[20:21], 0, v[134:135]
	global_load_lds_dwordx4 v[150:151], off
	s_waitcnt vmcnt(6)
	s_barrier
	s_setprio 1
	v_mfma_f32_16x16x32_bf16 v[52:55], v[208:211], v[172:175], v[52:55]
	v_mfma_f32_16x16x32_bf16 v[48:51], v[216:219], v[172:175], v[48:51]
	v_mfma_f32_16x16x32_bf16 v[36:39], v[208:211], v[180:183], v[36:39]
	v_mfma_f32_16x16x32_bf16 v[32:35], v[216:219], v[180:183], v[32:35]
	v_mfma_f32_16x16x32_bf16 v[20:23], v[208:211], v[188:191], v[20:23]
	v_mfma_f32_16x16x32_bf16 v[16:19], v[216:219], v[188:191], v[16:19]
	v_mfma_f32_16x16x32_bf16 v[4:7], v[208:211], v[200:203], v[4:7]
	v_mfma_f32_16x16x32_bf16 v[0:3], v[216:219], v[200:203], v[0:3]
	v_mfma_f32_16x16x32_bf16 v[52:55], v[212:215], v[176:179], v[52:55]
	v_mfma_f32_16x16x32_bf16 v[48:51], v[220:223], v[176:179], v[48:51]
	v_mfma_f32_16x16x32_bf16 v[36:39], v[212:215], v[184:187], v[36:39]
	v_mfma_f32_16x16x32_bf16 v[32:35], v[220:223], v[184:187], v[32:35]
	v_mfma_f32_16x16x32_bf16 v[20:23], v[212:215], v[196:199], v[20:23]
	v_mfma_f32_16x16x32_bf16 v[16:19], v[220:223], v[196:199], v[16:19]
	v_mfma_f32_16x16x32_bf16 v[4:7], v[212:215], v[204:207], v[4:7]
	v_mfma_f32_16x16x32_bf16 v[0:3], v[220:223], v[204:207], v[0:3]
	s_setprio 0
	s_add_i32 s47, s47, 2
	s_add_u32 s48, s48, 0x100
	s_addc_u32 s49, s49, 0
	s_add_u32 s35, s35, 0x100
	s_addc_u32 s45, s45, 0
	s_cmp_gt_u32 s47, 29
	s_cbranch_scc1 .Lepi_last_about
	s_barrier
	s_branch .LBB0_912
.Lepi_last_about:
	s_cmp_lg_u32 s57, 64
	s_cbranch_scc1 .Lepi_bar_about
	s_lshl_b32 s15, s46, 8
	s_add_i32 s15, s15, s57
	v_or_b32_e32 v154, s15, v147
	s_add_i32 s17, s15, 0xffffe000
	v_lshl_or_b32 v150, s44, 8, v160
	s_lshr_b32 s17, s17, 12
	v_lshlrev_b32_e32 v151, 13, v154
	s_add_i32 s17, s17, 1
	s_sub_u32 s34, s54, 0x4000000
	s_subb_u32 s35, s55, 0
	v_lshlrev_b32_e32 v152, 12, v154
	s_cmp_gt_i32 s15, s64
	s_cselect_b32 s34, s34, s52
	s_cselect_b32 s35, s35, s53
	s_cselect_b32 s17, s17, 0
	s_mul_i32 s17, s17, 0xc000
	v_lshl_add_u32 v151, v150, 2, v151
	s_add_u32 s20, s8, s17
	s_addc_u32 s21, s9, 0
	v_lshl_add_u32 v152, v150, 1, v152
	v_lshlrev_b32_e32 v153, 2, v150
	s_nop 0
	global_load_dwordx4 v[196:199], v153, s[20:21]
	global_load_dwordx4 v[200:203], v153, s[20:21] offset:16
	global_load_dwordx4 v[204:207], v153, s[20:21] offset:512
	global_load_dwordx4 v[208:211], v153, s[20:21] offset:528
	global_load_dwordx4 v[164:167], v151, s[34:35]
	global_load_dwordx4 v[168:171], v151, s[34:35] offset:16
	global_load_dwordx4 v[172:175], v151, s[34:35] offset:512
	global_load_dwordx4 v[176:179], v151, s[34:35] offset:528
	v_add_u32_e32 v155, 0x20000, v151
	global_load_dwordx4 v[180:183], v155, s[34:35]
	global_load_dwordx4 v[184:187], v155, s[34:35] offset:16
	global_load_dwordx4 v[188:191], v155, s[34:35] offset:512
	global_load_dwordx4 v[212:215], v155, s[34:35] offset:528
	v_add_u32_e32 v155, 0x40000, v151
	global_load_dwordx4 v[216:219], v155, s[34:35]
	global_load_dwordx4 v[220:223], v155, s[34:35] offset:16
	global_load_dwordx4 v[224:227], v155, s[34:35] offset:512
	global_load_dwordx4 v[228:231], v155, s[34:35] offset:528
	v_add_u32_e32 v155, 0x60000, v151
	global_load_dwordx4 v[236:239], v155, s[34:35]
	global_load_dwordx4 v[240:243], v155, s[34:35] offset:16
	global_load_dwordx4 v[244:247], v155, s[34:35] offset:512
	global_load_dwordx4 v[248:251], v155, s[34:35] offset:528
	s_waitcnt vmcnt(0)
	v_pk_fma_f32 v[124:125], v[124:125], v[196:197], v[164:165]
	v_pk_fma_f32 v[126:127], v[126:127], v[198:199], v[166:167]
	v_pk_fma_f32 v[120:121], v[120:121], v[200:201], v[168:169]
	v_pk_fma_f32 v[122:123], v[122:123], v[202:203], v[170:171]
	v_cvt_pk_bf16_f32 v123, v122, v123
	v_cvt_pk_bf16_f32 v122, v120, v121
	v_cvt_pk_bf16_f32 v121, v126, v127
	v_cvt_pk_bf16_f32 v120, v124, v125
	global_store_dwordx4 v152, v[120:123], s[74:75]
	v_pk_fma_f32 v[116:117], v[116:117], v[204:205], v[172:173]
	v_pk_fma_f32 v[118:119], v[118:119], v[206:207], v[174:175]
	v_pk_fma_f32 v[112:113], v[112:113], v[208:209], v[176:177]
	v_pk_fma_f32 v[114:115], v[114:115], v[210:211], v[178:179]
	v_cvt_pk_bf16_f32 v115, v114, v115
	v_cvt_pk_bf16_f32 v114, v112, v113
	v_cvt_pk_bf16_f32 v113, v118, v119
	v_cvt_pk_bf16_f32 v112, v116, v117
	global_store_dwordx4 v152, v[112:115], s[74:75] offset:256
	v_pk_fma_f32 v[108:109], v[108:109], v[196:197], v[180:181]
	v_pk_fma_f32 v[110:111], v[110:111], v[198:199], v[182:183]
	v_pk_fma_f32 v[104:105], v[104:105], v[200:201], v[184:185]
	v_pk_fma_f32 v[106:107], v[106:107], v[202:203], v[186:187]
	v_cvt_pk_bf16_f32 v107, v106, v107
	v_cvt_pk_bf16_f32 v106, v104, v105
	v_cvt_pk_bf16_f32 v105, v110, v111
	v_cvt_pk_bf16_f32 v104, v108, v109
	v_add_u32_e32 v156, 0x10000, v152
	global_store_dwordx4 v156, v[104:107], s[74:75]
	v_pk_fma_f32 v[100:101], v[100:101], v[204:205], v[188:189]
	v_pk_fma_f32 v[102:103], v[102:103], v[206:207], v[190:191]
	v_pk_fma_f32 v[96:97], v[96:97], v[208:209], v[212:213]
	v_pk_fma_f32 v[98:99], v[98:99], v[210:211], v[214:215]
	v_cvt_pk_bf16_f32 v99, v98, v99
	v_cvt_pk_bf16_f32 v98, v96, v97
	v_cvt_pk_bf16_f32 v97, v102, v103
	v_cvt_pk_bf16_f32 v96, v100, v101
	v_add_u32_e32 v156, 0x10000, v152
	global_store_dwordx4 v156, v[96:99], s[74:75] offset:256
	v_add_u32_e32 v155, 0x100000, v151
	global_load_dwordx4 v[164:167], v155, s[34:35]
	global_load_dwordx4 v[168:171], v155, s[34:35] offset:16
	global_load_dwordx4 v[172:175], v155, s[34:35] offset:512
	global_load_dwordx4 v[176:179], v155, s[34:35] offset:528
	v_add_u32_e32 v155, 0x120000, v151
	global_load_dwordx4 v[180:183], v155, s[34:35]
	global_load_dwordx4 v[184:187], v155, s[34:35] offset:16
	global_load_dwordx4 v[188:191], v155, s[34:35] offset:512
	global_load_dwordx4 v[212:215], v155, s[34:35] offset:528
	v_pk_fma_f32 v[92:93], v[92:93], v[196:197], v[216:217]
	v_pk_fma_f32 v[94:95], v[94:95], v[198:199], v[218:219]
	v_pk_fma_f32 v[88:89], v[88:89], v[200:201], v[220:221]
	v_pk_fma_f32 v[90:91], v[90:91], v[202:203], v[222:223]
	v_cvt_pk_bf16_f32 v91, v90, v91
	v_cvt_pk_bf16_f32 v90, v88, v89
	v_cvt_pk_bf16_f32 v89, v94, v95
	v_cvt_pk_bf16_f32 v88, v92, v93
	v_add_u32_e32 v156, 0x20000, v152
	global_store_dwordx4 v156, v[88:91], s[74:75]
	v_pk_fma_f32 v[84:85], v[84:85], v[204:205], v[224:225]
	v_pk_fma_f32 v[86:87], v[86:87], v[206:207], v[226:227]
	v_pk_fma_f32 v[80:81], v[80:81], v[208:209], v[228:229]
	v_pk_fma_f32 v[82:83], v[82:83], v[210:211], v[230:231]
	v_cvt_pk_bf16_f32 v83, v82, v83
	v_cvt_pk_bf16_f32 v82, v80, v81
	v_cvt_pk_bf16_f32 v81, v86, v87
	v_cvt_pk_bf16_f32 v80, v84, v85
	v_add_u32_e32 v156, 0x20000, v152
	global_store_dwordx4 v156, v[80:83], s[74:75] offset:256
	v_pk_fma_f32 v[76:77], v[76:77], v[196:197], v[236:237]
	v_pk_fma_f32 v[78:79], v[78:79], v[198:199], v[238:239]
	v_pk_fma_f32 v[72:73], v[72:73], v[200:201], v[240:241]
	v_pk_fma_f32 v[74:75], v[74:75], v[202:203], v[242:243]
	v_cvt_pk_bf16_f32 v75, v74, v75
	v_cvt_pk_bf16_f32 v74, v72, v73
	v_cvt_pk_bf16_f32 v73, v78, v79
	v_cvt_pk_bf16_f32 v72, v76, v77
	v_add_u32_e32 v156, 0x30000, v152
	global_store_dwordx4 v156, v[72:75], s[74:75]
	v_pk_fma_f32 v[68:69], v[68:69], v[204:205], v[244:245]
	v_pk_fma_f32 v[70:71], v[70:71], v[206:207], v[246:247]
	v_pk_fma_f32 v[64:65], v[64:65], v[208:209], v[248:249]
	v_pk_fma_f32 v[66:67], v[66:67], v[210:211], v[250:251]
	v_cvt_pk_bf16_f32 v67, v66, v67
	v_cvt_pk_bf16_f32 v66, v64, v65
	v_cvt_pk_bf16_f32 v65, v70, v71
	v_cvt_pk_bf16_f32 v64, v68, v69
	v_add_u32_e32 v156, 0x30000, v152
	global_store_dwordx4 v156, v[64:67], s[74:75] offset:256
	v_add_u32_e32 v155, 0x140000, v151
	global_load_dwordx4 v[216:219], v155, s[34:35]
	global_load_dwordx4 v[220:223], v155, s[34:35] offset:16
	global_load_dwordx4 v[224:227], v155, s[34:35] offset:512
	global_load_dwordx4 v[228:231], v155, s[34:35] offset:528
	v_add_u32_e32 v155, 0x160000, v151
	global_load_dwordx4 v[236:239], v155, s[34:35]
	global_load_dwordx4 v[240:243], v155, s[34:35] offset:16
	global_load_dwordx4 v[244:247], v155, s[34:35] offset:512
	global_load_dwordx4 v[248:251], v155, s[34:35] offset:528
	s_waitcnt vmcnt(0)
	v_pk_fma_f32 v[60:61], v[60:61], v[196:197], v[164:165]
	v_pk_fma_f32 v[62:63], v[62:63], v[198:199], v[166:167]
	v_pk_fma_f32 v[56:57], v[56:57], v[200:201], v[168:169]
	v_pk_fma_f32 v[58:59], v[58:59], v[202:203], v[170:171]
	v_cvt_pk_bf16_f32 v59, v58, v59
	v_cvt_pk_bf16_f32 v58, v56, v57
	v_cvt_pk_bf16_f32 v57, v62, v63
	v_cvt_pk_bf16_f32 v56, v60, v61
	v_add_u32_e32 v156, 0x80000, v152
	global_store_dwordx4 v156, v[56:59], s[74:75]
	v_pk_fma_f32 v[52:53], v[52:53], v[204:205], v[172:173]
	v_pk_fma_f32 v[54:55], v[54:55], v[206:207], v[174:175]
	v_pk_fma_f32 v[48:49], v[48:49], v[208:209], v[176:177]
	v_pk_fma_f32 v[50:51], v[50:51], v[210:211], v[178:179]
	v_cvt_pk_bf16_f32 v51, v50, v51
	v_cvt_pk_bf16_f32 v50, v48, v49
	v_cvt_pk_bf16_f32 v49, v54, v55
	v_cvt_pk_bf16_f32 v48, v52, v53
	v_add_u32_e32 v156, 0x80000, v152
	global_store_dwordx4 v156, v[48:51], s[74:75] offset:256
	v_pk_fma_f32 v[44:45], v[44:45], v[196:197], v[180:181]
	v_pk_fma_f32 v[46:47], v[46:47], v[198:199], v[182:183]
	v_pk_fma_f32 v[40:41], v[40:41], v[200:201], v[184:185]
	v_pk_fma_f32 v[42:43], v[42:43], v[202:203], v[186:187]
	v_cvt_pk_bf16_f32 v43, v42, v43
	v_cvt_pk_bf16_f32 v42, v40, v41
	v_cvt_pk_bf16_f32 v41, v46, v47
	v_cvt_pk_bf16_f32 v40, v44, v45
	v_add_u32_e32 v156, 0x90000, v152
	global_store_dwordx4 v156, v[40:43], s[74:75]
	v_pk_fma_f32 v[36:37], v[36:37], v[204:205], v[188:189]
	v_pk_fma_f32 v[38:39], v[38:39], v[206:207], v[190:191]
	v_pk_fma_f32 v[32:33], v[32:33], v[208:209], v[212:213]
	v_pk_fma_f32 v[34:35], v[34:35], v[210:211], v[214:215]
	v_cvt_pk_bf16_f32 v35, v34, v35
	v_cvt_pk_bf16_f32 v34, v32, v33
	v_cvt_pk_bf16_f32 v33, v38, v39
	v_cvt_pk_bf16_f32 v32, v36, v37
	v_add_u32_e32 v156, 0x90000, v152
	global_store_dwordx4 v156, v[32:35], s[74:75] offset:256
	v_pk_fma_f32 v[28:29], v[28:29], v[196:197], v[216:217]
	v_pk_fma_f32 v[30:31], v[30:31], v[198:199], v[218:219]
	v_pk_fma_f32 v[24:25], v[24:25], v[200:201], v[220:221]
	v_pk_fma_f32 v[26:27], v[26:27], v[202:203], v[222:223]
	v_cvt_pk_bf16_f32 v27, v26, v27
	v_cvt_pk_bf16_f32 v26, v24, v25
	v_cvt_pk_bf16_f32 v25, v30, v31
	v_cvt_pk_bf16_f32 v24, v28, v29
	v_add_u32_e32 v156, 0xa0000, v152
	global_store_dwordx4 v156, v[24:27], s[74:75]
	v_pk_fma_f32 v[20:21], v[20:21], v[204:205], v[224:225]
	v_pk_fma_f32 v[22:23], v[22:23], v[206:207], v[226:227]
	v_pk_fma_f32 v[16:17], v[16:17], v[208:209], v[228:229]
	v_pk_fma_f32 v[18:19], v[18:19], v[210:211], v[230:231]
	v_cvt_pk_bf16_f32 v19, v18, v19
	v_cvt_pk_bf16_f32 v18, v16, v17
	v_cvt_pk_bf16_f32 v17, v22, v23
	v_cvt_pk_bf16_f32 v16, v20, v21
	v_add_u32_e32 v156, 0xa0000, v152
	global_store_dwordx4 v156, v[16:19], s[74:75] offset:256
	v_pk_fma_f32 v[12:13], v[12:13], v[196:197], v[236:237]
	v_pk_fma_f32 v[14:15], v[14:15], v[198:199], v[238:239]
	v_pk_fma_f32 v[8:9], v[8:9], v[200:201], v[240:241]
	v_pk_fma_f32 v[10:11], v[10:11], v[202:203], v[242:243]
	v_cvt_pk_bf16_f32 v11, v10, v11
	v_cvt_pk_bf16_f32 v10, v8, v9
	v_cvt_pk_bf16_f32 v9, v14, v15
	v_cvt_pk_bf16_f32 v8, v12, v13
	v_add_u32_e32 v156, 0xb0000, v152
	global_store_dwordx4 v156, v[8:11], s[74:75]
	v_pk_fma_f32 v[4:5], v[4:5], v[204:205], v[244:245]
	v_pk_fma_f32 v[6:7], v[6:7], v[206:207], v[246:247]
	v_pk_fma_f32 v[0:1], v[0:1], v[208:209], v[248:249]
	v_pk_fma_f32 v[2:3], v[2:3], v[210:211], v[250:251]
	v_cvt_pk_bf16_f32 v3, v2, v3
	v_cvt_pk_bf16_f32 v2, v0, v1
	v_cvt_pk_bf16_f32 v1, v6, v7
	v_cvt_pk_bf16_f32 v0, v4, v5
	v_add_u32_e32 v156, 0xb0000, v152
	global_store_dwordx4 v156, v[0:3], s[74:75] offset:256
.Lepi_bar_about:
	s_barrier
	s_cmp_lg_u32 s57, 0
	s_cbranch_scc1 .Lepi_g0done_about
	s_lshl_b32 s15, s46, 8
	s_add_i32 s15, s15, s57
	v_or_b32_e32 v154, s15, v147
	s_add_i32 s17, s15, 0xffffe000
	v_lshl_or_b32 v150, s44, 8, v160
	s_lshr_b32 s17, s17, 12
	v_lshlrev_b32_e32 v151, 13, v154
	s_add_i32 s17, s17, 1
	s_sub_u32 s34, s54, 0x4000000
	s_subb_u32 s35, s55, 0
	v_lshlrev_b32_e32 v152, 12, v154
	s_cmp_gt_i32 s15, s64
	s_cselect_b32 s34, s34, s52
	s_cselect_b32 s35, s35, s53
	s_cselect_b32 s17, s17, 0
	s_mul_i32 s17, s17, 0xc000
	v_lshl_add_u32 v151, v150, 2, v151
	s_add_u32 s20, s8, s17
	s_addc_u32 s21, s9, 0
	v_lshl_add_u32 v152, v150, 1, v152
	v_lshlrev_b32_e32 v153, 2, v150
	s_nop 0
	global_load_dwordx4 v[196:199], v153, s[20:21]
	global_load_dwordx4 v[200:203], v153, s[20:21] offset:16
	global_load_dwordx4 v[204:207], v153, s[20:21] offset:512
	global_load_dwordx4 v[208:211], v153, s[20:21] offset:528
	global_load_dwordx4 v[164:167], v151, s[34:35]
	global_load_dwordx4 v[168:171], v151, s[34:35] offset:16
	global_load_dwordx4 v[172:175], v151, s[34:35] offset:512
	global_load_dwordx4 v[176:179], v151, s[34:35] offset:528
	v_add_u32_e32 v155, 0x20000, v151
	global_load_dwordx4 v[180:183], v155, s[34:35]
	global_load_dwordx4 v[184:187], v155, s[34:35] offset:16
	global_load_dwordx4 v[188:191], v155, s[34:35] offset:512
	global_load_dwordx4 v[212:215], v155, s[34:35] offset:528
	v_add_u32_e32 v155, 0x40000, v151
	global_load_dwordx4 v[216:219], v155, s[34:35]
	global_load_dwordx4 v[220:223], v155, s[34:35] offset:16
	global_load_dwordx4 v[224:227], v155, s[34:35] offset:512
	global_load_dwordx4 v[228:231], v155, s[34:35] offset:528
	v_add_u32_e32 v155, 0x60000, v151
	global_load_dwordx4 v[236:239], v155, s[34:35]
	global_load_dwordx4 v[240:243], v155, s[34:35] offset:16
	global_load_dwordx4 v[244:247], v155, s[34:35] offset:512
	global_load_dwordx4 v[248:251], v155, s[34:35] offset:528
	s_waitcnt vmcnt(0)
	v_pk_fma_f32 v[124:125], v[124:125], v[196:197], v[164:165]
	v_pk_fma_f32 v[126:127], v[126:127], v[198:199], v[166:167]
	v_pk_fma_f32 v[120:121], v[120:121], v[200:201], v[168:169]
	v_pk_fma_f32 v[122:123], v[122:123], v[202:203], v[170:171]
	v_cvt_pk_bf16_f32 v123, v122, v123
	v_cvt_pk_bf16_f32 v122, v120, v121
	v_cvt_pk_bf16_f32 v121, v126, v127
	v_cvt_pk_bf16_f32 v120, v124, v125
	global_store_dwordx4 v152, v[120:123], s[74:75]
	v_pk_fma_f32 v[116:117], v[116:117], v[204:205], v[172:173]
	v_pk_fma_f32 v[118:119], v[118:119], v[206:207], v[174:175]
	v_pk_fma_f32 v[112:113], v[112:113], v[208:209], v[176:177]
	v_pk_fma_f32 v[114:115], v[114:115], v[210:211], v[178:179]
	v_cvt_pk_bf16_f32 v115, v114, v115
	v_cvt_pk_bf16_f32 v114, v112, v113
	v_cvt_pk_bf16_f32 v113, v118, v119
	v_cvt_pk_bf16_f32 v112, v116, v117
	global_store_dwordx4 v152, v[112:115], s[74:75] offset:256
	v_pk_fma_f32 v[108:109], v[108:109], v[196:197], v[180:181]
	v_pk_fma_f32 v[110:111], v[110:111], v[198:199], v[182:183]
	v_pk_fma_f32 v[104:105], v[104:105], v[200:201], v[184:185]
	v_pk_fma_f32 v[106:107], v[106:107], v[202:203], v[186:187]
	v_cvt_pk_bf16_f32 v107, v106, v107
	v_cvt_pk_bf16_f32 v106, v104, v105
	v_cvt_pk_bf16_f32 v105, v110, v111
	v_cvt_pk_bf16_f32 v104, v108, v109
	v_add_u32_e32 v156, 0x10000, v152
	global_store_dwordx4 v156, v[104:107], s[74:75]
	v_pk_fma_f32 v[100:101], v[100:101], v[204:205], v[188:189]
	v_pk_fma_f32 v[102:103], v[102:103], v[206:207], v[190:191]
	v_pk_fma_f32 v[96:97], v[96:97], v[208:209], v[212:213]
	v_pk_fma_f32 v[98:99], v[98:99], v[210:211], v[214:215]
	v_cvt_pk_bf16_f32 v99, v98, v99
	v_cvt_pk_bf16_f32 v98, v96, v97
	v_cvt_pk_bf16_f32 v97, v102, v103
	v_cvt_pk_bf16_f32 v96, v100, v101
	v_add_u32_e32 v156, 0x10000, v152
	global_store_dwordx4 v156, v[96:99], s[74:75] offset:256
	v_add_u32_e32 v155, 0x100000, v151
	global_load_dwordx4 v[164:167], v155, s[34:35]
	global_load_dwordx4 v[168:171], v155, s[34:35] offset:16
	global_load_dwordx4 v[172:175], v155, s[34:35] offset:512
	global_load_dwordx4 v[176:179], v155, s[34:35] offset:528
	v_add_u32_e32 v155, 0x120000, v151
	global_load_dwordx4 v[180:183], v155, s[34:35]
	global_load_dwordx4 v[184:187], v155, s[34:35] offset:16
	global_load_dwordx4 v[188:191], v155, s[34:35] offset:512
	global_load_dwordx4 v[212:215], v155, s[34:35] offset:528
	v_pk_fma_f32 v[92:93], v[92:93], v[196:197], v[216:217]
	v_pk_fma_f32 v[94:95], v[94:95], v[198:199], v[218:219]
	v_pk_fma_f32 v[88:89], v[88:89], v[200:201], v[220:221]
	v_pk_fma_f32 v[90:91], v[90:91], v[202:203], v[222:223]
	v_cvt_pk_bf16_f32 v91, v90, v91
	v_cvt_pk_bf16_f32 v90, v88, v89
	v_cvt_pk_bf16_f32 v89, v94, v95
	v_cvt_pk_bf16_f32 v88, v92, v93
	v_add_u32_e32 v156, 0x20000, v152
	global_store_dwordx4 v156, v[88:91], s[74:75]
	v_pk_fma_f32 v[84:85], v[84:85], v[204:205], v[224:225]
	v_pk_fma_f32 v[86:87], v[86:87], v[206:207], v[226:227]
	v_pk_fma_f32 v[80:81], v[80:81], v[208:209], v[228:229]
	v_pk_fma_f32 v[82:83], v[82:83], v[210:211], v[230:231]
	v_cvt_pk_bf16_f32 v83, v82, v83
	v_cvt_pk_bf16_f32 v82, v80, v81
	v_cvt_pk_bf16_f32 v81, v86, v87
	v_cvt_pk_bf16_f32 v80, v84, v85
	v_add_u32_e32 v156, 0x20000, v152
	global_store_dwordx4 v156, v[80:83], s[74:75] offset:256
	v_pk_fma_f32 v[76:77], v[76:77], v[196:197], v[236:237]
	v_pk_fma_f32 v[78:79], v[78:79], v[198:199], v[238:239]
	v_pk_fma_f32 v[72:73], v[72:73], v[200:201], v[240:241]
	v_pk_fma_f32 v[74:75], v[74:75], v[202:203], v[242:243]
	v_cvt_pk_bf16_f32 v75, v74, v75
	v_cvt_pk_bf16_f32 v74, v72, v73
	v_cvt_pk_bf16_f32 v73, v78, v79
	v_cvt_pk_bf16_f32 v72, v76, v77
	v_add_u32_e32 v156, 0x30000, v152
	global_store_dwordx4 v156, v[72:75], s[74:75]
	v_pk_fma_f32 v[68:69], v[68:69], v[204:205], v[244:245]
	v_pk_fma_f32 v[70:71], v[70:71], v[206:207], v[246:247]
	v_pk_fma_f32 v[64:65], v[64:65], v[208:209], v[248:249]
	v_pk_fma_f32 v[66:67], v[66:67], v[210:211], v[250:251]
	v_cvt_pk_bf16_f32 v67, v66, v67
	v_cvt_pk_bf16_f32 v66, v64, v65
	v_cvt_pk_bf16_f32 v65, v70, v71
	v_cvt_pk_bf16_f32 v64, v68, v69
	v_add_u32_e32 v156, 0x30000, v152
	global_store_dwordx4 v156, v[64:67], s[74:75] offset:256
	v_add_u32_e32 v155, 0x140000, v151
	global_load_dwordx4 v[216:219], v155, s[34:35]
	global_load_dwordx4 v[220:223], v155, s[34:35] offset:16
	global_load_dwordx4 v[224:227], v155, s[34:35] offset:512
	global_load_dwordx4 v[228:231], v155, s[34:35] offset:528
	v_add_u32_e32 v155, 0x160000, v151
	global_load_dwordx4 v[236:239], v155, s[34:35]
	global_load_dwordx4 v[240:243], v155, s[34:35] offset:16
	global_load_dwordx4 v[244:247], v155, s[34:35] offset:512
	global_load_dwordx4 v[248:251], v155, s[34:35] offset:528
	s_waitcnt vmcnt(0)
	v_pk_fma_f32 v[60:61], v[60:61], v[196:197], v[164:165]
	v_pk_fma_f32 v[62:63], v[62:63], v[198:199], v[166:167]
	v_pk_fma_f32 v[56:57], v[56:57], v[200:201], v[168:169]
	v_pk_fma_f32 v[58:59], v[58:59], v[202:203], v[170:171]
	v_cvt_pk_bf16_f32 v59, v58, v59
	v_cvt_pk_bf16_f32 v58, v56, v57
	v_cvt_pk_bf16_f32 v57, v62, v63
	v_cvt_pk_bf16_f32 v56, v60, v61
	v_add_u32_e32 v156, 0x80000, v152
	global_store_dwordx4 v156, v[56:59], s[74:75]
	v_pk_fma_f32 v[52:53], v[52:53], v[204:205], v[172:173]
	v_pk_fma_f32 v[54:55], v[54:55], v[206:207], v[174:175]
	v_pk_fma_f32 v[48:49], v[48:49], v[208:209], v[176:177]
	v_pk_fma_f32 v[50:51], v[50:51], v[210:211], v[178:179]
	v_cvt_pk_bf16_f32 v51, v50, v51
	v_cvt_pk_bf16_f32 v50, v48, v49
	v_cvt_pk_bf16_f32 v49, v54, v55
	v_cvt_pk_bf16_f32 v48, v52, v53
	v_add_u32_e32 v156, 0x80000, v152
	global_store_dwordx4 v156, v[48:51], s[74:75] offset:256
	v_pk_fma_f32 v[44:45], v[44:45], v[196:197], v[180:181]
	v_pk_fma_f32 v[46:47], v[46:47], v[198:199], v[182:183]
	v_pk_fma_f32 v[40:41], v[40:41], v[200:201], v[184:185]
	v_pk_fma_f32 v[42:43], v[42:43], v[202:203], v[186:187]
	v_cvt_pk_bf16_f32 v43, v42, v43
	v_cvt_pk_bf16_f32 v42, v40, v41
	v_cvt_pk_bf16_f32 v41, v46, v47
	v_cvt_pk_bf16_f32 v40, v44, v45
	v_add_u32_e32 v156, 0x90000, v152
	global_store_dwordx4 v156, v[40:43], s[74:75]
	v_pk_fma_f32 v[36:37], v[36:37], v[204:205], v[188:189]
	v_pk_fma_f32 v[38:39], v[38:39], v[206:207], v[190:191]
	v_pk_fma_f32 v[32:33], v[32:33], v[208:209], v[212:213]
	v_pk_fma_f32 v[34:35], v[34:35], v[210:211], v[214:215]
	v_cvt_pk_bf16_f32 v35, v34, v35
	v_cvt_pk_bf16_f32 v34, v32, v33
	v_cvt_pk_bf16_f32 v33, v38, v39
	v_cvt_pk_bf16_f32 v32, v36, v37
	v_add_u32_e32 v156, 0x90000, v152
	global_store_dwordx4 v156, v[32:35], s[74:75] offset:256
	v_pk_fma_f32 v[28:29], v[28:29], v[196:197], v[216:217]
	v_pk_fma_f32 v[30:31], v[30:31], v[198:199], v[218:219]
	v_pk_fma_f32 v[24:25], v[24:25], v[200:201], v[220:221]
	v_pk_fma_f32 v[26:27], v[26:27], v[202:203], v[222:223]
	v_cvt_pk_bf16_f32 v27, v26, v27
	v_cvt_pk_bf16_f32 v26, v24, v25
	v_cvt_pk_bf16_f32 v25, v30, v31
	v_cvt_pk_bf16_f32 v24, v28, v29
	v_add_u32_e32 v156, 0xa0000, v152
	global_store_dwordx4 v156, v[24:27], s[74:75]
	v_pk_fma_f32 v[20:21], v[20:21], v[204:205], v[224:225]
	v_pk_fma_f32 v[22:23], v[22:23], v[206:207], v[226:227]
	v_pk_fma_f32 v[16:17], v[16:17], v[208:209], v[228:229]
	v_pk_fma_f32 v[18:19], v[18:19], v[210:211], v[230:231]
	v_cvt_pk_bf16_f32 v19, v18, v19
	v_cvt_pk_bf16_f32 v18, v16, v17
	v_cvt_pk_bf16_f32 v17, v22, v23
	v_cvt_pk_bf16_f32 v16, v20, v21
	v_add_u32_e32 v156, 0xa0000, v152
	global_store_dwordx4 v156, v[16:19], s[74:75] offset:256
	v_pk_fma_f32 v[12:13], v[12:13], v[196:197], v[236:237]
	v_pk_fma_f32 v[14:15], v[14:15], v[198:199], v[238:239]
	v_pk_fma_f32 v[8:9], v[8:9], v[200:201], v[240:241]
	v_pk_fma_f32 v[10:11], v[10:11], v[202:203], v[242:243]
	v_cvt_pk_bf16_f32 v11, v10, v11
	v_cvt_pk_bf16_f32 v10, v8, v9
	v_cvt_pk_bf16_f32 v9, v14, v15
	v_cvt_pk_bf16_f32 v8, v12, v13
	v_add_u32_e32 v156, 0xb0000, v152
	global_store_dwordx4 v156, v[8:11], s[74:75]
	v_pk_fma_f32 v[4:5], v[4:5], v[204:205], v[244:245]
	v_pk_fma_f32 v[6:7], v[6:7], v[206:207], v[246:247]
	v_pk_fma_f32 v[0:1], v[0:1], v[208:209], v[248:249]
	v_pk_fma_f32 v[2:3], v[2:3], v[210:211], v[250:251]
	v_cvt_pk_bf16_f32 v3, v2, v3
	v_cvt_pk_bf16_f32 v2, v0, v1
	v_cvt_pk_bf16_f32 v1, v6, v7
	v_cvt_pk_bf16_f32 v0, v4, v5
	v_add_u32_e32 v156, 0xb0000, v152
	global_store_dwordx4 v156, v[0:3], s[74:75] offset:256

.LBB0_999:
	ds_read_b128 v[156:159], v152
	ds_read_b128 v[160:163], v152 offset:1024
	ds_read_b128 v[164:167], v152 offset:2048
	ds_read_b128 v[168:171], v152 offset:3072
	s_add_u32 s20, s46, 0xfff80080
	s_addc_u32 s21, s47, -1
	s_cmp_eq_u32 s58, 28
	s_cselect_b32 s21, s15, s21
	s_cselect_b32 s20, s54, s20
	s_cselect_b32 s49, s11, s57
	s_cselect_b32 s48, s55, s56
	v_lshl_add_u64 v[148:149], s[46:47], 0, v[136:137]
	s_add_i32 m0, s35, 0xc000
	ds_read_b128 v[172:175], v153
	ds_read_b128 v[176:179], v153 offset:1024
	ds_read_b128 v[180:183], v153 offset:2048
	ds_read_b128 v[184:187], v153 offset:3072
	ds_read_b128 v[188:191], v153 offset:4096
	ds_read_b128 v[196:199], v153 offset:5120
	ds_read_b128 v[200:203], v153 offset:6144
	ds_read_b128 v[204:207], v153 offset:7168
	global_load_lds_dwordx4 v[148:149], off
	s_add_i32 m0, s35, 0xe000
	v_lshl_add_u64 v[148:149], s[46:47], 0, v[138:139]
	global_load_lds_dwordx4 v[148:149], off
	s_waitcnt lgkmcnt(8)
	s_barrier
	s_waitcnt lgkmcnt(0)
	s_setprio 1
	v_mfma_f32_16x16x32_bf16 v[124:127], v[156:159], v[172:175], v[124:127]
	v_mfma_f32_16x16x32_bf16 v[120:123], v[164:167], v[172:175], v[120:123]
	v_mfma_f32_16x16x32_bf16 v[108:111], v[156:159], v[180:183], v[108:111]
	v_mfma_f32_16x16x32_bf16 v[104:107], v[164:167], v[180:183], v[104:107]
	v_mfma_f32_16x16x32_bf16 v[92:95], v[156:159], v[188:191], v[92:95]
	v_mfma_f32_16x16x32_bf16 v[88:91], v[164:167], v[188:191], v[88:91]
	v_mfma_f32_16x16x32_bf16 v[76:79], v[156:159], v[200:203], v[76:79]
	v_mfma_f32_16x16x32_bf16 v[72:75], v[164:167], v[200:203], v[72:75]
	v_mfma_f32_16x16x32_bf16 v[124:127], v[160:163], v[176:179], v[124:127]
	v_mfma_f32_16x16x32_bf16 v[120:123], v[168:171], v[176:179], v[120:123]
	v_mfma_f32_16x16x32_bf16 v[108:111], v[160:163], v[184:187], v[108:111]
	v_mfma_f32_16x16x32_bf16 v[104:107], v[168:171], v[184:187], v[104:107]
	v_mfma_f32_16x16x32_bf16 v[92:95], v[160:163], v[196:199], v[92:95]
	v_mfma_f32_16x16x32_bf16 v[88:91], v[168:171], v[196:199], v[88:91]
	v_mfma_f32_16x16x32_bf16 v[76:79], v[160:163], v[204:207], v[76:79]
	v_mfma_f32_16x16x32_bf16 v[72:75], v[168:171], v[204:207], v[72:75]
	s_setprio 0
	s_barrier
	s_add_i32 s59, s52, s23
	v_lshl_add_u64 v[148:149], s[48:49], 0, v[132:133]
	s_mov_b32 m0, s59
	ds_read_b128 v[208:211], v154
	ds_read_b128 v[212:215], v154 offset:1024
	ds_read_b128 v[216:219], v154 offset:2048
	ds_read_b128 v[220:223], v154 offset:3072
	global_load_lds_dwordx4 v[148:149], off
	s_add_i32 m0, s59, 0x2000
	v_lshl_add_u64 v[224:225], s[48:49], 0, v[128:129]
	global_load_lds_dwordx4 v[224:225], off
	s_barrier
	s_waitcnt lgkmcnt(0)
	s_setprio 1
	v_mfma_f32_16x16x32_bf16 v[116:119], v[208:211], v[172:175], v[116:119]
	v_mfma_f32_16x16x32_bf16 v[112:115], v[216:219], v[172:175], v[112:115]
	v_mfma_f32_16x16x32_bf16 v[100:103], v[208:211], v[180:183], v[100:103]
	v_mfma_f32_16x16x32_bf16 v[96:99], v[216:219], v[180:183], v[96:99]
	v_mfma_f32_16x16x32_bf16 v[84:87], v[208:211], v[188:191], v[84:87]
	v_mfma_f32_16x16x32_bf16 v[80:83], v[216:219], v[188:191], v[80:83]
	v_mfma_f32_16x16x32_bf16 v[68:71], v[208:211], v[200:203], v[68:71]
	v_mfma_f32_16x16x32_bf16 v[64:67], v[216:219], v[200:203], v[64:67]
	v_mfma_f32_16x16x32_bf16 v[116:119], v[212:215], v[176:179], v[116:119]
	v_mfma_f32_16x16x32_bf16 v[112:115], v[220:223], v[176:179], v[112:115]
	v_mfma_f32_16x16x32_bf16 v[100:103], v[212:215], v[184:187], v[100:103]
	v_mfma_f32_16x16x32_bf16 v[96:99], v[220:223], v[184:187], v[96:99]
	v_mfma_f32_16x16x32_bf16 v[84:87], v[212:215], v[196:199], v[84:87]
	v_mfma_f32_16x16x32_bf16 v[80:83], v[220:223], v[196:199], v[80:83]
	v_mfma_f32_16x16x32_bf16 v[68:71], v[212:215], v[204:207], v[68:71]
	v_mfma_f32_16x16x32_bf16 v[64:67], v[220:223], v[204:207], v[64:67]
	s_setprio 0
	s_mov_b32 m0, s35
	v_lshl_add_u64 v[226:227], s[20:21], 0, v[134:135]
	s_barrier
	ds_read_b128 v[172:175], v153 offset:16384
	ds_read_b128 v[176:179], v153 offset:17408
	ds_read_b128 v[180:183], v153 offset:18432
	ds_read_b128 v[184:187], v153 offset:19456
	ds_read_b128 v[188:191], v153 offset:20480
	ds_read_b128 v[196:199], v153 offset:21504
	ds_read_b128 v[200:203], v153 offset:22528
	ds_read_b128 v[204:207], v153 offset:23552
	global_load_lds_dwordx4 v[226:227], off
	s_mov_b32 m0, s36
	v_lshl_add_u64 v[228:229], s[20:21], 0, v[130:131]
	global_load_lds_dwordx4 v[228:229], off
	s_barrier
	s_waitcnt lgkmcnt(0)
	s_setprio 1
	v_mfma_f32_16x16x32_bf16 v[60:63], v[156:159], v[172:175], v[60:63]
	v_mfma_f32_16x16x32_bf16 v[56:59], v[164:167], v[172:175], v[56:59]
	v_mfma_f32_16x16x32_bf16 v[44:47], v[156:159], v[180:183], v[44:47]
	v_mfma_f32_16x16x32_bf16 v[40:43], v[164:167], v[180:183], v[40:43]
	v_mfma_f32_16x16x32_bf16 v[28:31], v[156:159], v[188:191], v[28:31]
	v_mfma_f32_16x16x32_bf16 v[24:27], v[164:167], v[188:191], v[24:27]
	v_mfma_f32_16x16x32_bf16 v[12:15], v[156:159], v[200:203], v[12:15]
	v_mfma_f32_16x16x32_bf16 v[8:11], v[164:167], v[200:203], v[8:11]
	v_mfma_f32_16x16x32_bf16 v[60:63], v[160:163], v[176:179], v[60:63]
	v_mfma_f32_16x16x32_bf16 v[56:59], v[168:171], v[176:179], v[56:59]
	v_mfma_f32_16x16x32_bf16 v[44:47], v[160:163], v[184:187], v[44:47]
	v_mfma_f32_16x16x32_bf16 v[40:43], v[168:171], v[184:187], v[40:43]
	v_mfma_f32_16x16x32_bf16 v[28:31], v[160:163], v[196:199], v[28:31]
	v_mfma_f32_16x16x32_bf16 v[24:27], v[168:171], v[196:199], v[24:27]
	v_mfma_f32_16x16x32_bf16 v[12:15], v[160:163], v[204:207], v[12:15]
	v_mfma_f32_16x16x32_bf16 v[8:11], v[168:171], v[204:207], v[8:11]
	s_setprio 0
	s_barrier
	s_add_u32 s60, s48, 0x80000
	s_addc_u32 s61, s49, 0
	s_add_i32 s59, s53, s23
	s_mov_b32 m0, s59
	v_lshl_add_u64 v[156:157], s[60:61], 0, v[132:133]
	global_load_lds_dwordx4 v[156:157], off
	s_add_i32 m0, s59, 0x2000
	v_lshl_add_u64 v[156:157], s[60:61], 0, v[128:129]
	global_load_lds_dwordx4 v[156:157], off
	s_waitcnt vmcnt(6)
	s_barrier
	s_setprio 1
	v_mfma_f32_16x16x32_bf16 v[52:55], v[208:211], v[172:175], v[52:55]
	v_mfma_f32_16x16x32_bf16 v[48:51], v[216:219], v[172:175], v[48:51]
	v_mfma_f32_16x16x32_bf16 v[36:39], v[208:211], v[180:183], v[36:39]
	v_mfma_f32_16x16x32_bf16 v[32:35], v[216:219], v[180:183], v[32:35]
	v_mfma_f32_16x16x32_bf16 v[20:23], v[208:211], v[188:191], v[20:23]
	v_mfma_f32_16x16x32_bf16 v[16:19], v[216:219], v[188:191], v[16:19]
	v_mfma_f32_16x16x32_bf16 v[4:7], v[208:211], v[200:203], v[4:7]
	v_mfma_f32_16x16x32_bf16 v[0:3], v[216:219], v[200:203], v[0:3]
	v_mfma_f32_16x16x32_bf16 v[52:55], v[212:215], v[176:179], v[52:55]
	v_mfma_f32_16x16x32_bf16 v[48:51], v[220:223], v[176:179], v[48:51]
	v_mfma_f32_16x16x32_bf16 v[36:39], v[212:215], v[184:187], v[36:39]
	v_mfma_f32_16x16x32_bf16 v[32:35], v[220:223], v[184:187], v[32:35]
	v_mfma_f32_16x16x32_bf16 v[20:23], v[212:215], v[196:199], v[20:23]
	v_mfma_f32_16x16x32_bf16 v[16:19], v[220:223], v[196:199], v[16:19]
	v_mfma_f32_16x16x32_bf16 v[4:7], v[212:215], v[204:207], v[4:7]
	v_mfma_f32_16x16x32_bf16 v[0:3], v[220:223], v[204:207], v[0:3]
	s_setprio 0
	s_add_i32 s59, 0, 0x18000
	v_add_u32_e32 v155, s59, v150
	s_barrier
	ds_read_b128 v[156:159], v155
	ds_read_b128 v[160:163], v155 offset:1024
	ds_read_b128 v[164:167], v155 offset:2048
	ds_read_b128 v[168:171], v155 offset:3072
	s_add_u32 s20, s20, 0x80000
	s_addc_u32 s21, s21, 0
	s_mov_b32 m0, s37
	v_lshl_add_u64 v[208:209], s[20:21], 0, v[134:135]
	ds_read_b128 v[172:175], v153 offset:32768
	ds_read_b128 v[176:179], v153 offset:33792
	ds_read_b128 v[180:183], v153 offset:34816
	ds_read_b128 v[184:187], v153 offset:35840
	ds_read_b128 v[188:191], v153 offset:36864
	ds_read_b128 v[196:199], v153 offset:37888
	ds_read_b128 v[200:203], v153 offset:38912
	ds_read_b128 v[204:207], v153 offset:39936
	global_load_lds_dwordx4 v[208:209], off
	s_mov_b32 m0, s38
	v_lshl_add_u64 v[208:209], s[20:21], 0, v[130:131]
	global_load_lds_dwordx4 v[208:209], off
	s_waitcnt lgkmcnt(8)
	s_barrier
	s_waitcnt lgkmcnt(0)
	s_setprio 1
	v_mfma_f32_16x16x32_bf16 v[124:127], v[156:159], v[172:175], v[124:127]
	v_mfma_f32_16x16x32_bf16 v[120:123], v[164:167], v[172:175], v[120:123]
	v_mfma_f32_16x16x32_bf16 v[108:111], v[156:159], v[180:183], v[108:111]
	v_mfma_f32_16x16x32_bf16 v[104:107], v[164:167], v[180:183], v[104:107]
	v_mfma_f32_16x16x32_bf16 v[92:95], v[156:159], v[188:191], v[92:95]
	v_mfma_f32_16x16x32_bf16 v[88:91], v[164:167], v[188:191], v[88:91]
	v_mfma_f32_16x16x32_bf16 v[76:79], v[156:159], v[200:203], v[76:79]
	v_mfma_f32_16x16x32_bf16 v[72:75], v[164:167], v[200:203], v[72:75]
	v_mfma_f32_16x16x32_bf16 v[124:127], v[160:163], v[176:179], v[124:127]
	v_mfma_f32_16x16x32_bf16 v[120:123], v[168:171], v[176:179], v[120:123]
	v_mfma_f32_16x16x32_bf16 v[108:111], v[160:163], v[184:187], v[108:111]
	v_mfma_f32_16x16x32_bf16 v[104:107], v[168:171], v[184:187], v[104:107]
	v_mfma_f32_16x16x32_bf16 v[92:95], v[160:163], v[196:199], v[92:95]
	v_mfma_f32_16x16x32_bf16 v[88:91], v[168:171], v[196:199], v[88:91]
	v_mfma_f32_16x16x32_bf16 v[76:79], v[160:163], v[204:207], v[76:79]
	v_mfma_f32_16x16x32_bf16 v[72:75], v[168:171], v[204:207], v[72:75]
	s_setprio 0
	s_barrier
	s_add_i32 s60, 0, 0x1c000
	s_add_i32 s20, s59, s23
	v_add_u32_e32 v155, s60, v150
	v_lshl_add_u64 v[148:149], v[148:149], 0, s[8:9]
	s_mov_b32 m0, s20
	ds_read_b128 v[208:211], v155
	ds_read_b128 v[212:215], v155 offset:1024
	ds_read_b128 v[216:219], v155 offset:2048
	ds_read_b128 v[220:223], v155 offset:3072
	global_load_lds_dwordx4 v[148:149], off
	s_add_i32 m0, s20, 0x2000
	v_lshl_add_u64 v[148:149], v[224:225], 0, s[8:9]
	global_load_lds_dwordx4 v[148:149], off
	s_barrier
	s_waitcnt lgkmcnt(0)
	s_setprio 1
	v_mfma_f32_16x16x32_bf16 v[116:119], v[208:211], v[172:175], v[116:119]
	v_mfma_f32_16x16x32_bf16 v[112:115], v[216:219], v[172:175], v[112:115]
	v_mfma_f32_16x16x32_bf16 v[100:103], v[208:211], v[180:183], v[100:103]
	v_mfma_f32_16x16x32_bf16 v[96:99], v[216:219], v[180:183], v[96:99]
	v_mfma_f32_16x16x32_bf16 v[84:87], v[208:211], v[188:191], v[84:87]
	v_mfma_f32_16x16x32_bf16 v[80:83], v[216:219], v[188:191], v[80:83]
	v_mfma_f32_16x16x32_bf16 v[68:71], v[208:211], v[200:203], v[68:71]
	v_mfma_f32_16x16x32_bf16 v[64:67], v[216:219], v[200:203], v[64:67]
	v_mfma_f32_16x16x32_bf16 v[116:119], v[212:215], v[176:179], v[116:119]
	v_mfma_f32_16x16x32_bf16 v[112:115], v[220:223], v[176:179], v[112:115]
	v_mfma_f32_16x16x32_bf16 v[100:103], v[212:215], v[184:187], v[100:103]
	v_mfma_f32_16x16x32_bf16 v[96:99], v[220:223], v[184:187], v[96:99]
	v_mfma_f32_16x16x32_bf16 v[84:87], v[212:215], v[196:199], v[84:87]
	v_mfma_f32_16x16x32_bf16 v[80:83], v[220:223], v[196:199], v[80:83]
	v_mfma_f32_16x16x32_bf16 v[68:71], v[212:215], v[204:207], v[68:71]
	v_mfma_f32_16x16x32_bf16 v[64:67], v[220:223], v[204:207], v[64:67]
	s_setprio 0
	s_mov_b32 m0, s45
	v_lshl_add_u64 v[148:149], v[226:227], 0, s[8:9]
	s_barrier
	ds_read_b128 v[172:175], v153 offset:49152
	ds_read_b128 v[176:179], v153 offset:50176
	ds_read_b128 v[180:183], v153 offset:51200
	ds_read_b128 v[184:187], v153 offset:52224
	ds_read_b128 v[188:191], v153 offset:53248
	ds_read_b128 v[196:199], v153 offset:54272
	ds_read_b128 v[200:203], v153 offset:55296
	ds_read_b128 v[204:207], v153 offset:56320
	global_load_lds_dwordx4 v[148:149], off
	s_mov_b32 m0, s50
	v_lshl_add_u64 v[148:149], v[228:229], 0, s[8:9]
	global_load_lds_dwordx4 v[148:149], off
	s_barrier
	s_waitcnt lgkmcnt(0)
	s_setprio 1
	v_mfma_f32_16x16x32_bf16 v[60:63], v[156:159], v[172:175], v[60:63]
	v_mfma_f32_16x16x32_bf16 v[56:59], v[164:167], v[172:175], v[56:59]
	v_mfma_f32_16x16x32_bf16 v[44:47], v[156:159], v[180:183], v[44:47]
	v_mfma_f32_16x16x32_bf16 v[40:43], v[164:167], v[180:183], v[40:43]
	v_mfma_f32_16x16x32_bf16 v[28:31], v[156:159], v[188:191], v[28:31]
	v_mfma_f32_16x16x32_bf16 v[24:27], v[164:167], v[188:191], v[24:27]
	v_mfma_f32_16x16x32_bf16 v[12:15], v[156:159], v[200:203], v[12:15]
	v_mfma_f32_16x16x32_bf16 v[8:11], v[164:167], v[200:203], v[8:11]
	v_mfma_f32_16x16x32_bf16 v[60:63], v[160:163], v[176:179], v[60:63]
	v_mfma_f32_16x16x32_bf16 v[56:59], v[168:171], v[176:179], v[56:59]
	v_mfma_f32_16x16x32_bf16 v[44:47], v[160:163], v[184:187], v[44:47]
	v_mfma_f32_16x16x32_bf16 v[40:43], v[168:171], v[184:187], v[40:43]
	v_mfma_f32_16x16x32_bf16 v[28:31], v[160:163], v[196:199], v[28:31]
	v_mfma_f32_16x16x32_bf16 v[24:27], v[168:171], v[196:199], v[24:27]
	v_mfma_f32_16x16x32_bf16 v[12:15], v[160:163], v[204:207], v[12:15]
	v_mfma_f32_16x16x32_bf16 v[8:11], v[168:171], v[204:207], v[8:11]
	s_setprio 0
	s_barrier
	s_add_u32 s20, s48, 0x80080
	s_addc_u32 s21, s49, 0
	s_add_i32 s48, s60, s23
	s_mov_b32 m0, s48
	v_lshl_add_u64 v[148:149], s[20:21], 0, v[132:133]
	global_load_lds_dwordx4 v[148:149], off
	s_add_i32 m0, s48, 0x2000
	v_lshl_add_u64 v[148:149], s[20:21], 0, v[128:129]
	global_load_lds_dwordx4 v[148:149], off
	s_waitcnt vmcnt(6)
	s_barrier
	s_setprio 1
	v_mfma_f32_16x16x32_bf16 v[52:55], v[208:211], v[172:175], v[52:55]
	v_mfma_f32_16x16x32_bf16 v[48:51], v[216:219], v[172:175], v[48:51]
	v_mfma_f32_16x16x32_bf16 v[36:39], v[208:211], v[180:183], v[36:39]
	v_mfma_f32_16x16x32_bf16 v[32:35], v[216:219], v[180:183], v[32:35]
	v_mfma_f32_16x16x32_bf16 v[20:23], v[208:211], v[188:191], v[20:23]
	v_mfma_f32_16x16x32_bf16 v[16:19], v[216:219], v[188:191], v[16:19]
	v_mfma_f32_16x16x32_bf16 v[4:7], v[208:211], v[200:203], v[4:7]
	v_mfma_f32_16x16x32_bf16 v[0:3], v[216:219], v[200:203], v[0:3]
	v_mfma_f32_16x16x32_bf16 v[52:55], v[212:215], v[176:179], v[52:55]
	v_mfma_f32_16x16x32_bf16 v[48:51], v[220:223], v[176:179], v[48:51]
	v_mfma_f32_16x16x32_bf16 v[36:39], v[212:215], v[184:187], v[36:39]
	v_mfma_f32_16x16x32_bf16 v[32:35], v[220:223], v[184:187], v[32:35]
	v_mfma_f32_16x16x32_bf16 v[20:23], v[212:215], v[196:199], v[20:23]
	v_mfma_f32_16x16x32_bf16 v[16:19], v[220:223], v[196:199], v[16:19]
	v_mfma_f32_16x16x32_bf16 v[4:7], v[212:215], v[204:207], v[4:7]
	v_mfma_f32_16x16x32_bf16 v[0:3], v[220:223], v[204:207], v[0:3]
	s_setprio 0
	s_add_i32 s58, s58, 2
	s_add_u32 s46, s46, 0x100
	s_addc_u32 s47, s47, 0
	s_add_u32 s56, s56, 0x100
	s_addc_u32 s57, s57, 0
	s_cmp_gt_u32 s58, 29
	s_cbranch_scc1 .Ldup_last_mlpin0
	s_barrier
	s_branch .LBB0_999
.Ldup_last_mlpin0:
	s_cmpk_gt_u32 s12, 0xff
	s_cbranch_scc0 .Ldup_bar_mlpin0
	v_lshl_add_u32 v148, s44, 8, v147
	v_max_f32_e32 v124, v124, v124
	v_max_f32_e32 v120, v120, v120
	v_ashrrev_i32_e32 v149, 31, v148
	v_max_f32_e32 v124, 0, v124
	v_max_f32_e32 v120, 0, v120
	v_lshlrev_b64 v[158:159], 14, v[148:149]
	v_mul_f32_e32 v149, v124, v124
	v_mul_f32_e32 v124, v120, v120
	v_max_f32_e32 v120, v125, v125
	v_max_f32_e32 v121, v121, v121
	v_max_f32_e32 v120, 0, v120
	v_max_f32_e32 v121, 0, v121
	v_mul_f32_e32 v155, v120, v120
	v_mul_f32_e32 v160, v121, v121
	v_max_f32_e32 v120, v126, v126
	v_max_f32_e32 v121, v122, v122
	v_max_f32_e32 v120, 0, v120
	v_max_f32_e32 v121, 0, v121
	v_lshl_or_b32 v156, s33, 8, v151
	v_mul_f32_e32 v161, v120, v120
	v_mul_f32_e32 v125, v121, v121
	v_max_f32_e32 v120, v127, v127
	v_max_f32_e32 v121, v123, v123
	v_max_f32_e32 v116, v116, v116
	v_max_f32_e32 v112, v112, v112
	v_max_f32_e32 v117, v117, v117
	v_max_f32_e32 v113, v113, v113
	v_max_f32_e32 v118, v118, v118
	v_max_f32_e32 v114, v114, v114
	v_max_f32_e32 v119, v119, v119
	v_max_f32_e32 v115, v115, v115
	v_ashrrev_i32_e32 v157, 31, v156
	v_max_f32_e32 v120, 0, v120
	v_max_f32_e32 v121, 0, v121
	v_max_f32_e32 v116, 0, v116
	v_max_f32_e32 v112, 0, v112
	v_max_f32_e32 v117, 0, v117
	v_max_f32_e32 v113, 0, v113
	v_max_f32_e32 v118, 0, v118
	v_max_f32_e32 v114, 0, v114
	v_max_f32_e32 v119, 0, v119
	v_max_f32_e32 v115, 0, v115
	v_mul_f32_e32 v162, v120, v120
	v_mul_f32_e32 v163, v121, v121
	v_lshl_add_u64 v[122:123], s[28:29], 0, v[158:159]
	v_lshlrev_b64 v[120:121], 1, v[156:157]
	v_mul_f32_e32 v116, v116, v116
	v_mul_f32_e32 v112, v112, v112
	v_mul_f32_e32 v117, v117, v117
	v_mul_f32_e32 v113, v113, v113
	v_mul_f32_e32 v118, v118, v118
	v_mul_f32_e32 v114, v114, v114
	v_mul_f32_e32 v119, v119, v119
	v_mul_f32_e32 v115, v115, v115
	v_max_f32_e32 v104, v104, v104
	v_lshl_add_u64 v[126:127], v[122:123], 0, v[120:121]
	v_cvt_pk_bf16_f32 v115, v114, v115
	v_cvt_pk_bf16_f32 v114, v112, v113
	v_cvt_pk_bf16_f32 v113, v118, v119
	v_cvt_pk_bf16_f32 v112, v116, v117
	v_max_f32_e32 v104, 0, v104
	global_store_dwordx4 v[126:127], v[112:115], off offset:256
	v_max_f32_e32 v105, v105, v105
	v_max_f32_e32 v105, 0, v105
	v_mul_f32_e32 v115, v104, v104
	v_max_f32_e32 v104, v109, v109
	v_max_f32_e32 v104, 0, v104
	v_mul_f32_e32 v116, v104, v104
	v_mul_f32_e32 v117, v105, v105
	v_max_f32_e32 v104, v110, v110
	v_max_f32_e32 v105, v106, v106
	v_or_b32_e32 v112, 16, v148
	v_max_f32_e32 v104, 0, v104
	v_max_f32_e32 v105, 0, v105
	v_ashrrev_i32_e32 v113, 31, v112
	v_mul_f32_e32 v110, v104, v104
	v_mul_f32_e32 v106, v105, v105
	v_max_f32_e32 v104, v111, v111
	v_max_f32_e32 v105, v107, v107
	v_max_f32_e32 v100, v100, v100
	v_max_f32_e32 v96, v96, v96
	v_max_f32_e32 v101, v101, v101
	v_max_f32_e32 v97, v97, v97
	v_max_f32_e32 v102, v102, v102
	v_max_f32_e32 v98, v98, v98
	v_max_f32_e32 v103, v103, v103
	v_max_f32_e32 v99, v99, v99
	v_lshlrev_b64 v[112:113], 14, v[112:113]
	v_max_f32_e32 v108, v108, v108
	v_max_f32_e32 v104, 0, v104
	v_max_f32_e32 v105, 0, v105
	v_max_f32_e32 v100, 0, v100
	v_max_f32_e32 v96, 0, v96
	v_max_f32_e32 v101, 0, v101
	v_max_f32_e32 v97, 0, v97
	v_max_f32_e32 v102, 0, v102
	v_max_f32_e32 v98, 0, v98
	v_max_f32_e32 v103, 0, v103
	v_max_f32_e32 v99, 0, v99
	v_max_f32_e32 v108, 0, v108
	v_mul_f32_e32 v111, v104, v104
	v_mul_f32_e32 v107, v105, v105
	v_lshl_add_u64 v[104:105], s[28:29], 0, v[112:113]
	v_mul_f32_e32 v100, v100, v100
	v_mul_f32_e32 v96, v96, v96
	v_mul_f32_e32 v101, v101, v101
	v_mul_f32_e32 v97, v97, v97
	v_mul_f32_e32 v102, v102, v102
	v_mul_f32_e32 v98, v98, v98
	v_mul_f32_e32 v103, v103, v103
	v_mul_f32_e32 v99, v99, v99
	v_max_f32_e32 v88, v88, v88
	v_mul_f32_e32 v114, v108, v108
	v_lshl_add_u64 v[108:109], v[104:105], 0, v[120:121]
	v_cvt_pk_bf16_f32 v99, v98, v99
	v_cvt_pk_bf16_f32 v98, v96, v97
	v_cvt_pk_bf16_f32 v97, v102, v103
	v_cvt_pk_bf16_f32 v96, v100, v101
	v_max_f32_e32 v88, 0, v88
	global_store_dwordx4 v[108:109], v[96:99], off offset:256
	v_max_f32_e32 v89, v89, v89
	v_max_f32_e32 v89, 0, v89
	v_mul_f32_e32 v99, v88, v88
	v_max_f32_e32 v88, v93, v93
	v_max_f32_e32 v88, 0, v88
	v_mul_f32_e32 v100, v88, v88
	v_mul_f32_e32 v101, v89, v89
	v_max_f32_e32 v88, v94, v94
	v_max_f32_e32 v89, v90, v90
	v_or_b32_e32 v96, 32, v148
	v_max_f32_e32 v88, 0, v88
	v_max_f32_e32 v89, 0, v89
	v_ashrrev_i32_e32 v97, 31, v96
	v_mul_f32_e32 v94, v88, v88
	v_mul_f32_e32 v90, v89, v89
	v_max_f32_e32 v88, v95, v95
	v_max_f32_e32 v89, v91, v91
	v_max_f32_e32 v84, v84, v84
	v_max_f32_e32 v80, v80, v80
	v_max_f32_e32 v85, v85, v85
	v_max_f32_e32 v81, v81, v81
	v_max_f32_e32 v86, v86, v86
	v_max_f32_e32 v82, v82, v82
	v_max_f32_e32 v87, v87, v87
	v_max_f32_e32 v83, v83, v83
	v_lshlrev_b64 v[96:97], 14, v[96:97]
	v_max_f32_e32 v92, v92, v92
	v_max_f32_e32 v88, 0, v88
	v_max_f32_e32 v89, 0, v89
	v_max_f32_e32 v84, 0, v84
	v_max_f32_e32 v80, 0, v80
	v_max_f32_e32 v85, 0, v85
	v_max_f32_e32 v81, 0, v81
	v_max_f32_e32 v86, 0, v86
	v_max_f32_e32 v82, 0, v82
	v_max_f32_e32 v87, 0, v87
	v_max_f32_e32 v83, 0, v83
	v_max_f32_e32 v92, 0, v92
	v_mul_f32_e32 v95, v88, v88
	v_mul_f32_e32 v91, v89, v89
	v_lshl_add_u64 v[88:89], s[28:29], 0, v[96:97]
	v_mul_f32_e32 v84, v84, v84
	v_mul_f32_e32 v80, v80, v80
	v_mul_f32_e32 v85, v85, v85
	v_mul_f32_e32 v81, v81, v81
	v_mul_f32_e32 v86, v86, v86
	v_mul_f32_e32 v82, v82, v82
	v_mul_f32_e32 v87, v87, v87
	v_mul_f32_e32 v83, v83, v83
	v_max_f32_e32 v72, v72, v72
	v_mul_f32_e32 v98, v92, v92
	v_lshl_add_u64 v[92:93], v[88:89], 0, v[120:121]
	v_cvt_pk_bf16_f32 v83, v82, v83
	v_cvt_pk_bf16_f32 v82, v80, v81
	v_cvt_pk_bf16_f32 v81, v86, v87
	v_cvt_pk_bf16_f32 v80, v84, v85
	v_max_f32_e32 v72, 0, v72
	global_store_dwordx4 v[92:93], v[80:83], off offset:256
	v_max_f32_e32 v73, v73, v73
	v_max_f32_e32 v73, 0, v73
	v_mul_f32_e32 v83, v72, v72
	v_max_f32_e32 v72, v77, v77
	v_max_f32_e32 v72, 0, v72
	v_mul_f32_e32 v84, v72, v72
	v_mul_f32_e32 v85, v73, v73
	v_max_f32_e32 v72, v78, v78
	v_max_f32_e32 v73, v74, v74
	v_or_b32_e32 v80, 48, v148
	v_max_f32_e32 v72, 0, v72
	v_max_f32_e32 v73, 0, v73
	v_ashrrev_i32_e32 v81, 31, v80
	v_mul_f32_e32 v78, v72, v72
	v_mul_f32_e32 v74, v73, v73
	v_max_f32_e32 v72, v79, v79
	v_max_f32_e32 v73, v75, v75
	v_max_f32_e32 v68, v68, v68
	v_max_f32_e32 v64, v64, v64
	v_max_f32_e32 v69, v69, v69
	v_max_f32_e32 v65, v65, v65
	v_max_f32_e32 v70, v70, v70
	v_max_f32_e32 v66, v66, v66
	v_max_f32_e32 v71, v71, v71
	v_max_f32_e32 v67, v67, v67
	v_lshlrev_b64 v[80:81], 14, v[80:81]
	v_max_f32_e32 v76, v76, v76
	v_max_f32_e32 v72, 0, v72
	v_max_f32_e32 v73, 0, v73
	v_max_f32_e32 v68, 0, v68
	v_max_f32_e32 v64, 0, v64
	v_max_f32_e32 v69, 0, v69
	v_max_f32_e32 v65, 0, v65
	v_max_f32_e32 v70, 0, v70
	v_max_f32_e32 v66, 0, v66
	v_max_f32_e32 v71, 0, v71
	v_max_f32_e32 v67, 0, v67
	v_max_f32_e32 v76, 0, v76
	v_mul_f32_e32 v79, v72, v72
	v_mul_f32_e32 v75, v73, v73
	v_lshl_add_u64 v[72:73], s[28:29], 0, v[80:81]
	v_mul_f32_e32 v68, v68, v68
	v_mul_f32_e32 v64, v64, v64
	v_mul_f32_e32 v69, v69, v69
	v_mul_f32_e32 v65, v65, v65
	v_mul_f32_e32 v70, v70, v70
	v_mul_f32_e32 v66, v66, v66
	v_mul_f32_e32 v71, v71, v71
	v_mul_f32_e32 v67, v67, v67
	v_max_f32_e32 v56, v56, v56
	v_mul_f32_e32 v82, v76, v76
	v_lshl_add_u64 v[76:77], v[72:73], 0, v[120:121]
	v_cvt_pk_bf16_f32 v67, v66, v67
	v_cvt_pk_bf16_f32 v66, v64, v65
	v_cvt_pk_bf16_f32 v65, v70, v71
	v_cvt_pk_bf16_f32 v64, v68, v69
	v_max_f32_e32 v56, 0, v56
	global_store_dwordx4 v[76:77], v[64:67], off offset:256
	v_max_f32_e32 v57, v57, v57
	v_max_f32_e32 v57, 0, v57
	v_mul_f32_e32 v67, v56, v56
	v_max_f32_e32 v56, v61, v61
	v_max_f32_e32 v56, 0, v56
	v_mul_f32_e32 v68, v56, v56
	v_mul_f32_e32 v69, v57, v57
	v_max_f32_e32 v56, v62, v62
	v_max_f32_e32 v57, v58, v58
	v_add_u32_e32 v64, 0x80, v148
	v_max_f32_e32 v56, 0, v56
	v_max_f32_e32 v57, 0, v57
	v_ashrrev_i32_e32 v65, 31, v64
	v_mul_f32_e32 v62, v56, v56
	v_mul_f32_e32 v58, v57, v57
	v_max_f32_e32 v56, v63, v63
	v_max_f32_e32 v57, v59, v59
	v_max_f32_e32 v52, v52, v52
	v_max_f32_e32 v48, v48, v48
	v_max_f32_e32 v53, v53, v53
	v_max_f32_e32 v49, v49, v49
	v_max_f32_e32 v54, v54, v54
	v_max_f32_e32 v50, v50, v50
	v_max_f32_e32 v55, v55, v55
	v_max_f32_e32 v51, v51, v51
	v_lshlrev_b64 v[64:65], 14, v[64:65]
	v_max_f32_e32 v60, v60, v60
	v_max_f32_e32 v56, 0, v56
	v_max_f32_e32 v57, 0, v57
	v_max_f32_e32 v52, 0, v52
	v_max_f32_e32 v48, 0, v48
	v_max_f32_e32 v53, 0, v53
	v_max_f32_e32 v49, 0, v49
	v_max_f32_e32 v54, 0, v54
	v_max_f32_e32 v50, 0, v50
	v_max_f32_e32 v55, 0, v55
	v_max_f32_e32 v51, 0, v51
	v_max_f32_e32 v60, 0, v60
	v_mul_f32_e32 v63, v56, v56
	v_mul_f32_e32 v59, v57, v57
	v_lshl_add_u64 v[56:57], s[28:29], 0, v[64:65]
	v_mul_f32_e32 v52, v52, v52
	v_mul_f32_e32 v48, v48, v48
	v_mul_f32_e32 v53, v53, v53
	v_mul_f32_e32 v49, v49, v49
	v_mul_f32_e32 v54, v54, v54
	v_mul_f32_e32 v50, v50, v50
	v_mul_f32_e32 v55, v55, v55
	v_mul_f32_e32 v51, v51, v51
	v_max_f32_e32 v40, v40, v40
	v_mul_f32_e32 v66, v60, v60
	v_lshl_add_u64 v[60:61], v[56:57], 0, v[120:121]
	v_cvt_pk_bf16_f32 v51, v50, v51
	v_cvt_pk_bf16_f32 v50, v48, v49
	v_cvt_pk_bf16_f32 v49, v54, v55
	v_cvt_pk_bf16_f32 v48, v52, v53
	v_max_f32_e32 v40, 0, v40
	global_store_dwordx4 v[60:61], v[48:51], off offset:256
	v_max_f32_e32 v41, v41, v41
	v_max_f32_e32 v41, 0, v41
	v_mul_f32_e32 v51, v40, v40
	v_max_f32_e32 v40, v45, v45
	v_max_f32_e32 v40, 0, v40
	v_mul_f32_e32 v52, v40, v40
	v_mul_f32_e32 v53, v41, v41
	v_max_f32_e32 v40, v46, v46
	v_max_f32_e32 v41, v42, v42
	v_add_u32_e32 v48, 0x90, v148
	v_max_f32_e32 v40, 0, v40
	v_max_f32_e32 v41, 0, v41
	v_ashrrev_i32_e32 v49, 31, v48
	v_mul_f32_e32 v46, v40, v40
	v_mul_f32_e32 v42, v41, v41
	v_max_f32_e32 v40, v47, v47
	v_max_f32_e32 v41, v43, v43
	v_max_f32_e32 v36, v36, v36
	v_max_f32_e32 v32, v32, v32
	v_max_f32_e32 v37, v37, v37
	v_max_f32_e32 v33, v33, v33
	v_max_f32_e32 v38, v38, v38
	v_max_f32_e32 v34, v34, v34
	v_max_f32_e32 v39, v39, v39
	v_max_f32_e32 v35, v35, v35
	v_lshlrev_b64 v[48:49], 14, v[48:49]
	v_max_f32_e32 v44, v44, v44
	v_max_f32_e32 v40, 0, v40
	v_max_f32_e32 v41, 0, v41
	v_max_f32_e32 v36, 0, v36
	v_max_f32_e32 v32, 0, v32
	v_max_f32_e32 v37, 0, v37
	v_max_f32_e32 v33, 0, v33
	v_max_f32_e32 v38, 0, v38
	v_max_f32_e32 v34, 0, v34
	v_max_f32_e32 v39, 0, v39
	v_max_f32_e32 v35, 0, v35
	v_max_f32_e32 v44, 0, v44
	v_mul_f32_e32 v47, v40, v40
	v_mul_f32_e32 v43, v41, v41
	v_lshl_add_u64 v[40:41], s[28:29], 0, v[48:49]
	v_mul_f32_e32 v36, v36, v36
	v_mul_f32_e32 v32, v32, v32
	v_mul_f32_e32 v37, v37, v37
	v_mul_f32_e32 v33, v33, v33
	v_mul_f32_e32 v38, v38, v38
	v_mul_f32_e32 v34, v34, v34
	v_mul_f32_e32 v39, v39, v39
	v_mul_f32_e32 v35, v35, v35
	v_max_f32_e32 v24, v24, v24
	v_mul_f32_e32 v50, v44, v44
	v_lshl_add_u64 v[44:45], v[40:41], 0, v[120:121]
	v_cvt_pk_bf16_f32 v35, v34, v35
	v_cvt_pk_bf16_f32 v34, v32, v33
	v_cvt_pk_bf16_f32 v33, v38, v39
	v_cvt_pk_bf16_f32 v32, v36, v37
	v_max_f32_e32 v24, 0, v24
	global_store_dwordx4 v[44:45], v[32:35], off offset:256
	v_max_f32_e32 v25, v25, v25
	v_max_f32_e32 v25, 0, v25
	v_mul_f32_e32 v35, v24, v24
	v_max_f32_e32 v24, v29, v29
	v_max_f32_e32 v24, 0, v24
	v_mul_f32_e32 v36, v24, v24
	v_mul_f32_e32 v37, v25, v25
	v_max_f32_e32 v24, v30, v30
	v_max_f32_e32 v25, v26, v26
	v_add_u32_e32 v32, 0xa0, v148
	v_max_f32_e32 v24, 0, v24
	v_max_f32_e32 v25, 0, v25
	v_ashrrev_i32_e32 v33, 31, v32
	v_mul_f32_e32 v30, v24, v24
	v_mul_f32_e32 v26, v25, v25
	v_max_f32_e32 v24, v31, v31
	v_max_f32_e32 v25, v27, v27
	v_max_f32_e32 v20, v20, v20
	v_max_f32_e32 v16, v16, v16
	v_max_f32_e32 v21, v21, v21
	v_max_f32_e32 v17, v17, v17
	v_max_f32_e32 v22, v22, v22
	v_max_f32_e32 v18, v18, v18
	v_max_f32_e32 v23, v23, v23
	v_max_f32_e32 v19, v19, v19
	v_lshlrev_b64 v[32:33], 14, v[32:33]
	v_max_f32_e32 v28, v28, v28
	v_max_f32_e32 v24, 0, v24
	v_max_f32_e32 v25, 0, v25
	v_max_f32_e32 v20, 0, v20
	v_max_f32_e32 v16, 0, v16
	v_max_f32_e32 v21, 0, v21
	v_max_f32_e32 v17, 0, v17
	v_max_f32_e32 v22, 0, v22
	v_max_f32_e32 v18, 0, v18
	v_max_f32_e32 v23, 0, v23
	v_max_f32_e32 v19, 0, v19
	v_max_f32_e32 v28, 0, v28
	v_mul_f32_e32 v31, v24, v24
	v_mul_f32_e32 v27, v25, v25
	v_lshl_add_u64 v[24:25], s[28:29], 0, v[32:33]
	v_mul_f32_e32 v20, v20, v20
	v_mul_f32_e32 v16, v16, v16
	v_mul_f32_e32 v21, v21, v21
	v_mul_f32_e32 v17, v17, v17
	v_mul_f32_e32 v22, v22, v22
	v_mul_f32_e32 v18, v18, v18
	v_mul_f32_e32 v23, v23, v23
	v_mul_f32_e32 v19, v19, v19
	v_max_f32_e32 v8, v8, v8
	v_mul_f32_e32 v34, v28, v28
	v_lshl_add_u64 v[28:29], v[24:25], 0, v[120:121]
	v_cvt_pk_bf16_f32 v19, v18, v19
	v_cvt_pk_bf16_f32 v18, v16, v17
	v_cvt_pk_bf16_f32 v17, v22, v23
	v_cvt_pk_bf16_f32 v16, v20, v21
	v_max_f32_e32 v8, 0, v8
	global_store_dwordx4 v[28:29], v[16:19], off offset:256
	v_max_f32_e32 v9, v9, v9
	v_max_f32_e32 v9, 0, v9
	v_mul_f32_e32 v19, v8, v8
	v_max_f32_e32 v8, v13, v13
	v_max_f32_e32 v8, 0, v8
	v_mul_f32_e32 v20, v8, v8
	v_mul_f32_e32 v21, v9, v9
	v_max_f32_e32 v8, v14, v14
	v_max_f32_e32 v9, v10, v10
	v_add_u32_e32 v16, 0xb0, v148
	v_max_f32_e32 v8, 0, v8
	v_max_f32_e32 v9, 0, v9
	v_ashrrev_i32_e32 v17, 31, v16
	v_max_f32_e32 v12, v12, v12
	v_mul_f32_e32 v14, v8, v8
	v_mul_f32_e32 v10, v9, v9
	v_max_f32_e32 v8, v15, v15
	v_max_f32_e32 v9, v11, v11
	v_max_f32_e32 v4, v4, v4
	v_max_f32_e32 v0, v0, v0
	v_max_f32_e32 v5, v5, v5
	v_max_f32_e32 v1, v1, v1
	v_max_f32_e32 v6, v6, v6
	v_max_f32_e32 v2, v2, v2
	v_max_f32_e32 v7, v7, v7
	v_max_f32_e32 v3, v3, v3
	v_lshlrev_b64 v[16:17], 14, v[16:17]
	v_max_f32_e32 v12, 0, v12
	v_max_f32_e32 v8, 0, v8
	v_max_f32_e32 v9, 0, v9
	v_max_f32_e32 v4, 0, v4
	v_max_f32_e32 v0, 0, v0
	v_max_f32_e32 v5, 0, v5
	v_max_f32_e32 v1, 0, v1
	v_max_f32_e32 v6, 0, v6
	v_max_f32_e32 v2, 0, v2
	v_max_f32_e32 v7, 0, v7
	v_max_f32_e32 v3, 0, v3
	v_mul_f32_e32 v18, v12, v12
	v_mul_f32_e32 v15, v8, v8
	v_mul_f32_e32 v11, v9, v9
	v_lshl_add_u64 v[8:9], s[28:29], 0, v[16:17]
	v_mul_f32_e32 v4, v4, v4
	v_mul_f32_e32 v0, v0, v0
	v_mul_f32_e32 v5, v5, v5
	v_mul_f32_e32 v1, v1, v1
	v_mul_f32_e32 v6, v6, v6
	v_mul_f32_e32 v2, v2, v2
	v_mul_f32_e32 v7, v7, v7
	v_mul_f32_e32 v3, v3, v3
	v_cvt_pk_bf16_f32 v125, v125, v163
	v_cvt_pk_bf16_f32 v124, v124, v160
	v_cvt_pk_bf16_f32 v123, v161, v162
	v_cvt_pk_bf16_f32 v122, v149, v155
	v_cvt_pk_bf16_f32 v107, v106, v107
	v_cvt_pk_bf16_f32 v106, v115, v117
	v_cvt_pk_bf16_f32 v105, v110, v111
	v_cvt_pk_bf16_f32 v104, v114, v116
	v_cvt_pk_bf16_f32 v91, v90, v91
	v_cvt_pk_bf16_f32 v90, v99, v101
	v_cvt_pk_bf16_f32 v89, v94, v95
	v_cvt_pk_bf16_f32 v88, v98, v100
	v_cvt_pk_bf16_f32 v75, v74, v75
	v_cvt_pk_bf16_f32 v74, v83, v85
	v_cvt_pk_bf16_f32 v73, v78, v79
	v_cvt_pk_bf16_f32 v72, v82, v84
	v_cvt_pk_bf16_f32 v59, v58, v59
	v_cvt_pk_bf16_f32 v58, v67, v69
	v_cvt_pk_bf16_f32 v57, v62, v63
	v_cvt_pk_bf16_f32 v56, v66, v68
	v_cvt_pk_bf16_f32 v43, v42, v43
	v_cvt_pk_bf16_f32 v42, v51, v53
	v_cvt_pk_bf16_f32 v41, v46, v47
	v_cvt_pk_bf16_f32 v40, v50, v52
	v_cvt_pk_bf16_f32 v27, v26, v27
	v_cvt_pk_bf16_f32 v26, v35, v37
	v_cvt_pk_bf16_f32 v25, v30, v31
	v_cvt_pk_bf16_f32 v24, v34, v36
	v_lshl_add_u64 v[12:13], v[8:9], 0, v[120:121]
	v_cvt_pk_bf16_f32 v11, v10, v11
	v_cvt_pk_bf16_f32 v10, v19, v21
	v_cvt_pk_bf16_f32 v9, v14, v15
	v_cvt_pk_bf16_f32 v8, v18, v20
	v_cvt_pk_bf16_f32 v3, v2, v3
	v_cvt_pk_bf16_f32 v2, v0, v1
	v_cvt_pk_bf16_f32 v1, v6, v7
	v_cvt_pk_bf16_f32 v0, v4, v5
	global_store_dwordx4 v[126:127], v[122:125], off
	global_store_dwordx4 v[108:109], v[104:107], off
	global_store_dwordx4 v[92:93], v[88:91], off
	global_store_dwordx4 v[76:77], v[72:75], off
	global_store_dwordx4 v[60:61], v[56:59], off
	global_store_dwordx4 v[44:45], v[40:43], off
	global_store_dwordx4 v[28:29], v[24:27], off
	global_store_dwordx4 v[12:13], v[8:11], off
	global_store_dwordx4 v[12:13], v[0:3], off offset:256
.Ldup_bar_mlpin0:
	s_barrier
	s_cmpk_gt_u32 s12, 0xff
	s_cbranch_scc1 .Ldup_done_mlpin0
	v_lshl_add_u32 v148, s44, 8, v147
	v_max_f32_e32 v124, v124, v124
	v_max_f32_e32 v120, v120, v120
	v_ashrrev_i32_e32 v149, 31, v148
	v_max_f32_e32 v124, 0, v124
	v_max_f32_e32 v120, 0, v120
	v_lshlrev_b64 v[158:159], 14, v[148:149]
	v_mul_f32_e32 v149, v124, v124
	v_mul_f32_e32 v124, v120, v120
	v_max_f32_e32 v120, v125, v125
	v_max_f32_e32 v121, v121, v121
	v_max_f32_e32 v120, 0, v120
	v_max_f32_e32 v121, 0, v121
	v_mul_f32_e32 v155, v120, v120
	v_mul_f32_e32 v160, v121, v121
	v_max_f32_e32 v120, v126, v126
	v_max_f32_e32 v121, v122, v122
	v_max_f32_e32 v120, 0, v120
	v_max_f32_e32 v121, 0, v121
	v_lshl_or_b32 v156, s33, 8, v151
	v_mul_f32_e32 v161, v120, v120
	v_mul_f32_e32 v125, v121, v121
	v_max_f32_e32 v120, v127, v127
	v_max_f32_e32 v121, v123, v123
	v_max_f32_e32 v116, v116, v116
	v_max_f32_e32 v112, v112, v112
	v_max_f32_e32 v117, v117, v117
	v_max_f32_e32 v113, v113, v113
	v_max_f32_e32 v118, v118, v118
	v_max_f32_e32 v114, v114, v114
	v_max_f32_e32 v119, v119, v119
	v_max_f32_e32 v115, v115, v115
	v_ashrrev_i32_e32 v157, 31, v156
	v_max_f32_e32 v120, 0, v120
	v_max_f32_e32 v121, 0, v121
	v_max_f32_e32 v116, 0, v116
	v_max_f32_e32 v112, 0, v112
	v_max_f32_e32 v117, 0, v117
	v_max_f32_e32 v113, 0, v113
	v_max_f32_e32 v118, 0, v118
	v_max_f32_e32 v114, 0, v114
	v_max_f32_e32 v119, 0, v119
	v_max_f32_e32 v115, 0, v115
	v_mul_f32_e32 v162, v120, v120
	v_mul_f32_e32 v163, v121, v121
	v_lshl_add_u64 v[122:123], s[28:29], 0, v[158:159]
	v_lshlrev_b64 v[120:121], 1, v[156:157]
	v_mul_f32_e32 v116, v116, v116
	v_mul_f32_e32 v112, v112, v112
	v_mul_f32_e32 v117, v117, v117
	v_mul_f32_e32 v113, v113, v113
	v_mul_f32_e32 v118, v118, v118
	v_mul_f32_e32 v114, v114, v114
	v_mul_f32_e32 v119, v119, v119
	v_mul_f32_e32 v115, v115, v115
	v_max_f32_e32 v104, v104, v104
	v_lshl_add_u64 v[126:127], v[122:123], 0, v[120:121]
	v_cvt_pk_bf16_f32 v115, v114, v115
	v_cvt_pk_bf16_f32 v114, v112, v113
	v_cvt_pk_bf16_f32 v113, v118, v119
	v_cvt_pk_bf16_f32 v112, v116, v117
	v_max_f32_e32 v104, 0, v104
	global_store_dwordx4 v[126:127], v[112:115], off offset:256
	v_max_f32_e32 v105, v105, v105
	v_max_f32_e32 v105, 0, v105
	v_mul_f32_e32 v115, v104, v104
	v_max_f32_e32 v104, v109, v109
	v_max_f32_e32 v104, 0, v104
	v_mul_f32_e32 v116, v104, v104
	v_mul_f32_e32 v117, v105, v105
	v_max_f32_e32 v104, v110, v110
	v_max_f32_e32 v105, v106, v106
	v_or_b32_e32 v112, 16, v148
	v_max_f32_e32 v104, 0, v104
	v_max_f32_e32 v105, 0, v105
	v_ashrrev_i32_e32 v113, 31, v112
	v_mul_f32_e32 v110, v104, v104
	v_mul_f32_e32 v106, v105, v105
	v_max_f32_e32 v104, v111, v111
	v_max_f32_e32 v105, v107, v107
	v_max_f32_e32 v100, v100, v100
	v_max_f32_e32 v96, v96, v96
	v_max_f32_e32 v101, v101, v101
	v_max_f32_e32 v97, v97, v97
	v_max_f32_e32 v102, v102, v102
	v_max_f32_e32 v98, v98, v98
	v_max_f32_e32 v103, v103, v103
	v_max_f32_e32 v99, v99, v99
	v_lshlrev_b64 v[112:113], 14, v[112:113]
	v_max_f32_e32 v108, v108, v108
	v_max_f32_e32 v104, 0, v104
	v_max_f32_e32 v105, 0, v105
	v_max_f32_e32 v100, 0, v100
	v_max_f32_e32 v96, 0, v96
	v_max_f32_e32 v101, 0, v101
	v_max_f32_e32 v97, 0, v97
	v_max_f32_e32 v102, 0, v102
	v_max_f32_e32 v98, 0, v98
	v_max_f32_e32 v103, 0, v103
	v_max_f32_e32 v99, 0, v99
	v_max_f32_e32 v108, 0, v108
	v_mul_f32_e32 v111, v104, v104
	v_mul_f32_e32 v107, v105, v105
	v_lshl_add_u64 v[104:105], s[28:29], 0, v[112:113]
	v_mul_f32_e32 v100, v100, v100
	v_mul_f32_e32 v96, v96, v96
	v_mul_f32_e32 v101, v101, v101
	v_mul_f32_e32 v97, v97, v97
	v_mul_f32_e32 v102, v102, v102
	v_mul_f32_e32 v98, v98, v98
	v_mul_f32_e32 v103, v103, v103
	v_mul_f32_e32 v99, v99, v99
	v_max_f32_e32 v88, v88, v88
	v_mul_f32_e32 v114, v108, v108
	v_lshl_add_u64 v[108:109], v[104:105], 0, v[120:121]
	v_cvt_pk_bf16_f32 v99, v98, v99
	v_cvt_pk_bf16_f32 v98, v96, v97
	v_cvt_pk_bf16_f32 v97, v102, v103
	v_cvt_pk_bf16_f32 v96, v100, v101
	v_max_f32_e32 v88, 0, v88
	global_store_dwordx4 v[108:109], v[96:99], off offset:256
	v_max_f32_e32 v89, v89, v89
	v_max_f32_e32 v89, 0, v89
	v_mul_f32_e32 v99, v88, v88
	v_max_f32_e32 v88, v93, v93
	v_max_f32_e32 v88, 0, v88
	v_mul_f32_e32 v100, v88, v88
	v_mul_f32_e32 v101, v89, v89
	v_max_f32_e32 v88, v94, v94
	v_max_f32_e32 v89, v90, v90
	v_or_b32_e32 v96, 32, v148
	v_max_f32_e32 v88, 0, v88
	v_max_f32_e32 v89, 0, v89
	v_ashrrev_i32_e32 v97, 31, v96
	v_mul_f32_e32 v94, v88, v88
	v_mul_f32_e32 v90, v89, v89
	v_max_f32_e32 v88, v95, v95
	v_max_f32_e32 v89, v91, v91
	v_max_f32_e32 v84, v84, v84
	v_max_f32_e32 v80, v80, v80
	v_max_f32_e32 v85, v85, v85
	v_max_f32_e32 v81, v81, v81
	v_max_f32_e32 v86, v86, v86
	v_max_f32_e32 v82, v82, v82
	v_max_f32_e32 v87, v87, v87
	v_max_f32_e32 v83, v83, v83
	v_lshlrev_b64 v[96:97], 14, v[96:97]
	v_max_f32_e32 v92, v92, v92
	v_max_f32_e32 v88, 0, v88
	v_max_f32_e32 v89, 0, v89
	v_max_f32_e32 v84, 0, v84
	v_max_f32_e32 v80, 0, v80
	v_max_f32_e32 v85, 0, v85
	v_max_f32_e32 v81, 0, v81
	v_max_f32_e32 v86, 0, v86
	v_max_f32_e32 v82, 0, v82
	v_max_f32_e32 v87, 0, v87
	v_max_f32_e32 v83, 0, v83
	v_max_f32_e32 v92, 0, v92
	v_mul_f32_e32 v95, v88, v88
	v_mul_f32_e32 v91, v89, v89
	v_lshl_add_u64 v[88:89], s[28:29], 0, v[96:97]
	v_mul_f32_e32 v84, v84, v84
	v_mul_f32_e32 v80, v80, v80
	v_mul_f32_e32 v85, v85, v85
	v_mul_f32_e32 v81, v81, v81
	v_mul_f32_e32 v86, v86, v86
	v_mul_f32_e32 v82, v82, v82
	v_mul_f32_e32 v87, v87, v87
	v_mul_f32_e32 v83, v83, v83
	v_max_f32_e32 v72, v72, v72
	v_mul_f32_e32 v98, v92, v92
	v_lshl_add_u64 v[92:93], v[88:89], 0, v[120:121]
	v_cvt_pk_bf16_f32 v83, v82, v83
	v_cvt_pk_bf16_f32 v82, v80, v81
	v_cvt_pk_bf16_f32 v81, v86, v87
	v_cvt_pk_bf16_f32 v80, v84, v85
	v_max_f32_e32 v72, 0, v72
	global_store_dwordx4 v[92:93], v[80:83], off offset:256
	v_max_f32_e32 v73, v73, v73
	v_max_f32_e32 v73, 0, v73
	v_mul_f32_e32 v83, v72, v72
	v_max_f32_e32 v72, v77, v77
	v_max_f32_e32 v72, 0, v72
	v_mul_f32_e32 v84, v72, v72
	v_mul_f32_e32 v85, v73, v73
	v_max_f32_e32 v72, v78, v78
	v_max_f32_e32 v73, v74, v74
	v_or_b32_e32 v80, 48, v148
	v_max_f32_e32 v72, 0, v72
	v_max_f32_e32 v73, 0, v73
	v_ashrrev_i32_e32 v81, 31, v80
	v_mul_f32_e32 v78, v72, v72
	v_mul_f32_e32 v74, v73, v73
	v_max_f32_e32 v72, v79, v79
	v_max_f32_e32 v73, v75, v75
	v_max_f32_e32 v68, v68, v68
	v_max_f32_e32 v64, v64, v64
	v_max_f32_e32 v69, v69, v69
	v_max_f32_e32 v65, v65, v65
	v_max_f32_e32 v70, v70, v70
	v_max_f32_e32 v66, v66, v66
	v_max_f32_e32 v71, v71, v71
	v_max_f32_e32 v67, v67, v67
	v_lshlrev_b64 v[80:81], 14, v[80:81]
	v_max_f32_e32 v76, v76, v76
	v_max_f32_e32 v72, 0, v72
	v_max_f32_e32 v73, 0, v73
	v_max_f32_e32 v68, 0, v68
	v_max_f32_e32 v64, 0, v64
	v_max_f32_e32 v69, 0, v69
	v_max_f32_e32 v65, 0, v65
	v_max_f32_e32 v70, 0, v70
	v_max_f32_e32 v66, 0, v66
	v_max_f32_e32 v71, 0, v71
	v_max_f32_e32 v67, 0, v67
	v_max_f32_e32 v76, 0, v76
	v_mul_f32_e32 v79, v72, v72
	v_mul_f32_e32 v75, v73, v73
	v_lshl_add_u64 v[72:73], s[28:29], 0, v[80:81]
	v_mul_f32_e32 v68, v68, v68
	v_mul_f32_e32 v64, v64, v64
	v_mul_f32_e32 v69, v69, v69
	v_mul_f32_e32 v65, v65, v65
	v_mul_f32_e32 v70, v70, v70
	v_mul_f32_e32 v66, v66, v66
	v_mul_f32_e32 v71, v71, v71
	v_mul_f32_e32 v67, v67, v67
	v_max_f32_e32 v56, v56, v56
	v_mul_f32_e32 v82, v76, v76
	v_lshl_add_u64 v[76:77], v[72:73], 0, v[120:121]
	v_cvt_pk_bf16_f32 v67, v66, v67
	v_cvt_pk_bf16_f32 v66, v64, v65
	v_cvt_pk_bf16_f32 v65, v70, v71
	v_cvt_pk_bf16_f32 v64, v68, v69
	v_max_f32_e32 v56, 0, v56
	global_store_dwordx4 v[76:77], v[64:67], off offset:256
	v_max_f32_e32 v57, v57, v57
	v_max_f32_e32 v57, 0, v57
	v_mul_f32_e32 v67, v56, v56
	v_max_f32_e32 v56, v61, v61
	v_max_f32_e32 v56, 0, v56
	v_mul_f32_e32 v68, v56, v56
	v_mul_f32_e32 v69, v57, v57
	v_max_f32_e32 v56, v62, v62
	v_max_f32_e32 v57, v58, v58
	v_add_u32_e32 v64, 0x80, v148
	v_max_f32_e32 v56, 0, v56
	v_max_f32_e32 v57, 0, v57
	v_ashrrev_i32_e32 v65, 31, v64
	v_mul_f32_e32 v62, v56, v56
	v_mul_f32_e32 v58, v57, v57
	v_max_f32_e32 v56, v63, v63
	v_max_f32_e32 v57, v59, v59
	v_max_f32_e32 v52, v52, v52
	v_max_f32_e32 v48, v48, v48
	v_max_f32_e32 v53, v53, v53
	v_max_f32_e32 v49, v49, v49
	v_max_f32_e32 v54, v54, v54
	v_max_f32_e32 v50, v50, v50
	v_max_f32_e32 v55, v55, v55
	v_max_f32_e32 v51, v51, v51
	v_lshlrev_b64 v[64:65], 14, v[64:65]
	v_max_f32_e32 v60, v60, v60
	v_max_f32_e32 v56, 0, v56
	v_max_f32_e32 v57, 0, v57
	v_max_f32_e32 v52, 0, v52
	v_max_f32_e32 v48, 0, v48
	v_max_f32_e32 v53, 0, v53
	v_max_f32_e32 v49, 0, v49
	v_max_f32_e32 v54, 0, v54
	v_max_f32_e32 v50, 0, v50
	v_max_f32_e32 v55, 0, v55
	v_max_f32_e32 v51, 0, v51
	v_max_f32_e32 v60, 0, v60
	v_mul_f32_e32 v63, v56, v56
	v_mul_f32_e32 v59, v57, v57
	v_lshl_add_u64 v[56:57], s[28:29], 0, v[64:65]
	v_mul_f32_e32 v52, v52, v52
	v_mul_f32_e32 v48, v48, v48
	v_mul_f32_e32 v53, v53, v53
	v_mul_f32_e32 v49, v49, v49
	v_mul_f32_e32 v54, v54, v54
	v_mul_f32_e32 v50, v50, v50
	v_mul_f32_e32 v55, v55, v55
	v_mul_f32_e32 v51, v51, v51
	v_max_f32_e32 v40, v40, v40
	v_mul_f32_e32 v66, v60, v60
	v_lshl_add_u64 v[60:61], v[56:57], 0, v[120:121]
	v_cvt_pk_bf16_f32 v51, v50, v51
	v_cvt_pk_bf16_f32 v50, v48, v49
	v_cvt_pk_bf16_f32 v49, v54, v55
	v_cvt_pk_bf16_f32 v48, v52, v53
	v_max_f32_e32 v40, 0, v40
	global_store_dwordx4 v[60:61], v[48:51], off offset:256
	v_max_f32_e32 v41, v41, v41
	v_max_f32_e32 v41, 0, v41
	v_mul_f32_e32 v51, v40, v40
	v_max_f32_e32 v40, v45, v45
	v_max_f32_e32 v40, 0, v40
	v_mul_f32_e32 v52, v40, v40
	v_mul_f32_e32 v53, v41, v41
	v_max_f32_e32 v40, v46, v46
	v_max_f32_e32 v41, v42, v42
	v_add_u32_e32 v48, 0x90, v148
	v_max_f32_e32 v40, 0, v40
	v_max_f32_e32 v41, 0, v41
	v_ashrrev_i32_e32 v49, 31, v48
	v_mul_f32_e32 v46, v40, v40
	v_mul_f32_e32 v42, v41, v41
	v_max_f32_e32 v40, v47, v47
	v_max_f32_e32 v41, v43, v43
	v_max_f32_e32 v36, v36, v36
	v_max_f32_e32 v32, v32, v32
	v_max_f32_e32 v37, v37, v37
	v_max_f32_e32 v33, v33, v33
	v_max_f32_e32 v38, v38, v38
	v_max_f32_e32 v34, v34, v34
	v_max_f32_e32 v39, v39, v39
	v_max_f32_e32 v35, v35, v35
	v_lshlrev_b64 v[48:49], 14, v[48:49]
	v_max_f32_e32 v44, v44, v44
	v_max_f32_e32 v40, 0, v40
	v_max_f32_e32 v41, 0, v41
	v_max_f32_e32 v36, 0, v36
	v_max_f32_e32 v32, 0, v32
	v_max_f32_e32 v37, 0, v37
	v_max_f32_e32 v33, 0, v33
	v_max_f32_e32 v38, 0, v38
	v_max_f32_e32 v34, 0, v34
	v_max_f32_e32 v39, 0, v39
	v_max_f32_e32 v35, 0, v35
	v_max_f32_e32 v44, 0, v44
	v_mul_f32_e32 v47, v40, v40
	v_mul_f32_e32 v43, v41, v41
	v_lshl_add_u64 v[40:41], s[28:29], 0, v[48:49]
	v_mul_f32_e32 v36, v36, v36
	v_mul_f32_e32 v32, v32, v32
	v_mul_f32_e32 v37, v37, v37
	v_mul_f32_e32 v33, v33, v33
	v_mul_f32_e32 v38, v38, v38
	v_mul_f32_e32 v34, v34, v34
	v_mul_f32_e32 v39, v39, v39
	v_mul_f32_e32 v35, v35, v35
	v_max_f32_e32 v24, v24, v24
	v_mul_f32_e32 v50, v44, v44
	v_lshl_add_u64 v[44:45], v[40:41], 0, v[120:121]
	v_cvt_pk_bf16_f32 v35, v34, v35
	v_cvt_pk_bf16_f32 v34, v32, v33
	v_cvt_pk_bf16_f32 v33, v38, v39
	v_cvt_pk_bf16_f32 v32, v36, v37
	v_max_f32_e32 v24, 0, v24
	global_store_dwordx4 v[44:45], v[32:35], off offset:256
	v_max_f32_e32 v25, v25, v25
	v_max_f32_e32 v25, 0, v25
	v_mul_f32_e32 v35, v24, v24
	v_max_f32_e32 v24, v29, v29
	v_max_f32_e32 v24, 0, v24
	v_mul_f32_e32 v36, v24, v24
	v_mul_f32_e32 v37, v25, v25
	v_max_f32_e32 v24, v30, v30
	v_max_f32_e32 v25, v26, v26
	v_add_u32_e32 v32, 0xa0, v148
	v_max_f32_e32 v24, 0, v24
	v_max_f32_e32 v25, 0, v25
	v_ashrrev_i32_e32 v33, 31, v32
	v_mul_f32_e32 v30, v24, v24
	v_mul_f32_e32 v26, v25, v25
	v_max_f32_e32 v24, v31, v31
	v_max_f32_e32 v25, v27, v27
	v_max_f32_e32 v20, v20, v20
	v_max_f32_e32 v16, v16, v16
	v_max_f32_e32 v21, v21, v21
	v_max_f32_e32 v17, v17, v17
	v_max_f32_e32 v22, v22, v22
	v_max_f32_e32 v18, v18, v18
	v_max_f32_e32 v23, v23, v23
	v_max_f32_e32 v19, v19, v19
	v_lshlrev_b64 v[32:33], 14, v[32:33]
	v_max_f32_e32 v28, v28, v28
	v_max_f32_e32 v24, 0, v24
	v_max_f32_e32 v25, 0, v25
	v_max_f32_e32 v20, 0, v20
	v_max_f32_e32 v16, 0, v16
	v_max_f32_e32 v21, 0, v21
	v_max_f32_e32 v17, 0, v17
	v_max_f32_e32 v22, 0, v22
	v_max_f32_e32 v18, 0, v18
	v_max_f32_e32 v23, 0, v23
	v_max_f32_e32 v19, 0, v19
	v_max_f32_e32 v28, 0, v28
	v_mul_f32_e32 v31, v24, v24
	v_mul_f32_e32 v27, v25, v25
	v_lshl_add_u64 v[24:25], s[28:29], 0, v[32:33]
	v_mul_f32_e32 v20, v20, v20
	v_mul_f32_e32 v16, v16, v16
	v_mul_f32_e32 v21, v21, v21
	v_mul_f32_e32 v17, v17, v17
	v_mul_f32_e32 v22, v22, v22
	v_mul_f32_e32 v18, v18, v18
	v_mul_f32_e32 v23, v23, v23
	v_mul_f32_e32 v19, v19, v19
	v_max_f32_e32 v8, v8, v8
	v_mul_f32_e32 v34, v28, v28
	v_lshl_add_u64 v[28:29], v[24:25], 0, v[120:121]
	v_cvt_pk_bf16_f32 v19, v18, v19
	v_cvt_pk_bf16_f32 v18, v16, v17
	v_cvt_pk_bf16_f32 v17, v22, v23
	v_cvt_pk_bf16_f32 v16, v20, v21
	v_max_f32_e32 v8, 0, v8
	global_store_dwordx4 v[28:29], v[16:19], off offset:256
	v_max_f32_e32 v9, v9, v9
	v_max_f32_e32 v9, 0, v9
	v_mul_f32_e32 v19, v8, v8
	v_max_f32_e32 v8, v13, v13
	v_max_f32_e32 v8, 0, v8
	v_mul_f32_e32 v20, v8, v8
	v_mul_f32_e32 v21, v9, v9
	v_max_f32_e32 v8, v14, v14
	v_max_f32_e32 v9, v10, v10
	v_add_u32_e32 v16, 0xb0, v148
	v_max_f32_e32 v8, 0, v8
	v_max_f32_e32 v9, 0, v9
	v_ashrrev_i32_e32 v17, 31, v16
	v_max_f32_e32 v12, v12, v12
	v_mul_f32_e32 v14, v8, v8
	v_mul_f32_e32 v10, v9, v9
	v_max_f32_e32 v8, v15, v15
	v_max_f32_e32 v9, v11, v11
	v_max_f32_e32 v4, v4, v4
	v_max_f32_e32 v0, v0, v0
	v_max_f32_e32 v5, v5, v5
	v_max_f32_e32 v1, v1, v1
	v_max_f32_e32 v6, v6, v6
	v_max_f32_e32 v2, v2, v2
	v_max_f32_e32 v7, v7, v7
	v_max_f32_e32 v3, v3, v3
	v_lshlrev_b64 v[16:17], 14, v[16:17]
	v_max_f32_e32 v12, 0, v12
	v_max_f32_e32 v8, 0, v8
	v_max_f32_e32 v9, 0, v9
	v_max_f32_e32 v4, 0, v4
	v_max_f32_e32 v0, 0, v0
	v_max_f32_e32 v5, 0, v5
	v_max_f32_e32 v1, 0, v1
	v_max_f32_e32 v6, 0, v6
	v_max_f32_e32 v2, 0, v2
	v_max_f32_e32 v7, 0, v7
	v_max_f32_e32 v3, 0, v3
	v_mul_f32_e32 v18, v12, v12
	v_mul_f32_e32 v15, v8, v8
	v_mul_f32_e32 v11, v9, v9
	v_lshl_add_u64 v[8:9], s[28:29], 0, v[16:17]
	v_mul_f32_e32 v4, v4, v4
	v_mul_f32_e32 v0, v0, v0
	v_mul_f32_e32 v5, v5, v5
	v_mul_f32_e32 v1, v1, v1
	v_mul_f32_e32 v6, v6, v6
	v_mul_f32_e32 v2, v2, v2
	v_mul_f32_e32 v7, v7, v7
	v_mul_f32_e32 v3, v3, v3
	v_cvt_pk_bf16_f32 v125, v125, v163
	v_cvt_pk_bf16_f32 v124, v124, v160
	v_cvt_pk_bf16_f32 v123, v161, v162
	v_cvt_pk_bf16_f32 v122, v149, v155
	v_cvt_pk_bf16_f32 v107, v106, v107
	v_cvt_pk_bf16_f32 v106, v115, v117
	v_cvt_pk_bf16_f32 v105, v110, v111
	v_cvt_pk_bf16_f32 v104, v114, v116
	v_cvt_pk_bf16_f32 v91, v90, v91
	v_cvt_pk_bf16_f32 v90, v99, v101
	v_cvt_pk_bf16_f32 v89, v94, v95
	v_cvt_pk_bf16_f32 v88, v98, v100
	v_cvt_pk_bf16_f32 v75, v74, v75
	v_cvt_pk_bf16_f32 v74, v83, v85
	v_cvt_pk_bf16_f32 v73, v78, v79
	v_cvt_pk_bf16_f32 v72, v82, v84
	v_cvt_pk_bf16_f32 v59, v58, v59
	v_cvt_pk_bf16_f32 v58, v67, v69
	v_cvt_pk_bf16_f32 v57, v62, v63
	v_cvt_pk_bf16_f32 v56, v66, v68
	v_cvt_pk_bf16_f32 v43, v42, v43
	v_cvt_pk_bf16_f32 v42, v51, v53
	v_cvt_pk_bf16_f32 v41, v46, v47
	v_cvt_pk_bf16_f32 v40, v50, v52
	v_cvt_pk_bf16_f32 v27, v26, v27
	v_cvt_pk_bf16_f32 v26, v35, v37
	v_cvt_pk_bf16_f32 v25, v30, v31
	v_cvt_pk_bf16_f32 v24, v34, v36
	v_lshl_add_u64 v[12:13], v[8:9], 0, v[120:121]
	v_cvt_pk_bf16_f32 v11, v10, v11
	v_cvt_pk_bf16_f32 v10, v19, v21
	v_cvt_pk_bf16_f32 v9, v14, v15
	v_cvt_pk_bf16_f32 v8, v18, v20
	v_cvt_pk_bf16_f32 v3, v2, v3
	v_cvt_pk_bf16_f32 v2, v0, v1
	v_cvt_pk_bf16_f32 v1, v6, v7
	v_cvt_pk_bf16_f32 v0, v4, v5
	global_store_dwordx4 v[126:127], v[122:125], off
	global_store_dwordx4 v[108:109], v[104:107], off
	global_store_dwordx4 v[92:93], v[88:91], off
	global_store_dwordx4 v[76:77], v[72:75], off
	global_store_dwordx4 v[60:61], v[56:59], off
	global_store_dwordx4 v[44:45], v[40:43], off
	global_store_dwordx4 v[28:29], v[24:27], off
	global_store_dwordx4 v[12:13], v[8:11], off
	global_store_dwordx4 v[12:13], v[0:3], off offset:256

.LBB0_1030:
	ds_read_b128 v[148:151], v159
	ds_read_b128 v[152:155], v159 offset:1024
	ds_read_b128 v[162:165], v159 offset:2048
	ds_read_b128 v[166:169], v159 offset:3072
	s_add_u32 s20, s48, 0xffe00080
	s_addc_u32 s21, s49, -1
	s_cmpk_eq_i32 s63, 0x7c
	s_cselect_b32 s21, s17, s21
	s_cselect_b32 s20, s59, s20
	s_cselect_b32 s51, s15, s62
	s_cselect_b32 s50, s60, s61
	v_lshl_add_u64 v[190:191], s[48:49], 0, v[136:137]
	s_add_i32 m0, s37, 0xc000
	ds_read_b128 v[170:173], v160
	ds_read_b128 v[174:177], v160 offset:1024
	ds_read_b128 v[178:181], v160 offset:2048
	ds_read_b128 v[182:185], v160 offset:3072
	ds_read_b128 v[186:189], v160 offset:4096
	ds_read_b128 v[196:199], v160 offset:5120
	ds_read_b128 v[200:203], v160 offset:6144
	ds_read_b128 v[204:207], v160 offset:7168
	global_load_lds_dwordx4 v[190:191], off
	s_add_i32 m0, s37, 0xe000
	v_lshl_add_u64 v[190:191], s[48:49], 0, v[138:139]
	global_load_lds_dwordx4 v[190:191], off
	s_waitcnt lgkmcnt(8)
	s_barrier
	s_waitcnt lgkmcnt(0)
	s_setprio 1
	v_mfma_f32_16x16x32_bf16 v[124:127], v[148:151], v[170:173], v[124:127]
	v_mfma_f32_16x16x32_bf16 v[120:123], v[162:165], v[170:173], v[120:123]
	v_mfma_f32_16x16x32_bf16 v[108:111], v[148:151], v[178:181], v[108:111]
	v_mfma_f32_16x16x32_bf16 v[104:107], v[162:165], v[178:181], v[104:107]
	v_mfma_f32_16x16x32_bf16 v[92:95], v[148:151], v[186:189], v[92:95]
	v_mfma_f32_16x16x32_bf16 v[88:91], v[162:165], v[186:189], v[88:91]
	v_mfma_f32_16x16x32_bf16 v[76:79], v[148:151], v[200:203], v[76:79]
	v_mfma_f32_16x16x32_bf16 v[72:75], v[162:165], v[200:203], v[72:75]
	v_mfma_f32_16x16x32_bf16 v[124:127], v[152:155], v[174:177], v[124:127]
	v_mfma_f32_16x16x32_bf16 v[120:123], v[166:169], v[174:177], v[120:123]
	v_mfma_f32_16x16x32_bf16 v[108:111], v[152:155], v[182:185], v[108:111]
	v_mfma_f32_16x16x32_bf16 v[104:107], v[166:169], v[182:185], v[104:107]
	v_mfma_f32_16x16x32_bf16 v[92:95], v[152:155], v[196:199], v[92:95]
	v_mfma_f32_16x16x32_bf16 v[88:91], v[166:169], v[196:199], v[88:91]
	v_mfma_f32_16x16x32_bf16 v[76:79], v[152:155], v[204:207], v[76:79]
	v_mfma_f32_16x16x32_bf16 v[72:75], v[166:169], v[204:207], v[72:75]
	s_setprio 0
	s_barrier
	s_add_i32 s64, s55, s23
	v_lshl_add_u64 v[190:191], s[50:51], 0, v[132:133]
	s_mov_b32 m0, s64
	ds_read_b128 v[208:211], v161
	ds_read_b128 v[212:215], v161 offset:1024
	ds_read_b128 v[216:219], v161 offset:2048
	ds_read_b128 v[220:223], v161 offset:3072
	global_load_lds_dwordx4 v[190:191], off
	s_add_i32 m0, s64, 0x2000
	v_lshl_add_u64 v[224:225], s[50:51], 0, v[128:129]
	global_load_lds_dwordx4 v[224:225], off
	s_barrier
	s_waitcnt lgkmcnt(0)
	s_setprio 1
	v_mfma_f32_16x16x32_bf16 v[116:119], v[208:211], v[170:173], v[116:119]
	v_mfma_f32_16x16x32_bf16 v[112:115], v[216:219], v[170:173], v[112:115]
	v_mfma_f32_16x16x32_bf16 v[100:103], v[208:211], v[178:181], v[100:103]
	v_mfma_f32_16x16x32_bf16 v[96:99], v[216:219], v[178:181], v[96:99]
	v_mfma_f32_16x16x32_bf16 v[84:87], v[208:211], v[186:189], v[84:87]
	v_mfma_f32_16x16x32_bf16 v[80:83], v[216:219], v[186:189], v[80:83]
	v_mfma_f32_16x16x32_bf16 v[68:71], v[208:211], v[200:203], v[68:71]
	v_mfma_f32_16x16x32_bf16 v[64:67], v[216:219], v[200:203], v[64:67]
	v_mfma_f32_16x16x32_bf16 v[116:119], v[212:215], v[174:177], v[116:119]
	v_mfma_f32_16x16x32_bf16 v[112:115], v[220:223], v[174:177], v[112:115]
	v_mfma_f32_16x16x32_bf16 v[100:103], v[212:215], v[182:185], v[100:103]
	v_mfma_f32_16x16x32_bf16 v[96:99], v[220:223], v[182:185], v[96:99]
	v_mfma_f32_16x16x32_bf16 v[84:87], v[212:215], v[196:199], v[84:87]
	v_mfma_f32_16x16x32_bf16 v[80:83], v[220:223], v[196:199], v[80:83]
	v_mfma_f32_16x16x32_bf16 v[68:71], v[212:215], v[204:207], v[68:71]
	v_mfma_f32_16x16x32_bf16 v[64:67], v[220:223], v[204:207], v[64:67]
	s_setprio 0
	s_mov_b32 m0, s37
	v_lshl_add_u64 v[226:227], s[20:21], 0, v[134:135]
	s_barrier
	ds_read_b128 v[170:173], v160 offset:16384
	ds_read_b128 v[174:177], v160 offset:17408
	ds_read_b128 v[178:181], v160 offset:18432
	ds_read_b128 v[182:185], v160 offset:19456
	ds_read_b128 v[186:189], v160 offset:20480
	ds_read_b128 v[196:199], v160 offset:21504
	ds_read_b128 v[200:203], v160 offset:22528
	ds_read_b128 v[204:207], v160 offset:23552
	global_load_lds_dwordx4 v[226:227], off
	s_mov_b32 m0, s38
	v_lshl_add_u64 v[228:229], s[20:21], 0, v[130:131]
	global_load_lds_dwordx4 v[228:229], off
	s_barrier
	s_waitcnt lgkmcnt(0)
	s_setprio 1
	v_mfma_f32_16x16x32_bf16 v[60:63], v[148:151], v[170:173], v[60:63]
	v_mfma_f32_16x16x32_bf16 v[56:59], v[162:165], v[170:173], v[56:59]
	v_mfma_f32_16x16x32_bf16 v[44:47], v[148:151], v[178:181], v[44:47]
	v_mfma_f32_16x16x32_bf16 v[40:43], v[162:165], v[178:181], v[40:43]
	v_mfma_f32_16x16x32_bf16 v[28:31], v[148:151], v[186:189], v[28:31]
	v_mfma_f32_16x16x32_bf16 v[24:27], v[162:165], v[186:189], v[24:27]
	v_mfma_f32_16x16x32_bf16 v[12:15], v[148:151], v[200:203], v[12:15]
	v_mfma_f32_16x16x32_bf16 v[8:11], v[162:165], v[200:203], v[8:11]
	v_mfma_f32_16x16x32_bf16 v[60:63], v[152:155], v[174:177], v[60:63]
	v_mfma_f32_16x16x32_bf16 v[56:59], v[166:169], v[174:177], v[56:59]
	v_mfma_f32_16x16x32_bf16 v[44:47], v[152:155], v[182:185], v[44:47]
	v_mfma_f32_16x16x32_bf16 v[40:43], v[166:169], v[182:185], v[40:43]
	v_mfma_f32_16x16x32_bf16 v[28:31], v[152:155], v[196:199], v[28:31]
	v_mfma_f32_16x16x32_bf16 v[24:27], v[166:169], v[196:199], v[24:27]
	v_mfma_f32_16x16x32_bf16 v[12:15], v[152:155], v[204:207], v[12:15]
	v_mfma_f32_16x16x32_bf16 v[8:11], v[166:169], v[204:207], v[8:11]
	s_setprio 0
	s_barrier
	s_add_u32 s64, s50, 0x200000
	s_addc_u32 s65, s51, 0
	s_add_i32 s66, s57, s23
	s_mov_b32 m0, s66
	v_lshl_add_u64 v[148:149], s[64:65], 0, v[132:133]
	global_load_lds_dwordx4 v[148:149], off
	s_add_i32 m0, s66, 0x2000
	v_lshl_add_u64 v[148:149], s[64:65], 0, v[128:129]
	global_load_lds_dwordx4 v[148:149], off
	s_waitcnt vmcnt(6)
	s_barrier
	s_setprio 1
	v_mfma_f32_16x16x32_bf16 v[52:55], v[208:211], v[170:173], v[52:55]
	v_mfma_f32_16x16x32_bf16 v[48:51], v[216:219], v[170:173], v[48:51]
	v_mfma_f32_16x16x32_bf16 v[36:39], v[208:211], v[178:181], v[36:39]
	v_mfma_f32_16x16x32_bf16 v[32:35], v[216:219], v[178:181], v[32:35]
	v_mfma_f32_16x16x32_bf16 v[20:23], v[208:211], v[186:189], v[20:23]
	v_mfma_f32_16x16x32_bf16 v[16:19], v[216:219], v[186:189], v[16:19]
	v_mfma_f32_16x16x32_bf16 v[4:7], v[208:211], v[200:203], v[4:7]
	v_mfma_f32_16x16x32_bf16 v[0:3], v[216:219], v[200:203], v[0:3]
	v_mfma_f32_16x16x32_bf16 v[52:55], v[212:215], v[174:177], v[52:55]
	v_mfma_f32_16x16x32_bf16 v[48:51], v[220:223], v[174:177], v[48:51]
	v_mfma_f32_16x16x32_bf16 v[36:39], v[212:215], v[182:185], v[36:39]
	v_mfma_f32_16x16x32_bf16 v[32:35], v[220:223], v[182:185], v[32:35]
	v_mfma_f32_16x16x32_bf16 v[20:23], v[212:215], v[196:199], v[20:23]
	v_mfma_f32_16x16x32_bf16 v[16:19], v[220:223], v[196:199], v[16:19]
	v_mfma_f32_16x16x32_bf16 v[4:7], v[212:215], v[204:207], v[4:7]
	v_mfma_f32_16x16x32_bf16 v[0:3], v[220:223], v[204:207], v[0:3]
	s_setprio 0
	s_add_i32 s64, 0, 0x18000
	v_add_u32_e32 v166, s64, v156
	s_barrier
	ds_read_b128 v[148:151], v166
	ds_read_b128 v[152:155], v166 offset:1024
	ds_read_b128 v[162:165], v166 offset:2048
	ds_read_b128 v[166:169], v166 offset:3072
	s_add_u32 s20, s20, 0x200000
	s_addc_u32 s21, s21, 0
	s_mov_b32 m0, s39
	v_lshl_add_u64 v[208:209], s[20:21], 0, v[134:135]
	ds_read_b128 v[170:173], v160 offset:32768
	ds_read_b128 v[174:177], v160 offset:33792
	ds_read_b128 v[178:181], v160 offset:34816
	ds_read_b128 v[182:185], v160 offset:35840
	ds_read_b128 v[186:189], v160 offset:36864
	ds_read_b128 v[196:199], v160 offset:37888
	ds_read_b128 v[200:203], v160 offset:38912
	ds_read_b128 v[204:207], v160 offset:39936
	global_load_lds_dwordx4 v[208:209], off
	s_mov_b32 m0, s47
	v_lshl_add_u64 v[208:209], s[20:21], 0, v[130:131]
	global_load_lds_dwordx4 v[208:209], off
	s_waitcnt lgkmcnt(8)
	s_barrier
	s_waitcnt lgkmcnt(0)
	s_setprio 1
	v_mfma_f32_16x16x32_bf16 v[124:127], v[148:151], v[170:173], v[124:127]
	v_mfma_f32_16x16x32_bf16 v[120:123], v[162:165], v[170:173], v[120:123]
	v_mfma_f32_16x16x32_bf16 v[108:111], v[148:151], v[178:181], v[108:111]
	v_mfma_f32_16x16x32_bf16 v[104:107], v[162:165], v[178:181], v[104:107]
	v_mfma_f32_16x16x32_bf16 v[92:95], v[148:151], v[186:189], v[92:95]
	v_mfma_f32_16x16x32_bf16 v[88:91], v[162:165], v[186:189], v[88:91]
	v_mfma_f32_16x16x32_bf16 v[76:79], v[148:151], v[200:203], v[76:79]
	v_mfma_f32_16x16x32_bf16 v[72:75], v[162:165], v[200:203], v[72:75]
	v_mfma_f32_16x16x32_bf16 v[124:127], v[152:155], v[174:177], v[124:127]
	v_mfma_f32_16x16x32_bf16 v[120:123], v[166:169], v[174:177], v[120:123]
	v_mfma_f32_16x16x32_bf16 v[108:111], v[152:155], v[182:185], v[108:111]
	v_mfma_f32_16x16x32_bf16 v[104:107], v[166:169], v[182:185], v[104:107]
	v_mfma_f32_16x16x32_bf16 v[92:95], v[152:155], v[196:199], v[92:95]
	v_mfma_f32_16x16x32_bf16 v[88:91], v[166:169], v[196:199], v[88:91]
	v_mfma_f32_16x16x32_bf16 v[76:79], v[152:155], v[204:207], v[76:79]
	v_mfma_f32_16x16x32_bf16 v[72:75], v[166:169], v[204:207], v[72:75]
	s_setprio 0
	s_barrier
	s_add_i32 s65, 0, 0x1c000
	s_add_i32 s20, s64, s23
	v_add_u32_e32 v195, s65, v156
	v_lshl_add_u64 v[190:191], v[190:191], 0, s[10:11]
	s_mov_b32 m0, s20
	ds_read_b128 v[208:211], v195
	ds_read_b128 v[212:215], v195 offset:1024
	ds_read_b128 v[216:219], v195 offset:2048
	ds_read_b128 v[220:223], v195 offset:3072
	global_load_lds_dwordx4 v[190:191], off
	s_add_i32 m0, s20, 0x2000
	v_lshl_add_u64 v[190:191], v[224:225], 0, s[10:11]
	global_load_lds_dwordx4 v[190:191], off
	s_barrier
	s_waitcnt lgkmcnt(0)
	s_setprio 1
	v_mfma_f32_16x16x32_bf16 v[116:119], v[208:211], v[170:173], v[116:119]
	v_mfma_f32_16x16x32_bf16 v[112:115], v[216:219], v[170:173], v[112:115]
	v_mfma_f32_16x16x32_bf16 v[100:103], v[208:211], v[178:181], v[100:103]
	v_mfma_f32_16x16x32_bf16 v[96:99], v[216:219], v[178:181], v[96:99]
	v_mfma_f32_16x16x32_bf16 v[84:87], v[208:211], v[186:189], v[84:87]
	v_mfma_f32_16x16x32_bf16 v[80:83], v[216:219], v[186:189], v[80:83]
	v_mfma_f32_16x16x32_bf16 v[68:71], v[208:211], v[200:203], v[68:71]
	v_mfma_f32_16x16x32_bf16 v[64:67], v[216:219], v[200:203], v[64:67]
	v_mfma_f32_16x16x32_bf16 v[116:119], v[212:215], v[174:177], v[116:119]
	v_mfma_f32_16x16x32_bf16 v[112:115], v[220:223], v[174:177], v[112:115]
	v_mfma_f32_16x16x32_bf16 v[100:103], v[212:215], v[182:185], v[100:103]
	v_mfma_f32_16x16x32_bf16 v[96:99], v[220:223], v[182:185], v[96:99]
	v_mfma_f32_16x16x32_bf16 v[84:87], v[212:215], v[196:199], v[84:87]
	v_mfma_f32_16x16x32_bf16 v[80:83], v[220:223], v[196:199], v[80:83]
	v_mfma_f32_16x16x32_bf16 v[68:71], v[212:215], v[204:207], v[68:71]
	v_mfma_f32_16x16x32_bf16 v[64:67], v[220:223], v[204:207], v[64:67]
	s_setprio 0
	s_mov_b32 m0, s34
	v_lshl_add_u64 v[190:191], v[226:227], 0, s[10:11]
	s_barrier
	ds_read_b128 v[170:173], v160 offset:49152
	ds_read_b128 v[174:177], v160 offset:50176
	ds_read_b128 v[178:181], v160 offset:51200
	ds_read_b128 v[182:185], v160 offset:52224
	ds_read_b128 v[186:189], v160 offset:53248
	ds_read_b128 v[196:199], v160 offset:54272
	ds_read_b128 v[200:203], v160 offset:55296
	ds_read_b128 v[204:207], v160 offset:56320
	global_load_lds_dwordx4 v[190:191], off
	s_mov_b32 m0, s35
	v_lshl_add_u64 v[190:191], v[228:229], 0, s[10:11]
	global_load_lds_dwordx4 v[190:191], off
	s_barrier
	s_waitcnt lgkmcnt(0)
	s_setprio 1
	v_mfma_f32_16x16x32_bf16 v[60:63], v[148:151], v[170:173], v[60:63]
	v_mfma_f32_16x16x32_bf16 v[56:59], v[162:165], v[170:173], v[56:59]
	v_mfma_f32_16x16x32_bf16 v[44:47], v[148:151], v[178:181], v[44:47]
	v_mfma_f32_16x16x32_bf16 v[40:43], v[162:165], v[178:181], v[40:43]
	v_mfma_f32_16x16x32_bf16 v[28:31], v[148:151], v[186:189], v[28:31]
	v_mfma_f32_16x16x32_bf16 v[24:27], v[162:165], v[186:189], v[24:27]
	v_mfma_f32_16x16x32_bf16 v[12:15], v[148:151], v[200:203], v[12:15]
	v_mfma_f32_16x16x32_bf16 v[8:11], v[162:165], v[200:203], v[8:11]
	v_mfma_f32_16x16x32_bf16 v[60:63], v[152:155], v[174:177], v[60:63]
	v_mfma_f32_16x16x32_bf16 v[56:59], v[166:169], v[174:177], v[56:59]
	v_mfma_f32_16x16x32_bf16 v[44:47], v[152:155], v[182:185], v[44:47]
	v_mfma_f32_16x16x32_bf16 v[40:43], v[166:169], v[182:185], v[40:43]
	v_mfma_f32_16x16x32_bf16 v[28:31], v[152:155], v[196:199], v[28:31]
	v_mfma_f32_16x16x32_bf16 v[24:27], v[166:169], v[196:199], v[24:27]
	v_mfma_f32_16x16x32_bf16 v[12:15], v[152:155], v[204:207], v[12:15]
	v_mfma_f32_16x16x32_bf16 v[8:11], v[166:169], v[204:207], v[8:11]
	s_setprio 0
	s_barrier
	s_add_u32 s20, s50, 0x200080
	s_addc_u32 s21, s51, 0
	s_add_i32 s50, s65, s23
	s_mov_b32 m0, s50
	v_lshl_add_u64 v[148:149], s[20:21], 0, v[132:133]
	global_load_lds_dwordx4 v[148:149], off
	s_add_i32 m0, s50, 0x2000
	v_lshl_add_u64 v[148:149], s[20:21], 0, v[128:129]
	global_load_lds_dwordx4 v[148:149], off
	s_waitcnt vmcnt(6)
	s_barrier
	s_setprio 1
	v_mfma_f32_16x16x32_bf16 v[52:55], v[208:211], v[170:173], v[52:55]
	v_mfma_f32_16x16x32_bf16 v[48:51], v[216:219], v[170:173], v[48:51]
	v_mfma_f32_16x16x32_bf16 v[36:39], v[208:211], v[178:181], v[36:39]
	v_mfma_f32_16x16x32_bf16 v[32:35], v[216:219], v[178:181], v[32:35]
	v_mfma_f32_16x16x32_bf16 v[20:23], v[208:211], v[186:189], v[20:23]
	v_mfma_f32_16x16x32_bf16 v[16:19], v[216:219], v[186:189], v[16:19]
	v_mfma_f32_16x16x32_bf16 v[4:7], v[208:211], v[200:203], v[4:7]
	v_mfma_f32_16x16x32_bf16 v[0:3], v[216:219], v[200:203], v[0:3]
	v_mfma_f32_16x16x32_bf16 v[52:55], v[212:215], v[174:177], v[52:55]
	v_mfma_f32_16x16x32_bf16 v[48:51], v[220:223], v[174:177], v[48:51]
	v_mfma_f32_16x16x32_bf16 v[36:39], v[212:215], v[182:185], v[36:39]
	v_mfma_f32_16x16x32_bf16 v[32:35], v[220:223], v[182:185], v[32:35]
	v_mfma_f32_16x16x32_bf16 v[20:23], v[212:215], v[196:199], v[20:23]
	v_mfma_f32_16x16x32_bf16 v[16:19], v[220:223], v[196:199], v[16:19]
	v_mfma_f32_16x16x32_bf16 v[4:7], v[212:215], v[204:207], v[4:7]
	v_mfma_f32_16x16x32_bf16 v[0:3], v[220:223], v[204:207], v[0:3]
	s_setprio 0
	s_add_i32 s63, s63, 2
	s_add_u32 s48, s48, 0x100
	s_addc_u32 s49, s49, 0
	s_add_u32 s61, s61, 0x100
	s_addc_u32 s62, s62, 0
	s_cmpk_gt_u32 s63, 0x7d
	s_cbranch_scc1 .Lepi_last_mlpout0
	s_barrier
	s_branch .LBB0_1030
.Lepi_last_mlpout0:
	s_cmp_lg_u32 s53, 64
	s_cbranch_scc1 .Lepi_bar_mlpout0
	s_lshl_b32 s15, s46, 8
	s_add_i32 s15, s15, s53
	v_or_b32_e32 v154, s15, v147
	s_add_i32 s17, s15, 0xffffe000
	v_lshl_or_b32 v150, s33, 8, v158
	s_lshr_b32 s17, s17, 12
	v_lshlrev_b32_e32 v148, 12, v154
	s_add_i32 s17, s17, 1
	s_cmp_gt_i32 s15, s58
	s_cselect_b32 s17, s17, 0
	s_mul_i32 s17, s17, s56
	v_lshl_add_u32 v148, v150, 1, v148
	s_add_u32 s20, s8, s17
	s_addc_u32 s21, s9, 0
	v_lshlrev_b32_e32 v149, 2, v150
	s_nop 0
	global_load_dwordx4 v[196:199], v149, s[20:21]
	global_load_dwordx4 v[200:203], v149, s[20:21] offset:16
	global_load_dwordx4 v[204:207], v149, s[20:21] offset:512
	global_load_dwordx4 v[208:211], v149, s[20:21] offset:528
	global_load_dwordx4 v[212:215], v148, s[74:75]
	global_load_dwordx4 v[216:219], v148, s[74:75] offset:256
	v_add_u32_e32 v151, 0x10000, v148
	global_load_dwordx4 v[220:223], v151, s[74:75]
	global_load_dwordx4 v[224:227], v151, s[74:75] offset:256
	v_add_u32_e32 v151, 0x20000, v148
	global_load_dwordx4 v[164:167], v151, s[74:75]
	global_load_dwordx4 v[168:171], v151, s[74:75] offset:256
	v_add_u32_e32 v151, 0x30000, v148
	global_load_dwordx4 v[172:175], v151, s[74:75]
	global_load_dwordx4 v[176:179], v151, s[74:75] offset:256
	s_waitcnt vmcnt(0)
	v_lshlrev_b32_e32 v180, 16, v212
	v_and_b32_e32 v181, 0xffff0000, v212
	v_lshlrev_b32_e32 v182, 16, v213
	v_and_b32_e32 v183, 0xffff0000, v213
	v_lshlrev_b32_e32 v184, 16, v214
	v_and_b32_e32 v185, 0xffff0000, v214
	v_lshlrev_b32_e32 v186, 16, v215
	v_and_b32_e32 v187, 0xffff0000, v215
	v_pk_fma_f32 v[124:125], v[124:125], v[196:197], v[180:181]
	v_pk_fma_f32 v[126:127], v[126:127], v[198:199], v[182:183]
	v_pk_fma_f32 v[120:121], v[120:121], v[200:201], v[184:185]
	v_pk_fma_f32 v[122:123], v[122:123], v[202:203], v[186:187]
	v_cvt_pk_bf16_f32 v123, v122, v123
	v_cvt_pk_bf16_f32 v122, v120, v121
	v_cvt_pk_bf16_f32 v121, v126, v127
	v_cvt_pk_bf16_f32 v120, v124, v125
	global_store_dwordx4 v148, v[120:123], s[74:75]
	v_lshlrev_b32_e32 v180, 16, v216
	v_and_b32_e32 v181, 0xffff0000, v216
	v_lshlrev_b32_e32 v182, 16, v217
	v_and_b32_e32 v183, 0xffff0000, v217
	v_lshlrev_b32_e32 v184, 16, v218
	v_and_b32_e32 v185, 0xffff0000, v218
	v_lshlrev_b32_e32 v186, 16, v219
	v_and_b32_e32 v187, 0xffff0000, v219
	v_pk_fma_f32 v[116:117], v[116:117], v[204:205], v[180:181]
	v_pk_fma_f32 v[118:119], v[118:119], v[206:207], v[182:183]
	v_pk_fma_f32 v[112:113], v[112:113], v[208:209], v[184:185]
	v_pk_fma_f32 v[114:115], v[114:115], v[210:211], v[186:187]
	v_cvt_pk_bf16_f32 v115, v114, v115
	v_cvt_pk_bf16_f32 v114, v112, v113
	v_cvt_pk_bf16_f32 v113, v118, v119
	v_cvt_pk_bf16_f32 v112, v116, v117
	global_store_dwordx4 v148, v[112:115], s[74:75] offset:256
	v_lshlrev_b32_e32 v180, 16, v220
	v_and_b32_e32 v181, 0xffff0000, v220
	v_lshlrev_b32_e32 v182, 16, v221
	v_and_b32_e32 v183, 0xffff0000, v221
	v_lshlrev_b32_e32 v184, 16, v222
	v_and_b32_e32 v185, 0xffff0000, v222
	v_lshlrev_b32_e32 v186, 16, v223
	v_and_b32_e32 v187, 0xffff0000, v223
	v_pk_fma_f32 v[108:109], v[108:109], v[196:197], v[180:181]
	v_pk_fma_f32 v[110:111], v[110:111], v[198:199], v[182:183]
	v_pk_fma_f32 v[104:105], v[104:105], v[200:201], v[184:185]
	v_pk_fma_f32 v[106:107], v[106:107], v[202:203], v[186:187]
	v_cvt_pk_bf16_f32 v107, v106, v107
	v_cvt_pk_bf16_f32 v106, v104, v105
	v_cvt_pk_bf16_f32 v105, v110, v111
	v_cvt_pk_bf16_f32 v104, v108, v109
	v_add_u32_e32 v151, 0x10000, v148
	global_store_dwordx4 v151, v[104:107], s[74:75]
	v_lshlrev_b32_e32 v180, 16, v224
	v_and_b32_e32 v181, 0xffff0000, v224
	v_lshlrev_b32_e32 v182, 16, v225
	v_and_b32_e32 v183, 0xffff0000, v225
	v_lshlrev_b32_e32 v184, 16, v226
	v_and_b32_e32 v185, 0xffff0000, v226
	v_lshlrev_b32_e32 v186, 16, v227
	v_and_b32_e32 v187, 0xffff0000, v227
	v_pk_fma_f32 v[100:101], v[100:101], v[204:205], v[180:181]
	v_pk_fma_f32 v[102:103], v[102:103], v[206:207], v[182:183]
	v_pk_fma_f32 v[96:97], v[96:97], v[208:209], v[184:185]
	v_pk_fma_f32 v[98:99], v[98:99], v[210:211], v[186:187]
	v_cvt_pk_bf16_f32 v99, v98, v99
	v_cvt_pk_bf16_f32 v98, v96, v97
	v_cvt_pk_bf16_f32 v97, v102, v103
	v_cvt_pk_bf16_f32 v96, v100, v101
	v_add_u32_e32 v151, 0x10000, v148
	global_store_dwordx4 v151, v[96:99], s[74:75] offset:256
	v_add_u32_e32 v151, 0x80000, v148
	global_load_dwordx4 v[212:215], v151, s[74:75]
	global_load_dwordx4 v[216:219], v151, s[74:75] offset:256
	v_add_u32_e32 v151, 0x90000, v148
	global_load_dwordx4 v[220:223], v151, s[74:75]
	global_load_dwordx4 v[224:227], v151, s[74:75] offset:256
	v_lshlrev_b32_e32 v180, 16, v164
	v_and_b32_e32 v181, 0xffff0000, v164
	v_lshlrev_b32_e32 v182, 16, v165
	v_and_b32_e32 v183, 0xffff0000, v165
	v_lshlrev_b32_e32 v184, 16, v166
	v_and_b32_e32 v185, 0xffff0000, v166
	v_lshlrev_b32_e32 v186, 16, v167
	v_and_b32_e32 v187, 0xffff0000, v167
	v_pk_fma_f32 v[92:93], v[92:93], v[196:197], v[180:181]
	v_pk_fma_f32 v[94:95], v[94:95], v[198:199], v[182:183]
	v_pk_fma_f32 v[88:89], v[88:89], v[200:201], v[184:185]
	v_pk_fma_f32 v[90:91], v[90:91], v[202:203], v[186:187]
	v_cvt_pk_bf16_f32 v91, v90, v91
	v_cvt_pk_bf16_f32 v90, v88, v89
	v_cvt_pk_bf16_f32 v89, v94, v95
	v_cvt_pk_bf16_f32 v88, v92, v93
	v_add_u32_e32 v151, 0x20000, v148
	global_store_dwordx4 v151, v[88:91], s[74:75]
	v_lshlrev_b32_e32 v180, 16, v168
	v_and_b32_e32 v181, 0xffff0000, v168
	v_lshlrev_b32_e32 v182, 16, v169
	v_and_b32_e32 v183, 0xffff0000, v169
	v_lshlrev_b32_e32 v184, 16, v170
	v_and_b32_e32 v185, 0xffff0000, v170
	v_lshlrev_b32_e32 v186, 16, v171
	v_and_b32_e32 v187, 0xffff0000, v171
	v_pk_fma_f32 v[84:85], v[84:85], v[204:205], v[180:181]
	v_pk_fma_f32 v[86:87], v[86:87], v[206:207], v[182:183]
	v_pk_fma_f32 v[80:81], v[80:81], v[208:209], v[184:185]
	v_pk_fma_f32 v[82:83], v[82:83], v[210:211], v[186:187]
	v_cvt_pk_bf16_f32 v83, v82, v83
	v_cvt_pk_bf16_f32 v82, v80, v81
	v_cvt_pk_bf16_f32 v81, v86, v87
	v_cvt_pk_bf16_f32 v80, v84, v85
	v_add_u32_e32 v151, 0x20000, v148
	global_store_dwordx4 v151, v[80:83], s[74:75] offset:256
	v_lshlrev_b32_e32 v180, 16, v172
	v_and_b32_e32 v181, 0xffff0000, v172
	v_lshlrev_b32_e32 v182, 16, v173
	v_and_b32_e32 v183, 0xffff0000, v173
	v_lshlrev_b32_e32 v184, 16, v174
	v_and_b32_e32 v185, 0xffff0000, v174
	v_lshlrev_b32_e32 v186, 16, v175
	v_and_b32_e32 v187, 0xffff0000, v175
	v_pk_fma_f32 v[76:77], v[76:77], v[196:197], v[180:181]
	v_pk_fma_f32 v[78:79], v[78:79], v[198:199], v[182:183]
	v_pk_fma_f32 v[72:73], v[72:73], v[200:201], v[184:185]
	v_pk_fma_f32 v[74:75], v[74:75], v[202:203], v[186:187]
	v_cvt_pk_bf16_f32 v75, v74, v75
	v_cvt_pk_bf16_f32 v74, v72, v73
	v_cvt_pk_bf16_f32 v73, v78, v79
	v_cvt_pk_bf16_f32 v72, v76, v77
	v_add_u32_e32 v151, 0x30000, v148
	global_store_dwordx4 v151, v[72:75], s[74:75]
	v_lshlrev_b32_e32 v180, 16, v176
	v_and_b32_e32 v181, 0xffff0000, v176
	v_lshlrev_b32_e32 v182, 16, v177
	v_and_b32_e32 v183, 0xffff0000, v177
	v_lshlrev_b32_e32 v184, 16, v178
	v_and_b32_e32 v185, 0xffff0000, v178
	v_lshlrev_b32_e32 v186, 16, v179
	v_and_b32_e32 v187, 0xffff0000, v179
	v_pk_fma_f32 v[68:69], v[68:69], v[204:205], v[180:181]
	v_pk_fma_f32 v[70:71], v[70:71], v[206:207], v[182:183]
	v_pk_fma_f32 v[64:65], v[64:65], v[208:209], v[184:185]
	v_pk_fma_f32 v[66:67], v[66:67], v[210:211], v[186:187]
	v_cvt_pk_bf16_f32 v67, v66, v67
	v_cvt_pk_bf16_f32 v66, v64, v65
	v_cvt_pk_bf16_f32 v65, v70, v71
	v_cvt_pk_bf16_f32 v64, v68, v69
	v_add_u32_e32 v151, 0x30000, v148
	global_store_dwordx4 v151, v[64:67], s[74:75] offset:256
	v_add_u32_e32 v151, 0xa0000, v148
	global_load_dwordx4 v[164:167], v151, s[74:75]
	global_load_dwordx4 v[168:171], v151, s[74:75] offset:256
	v_add_u32_e32 v151, 0xb0000, v148
	global_load_dwordx4 v[172:175], v151, s[74:75]
	global_load_dwordx4 v[176:179], v151, s[74:75] offset:256
	s_waitcnt vmcnt(0)
	v_lshlrev_b32_e32 v180, 16, v212
	v_and_b32_e32 v181, 0xffff0000, v212
	v_lshlrev_b32_e32 v182, 16, v213
	v_and_b32_e32 v183, 0xffff0000, v213
	v_lshlrev_b32_e32 v184, 16, v214
	v_and_b32_e32 v185, 0xffff0000, v214
	v_lshlrev_b32_e32 v186, 16, v215
	v_and_b32_e32 v187, 0xffff0000, v215
	v_pk_fma_f32 v[60:61], v[60:61], v[196:197], v[180:181]
	v_pk_fma_f32 v[62:63], v[62:63], v[198:199], v[182:183]
	v_pk_fma_f32 v[56:57], v[56:57], v[200:201], v[184:185]
	v_pk_fma_f32 v[58:59], v[58:59], v[202:203], v[186:187]
	v_cvt_pk_bf16_f32 v59, v58, v59
	v_cvt_pk_bf16_f32 v58, v56, v57
	v_cvt_pk_bf16_f32 v57, v62, v63
	v_cvt_pk_bf16_f32 v56, v60, v61
	v_add_u32_e32 v151, 0x80000, v148
	global_store_dwordx4 v151, v[56:59], s[74:75]
	v_lshlrev_b32_e32 v180, 16, v216
	v_and_b32_e32 v181, 0xffff0000, v216
	v_lshlrev_b32_e32 v182, 16, v217
	v_and_b32_e32 v183, 0xffff0000, v217
	v_lshlrev_b32_e32 v184, 16, v218
	v_and_b32_e32 v185, 0xffff0000, v218
	v_lshlrev_b32_e32 v186, 16, v219
	v_and_b32_e32 v187, 0xffff0000, v219
	v_pk_fma_f32 v[52:53], v[52:53], v[204:205], v[180:181]
	v_pk_fma_f32 v[54:55], v[54:55], v[206:207], v[182:183]
	v_pk_fma_f32 v[48:49], v[48:49], v[208:209], v[184:185]
	v_pk_fma_f32 v[50:51], v[50:51], v[210:211], v[186:187]
	v_cvt_pk_bf16_f32 v51, v50, v51
	v_cvt_pk_bf16_f32 v50, v48, v49
	v_cvt_pk_bf16_f32 v49, v54, v55
	v_cvt_pk_bf16_f32 v48, v52, v53
	v_add_u32_e32 v151, 0x80000, v148
	global_store_dwordx4 v151, v[48:51], s[74:75] offset:256
	v_lshlrev_b32_e32 v180, 16, v220
	v_and_b32_e32 v181, 0xffff0000, v220
	v_lshlrev_b32_e32 v182, 16, v221
	v_and_b32_e32 v183, 0xffff0000, v221
	v_lshlrev_b32_e32 v184, 16, v222
	v_and_b32_e32 v185, 0xffff0000, v222
	v_lshlrev_b32_e32 v186, 16, v223
	v_and_b32_e32 v187, 0xffff0000, v223
	v_pk_fma_f32 v[44:45], v[44:45], v[196:197], v[180:181]
	v_pk_fma_f32 v[46:47], v[46:47], v[198:199], v[182:183]
	v_pk_fma_f32 v[40:41], v[40:41], v[200:201], v[184:185]
	v_pk_fma_f32 v[42:43], v[42:43], v[202:203], v[186:187]
	v_cvt_pk_bf16_f32 v43, v42, v43
	v_cvt_pk_bf16_f32 v42, v40, v41
	v_cvt_pk_bf16_f32 v41, v46, v47
	v_cvt_pk_bf16_f32 v40, v44, v45
	v_add_u32_e32 v151, 0x90000, v148
	global_store_dwordx4 v151, v[40:43], s[74:75]
	v_lshlrev_b32_e32 v180, 16, v224
	v_and_b32_e32 v181, 0xffff0000, v224
	v_lshlrev_b32_e32 v182, 16, v225
	v_and_b32_e32 v183, 0xffff0000, v225
	v_lshlrev_b32_e32 v184, 16, v226
	v_and_b32_e32 v185, 0xffff0000, v226
	v_lshlrev_b32_e32 v186, 16, v227
	v_and_b32_e32 v187, 0xffff0000, v227
	v_pk_fma_f32 v[36:37], v[36:37], v[204:205], v[180:181]
	v_pk_fma_f32 v[38:39], v[38:39], v[206:207], v[182:183]
	v_pk_fma_f32 v[32:33], v[32:33], v[208:209], v[184:185]
	v_pk_fma_f32 v[34:35], v[34:35], v[210:211], v[186:187]
	v_cvt_pk_bf16_f32 v35, v34, v35
	v_cvt_pk_bf16_f32 v34, v32, v33
	v_cvt_pk_bf16_f32 v33, v38, v39
	v_cvt_pk_bf16_f32 v32, v36, v37
	v_add_u32_e32 v151, 0x90000, v148
	global_store_dwordx4 v151, v[32:35], s[74:75] offset:256
	v_lshlrev_b32_e32 v180, 16, v164
	v_and_b32_e32 v181, 0xffff0000, v164
	v_lshlrev_b32_e32 v182, 16, v165
	v_and_b32_e32 v183, 0xffff0000, v165
	v_lshlrev_b32_e32 v184, 16, v166
	v_and_b32_e32 v185, 0xffff0000, v166
	v_lshlrev_b32_e32 v186, 16, v167
	v_and_b32_e32 v187, 0xffff0000, v167
	v_pk_fma_f32 v[28:29], v[28:29], v[196:197], v[180:181]
	v_pk_fma_f32 v[30:31], v[30:31], v[198:199], v[182:183]
	v_pk_fma_f32 v[24:25], v[24:25], v[200:201], v[184:185]
	v_pk_fma_f32 v[26:27], v[26:27], v[202:203], v[186:187]
	v_cvt_pk_bf16_f32 v27, v26, v27
	v_cvt_pk_bf16_f32 v26, v24, v25
	v_cvt_pk_bf16_f32 v25, v30, v31
	v_cvt_pk_bf16_f32 v24, v28, v29
	v_add_u32_e32 v151, 0xa0000, v148
	global_store_dwordx4 v151, v[24:27], s[74:75]
	v_lshlrev_b32_e32 v180, 16, v168
	v_and_b32_e32 v181, 0xffff0000, v168
	v_lshlrev_b32_e32 v182, 16, v169
	v_and_b32_e32 v183, 0xffff0000, v169
	v_lshlrev_b32_e32 v184, 16, v170
	v_and_b32_e32 v185, 0xffff0000, v170
	v_lshlrev_b32_e32 v186, 16, v171
	v_and_b32_e32 v187, 0xffff0000, v171
	v_pk_fma_f32 v[20:21], v[20:21], v[204:205], v[180:181]
	v_pk_fma_f32 v[22:23], v[22:23], v[206:207], v[182:183]
	v_pk_fma_f32 v[16:17], v[16:17], v[208:209], v[184:185]
	v_pk_fma_f32 v[18:19], v[18:19], v[210:211], v[186:187]
	v_cvt_pk_bf16_f32 v19, v18, v19
	v_cvt_pk_bf16_f32 v18, v16, v17
	v_cvt_pk_bf16_f32 v17, v22, v23
	v_cvt_pk_bf16_f32 v16, v20, v21
	v_add_u32_e32 v151, 0xa0000, v148
	global_store_dwordx4 v151, v[16:19], s[74:75] offset:256
	v_lshlrev_b32_e32 v180, 16, v172
	v_and_b32_e32 v181, 0xffff0000, v172
	v_lshlrev_b32_e32 v182, 16, v173
	v_and_b32_e32 v183, 0xffff0000, v173
	v_lshlrev_b32_e32 v184, 16, v174
	v_and_b32_e32 v185, 0xffff0000, v174
	v_lshlrev_b32_e32 v186, 16, v175
	v_and_b32_e32 v187, 0xffff0000, v175
	v_pk_fma_f32 v[12:13], v[12:13], v[196:197], v[180:181]
	v_pk_fma_f32 v[14:15], v[14:15], v[198:199], v[182:183]
	v_pk_fma_f32 v[8:9], v[8:9], v[200:201], v[184:185]
	v_pk_fma_f32 v[10:11], v[10:11], v[202:203], v[186:187]
	v_cvt_pk_bf16_f32 v11, v10, v11
	v_cvt_pk_bf16_f32 v10, v8, v9
	v_cvt_pk_bf16_f32 v9, v14, v15
	v_cvt_pk_bf16_f32 v8, v12, v13
	v_add_u32_e32 v151, 0xb0000, v148
	global_store_dwordx4 v151, v[8:11], s[74:75]
	v_lshlrev_b32_e32 v180, 16, v176
	v_and_b32_e32 v181, 0xffff0000, v176
	v_lshlrev_b32_e32 v182, 16, v177
	v_and_b32_e32 v183, 0xffff0000, v177
	v_lshlrev_b32_e32 v184, 16, v178
	v_and_b32_e32 v185, 0xffff0000, v178
	v_lshlrev_b32_e32 v186, 16, v179
	v_and_b32_e32 v187, 0xffff0000, v179
	v_pk_fma_f32 v[4:5], v[4:5], v[204:205], v[180:181]
	v_pk_fma_f32 v[6:7], v[6:7], v[206:207], v[182:183]
	v_pk_fma_f32 v[0:1], v[0:1], v[208:209], v[184:185]
	v_pk_fma_f32 v[2:3], v[2:3], v[210:211], v[186:187]
	v_cvt_pk_bf16_f32 v3, v2, v3
	v_cvt_pk_bf16_f32 v2, v0, v1
	v_cvt_pk_bf16_f32 v1, v6, v7
	v_cvt_pk_bf16_f32 v0, v4, v5
	v_add_u32_e32 v151, 0xb0000, v148
	global_store_dwordx4 v151, v[0:3], s[74:75] offset:256
.Lepi_bar_mlpout0:
	s_barrier
	s_cmp_lg_u32 s53, 0
	s_cbranch_scc1 .Lepi_g0done_mlpout0
	s_lshl_b32 s15, s46, 8
	s_add_i32 s15, s15, s53
	v_or_b32_e32 v154, s15, v147
	s_add_i32 s17, s15, 0xffffe000
	v_lshl_or_b32 v150, s33, 8, v158
	s_lshr_b32 s17, s17, 12
	v_lshlrev_b32_e32 v148, 12, v154
	s_add_i32 s17, s17, 1
	s_cmp_gt_i32 s15, s58
	s_cselect_b32 s17, s17, 0
	s_mul_i32 s17, s17, s56
	v_lshl_add_u32 v148, v150, 1, v148
	s_add_u32 s20, s8, s17
	s_addc_u32 s21, s9, 0
	v_lshlrev_b32_e32 v149, 2, v150
	s_nop 0
	global_load_dwordx4 v[196:199], v149, s[20:21]
	global_load_dwordx4 v[200:203], v149, s[20:21] offset:16
	global_load_dwordx4 v[204:207], v149, s[20:21] offset:512
	global_load_dwordx4 v[208:211], v149, s[20:21] offset:528
	global_load_dwordx4 v[212:215], v148, s[74:75]
	global_load_dwordx4 v[216:219], v148, s[74:75] offset:256
	v_add_u32_e32 v151, 0x10000, v148
	global_load_dwordx4 v[220:223], v151, s[74:75]
	global_load_dwordx4 v[224:227], v151, s[74:75] offset:256
	v_add_u32_e32 v151, 0x20000, v148
	global_load_dwordx4 v[164:167], v151, s[74:75]
	global_load_dwordx4 v[168:171], v151, s[74:75] offset:256
	v_add_u32_e32 v151, 0x30000, v148
	global_load_dwordx4 v[172:175], v151, s[74:75]
	global_load_dwordx4 v[176:179], v151, s[74:75] offset:256
	s_waitcnt vmcnt(0)
	v_lshlrev_b32_e32 v180, 16, v212
	v_and_b32_e32 v181, 0xffff0000, v212
	v_lshlrev_b32_e32 v182, 16, v213
	v_and_b32_e32 v183, 0xffff0000, v213
	v_lshlrev_b32_e32 v184, 16, v214
	v_and_b32_e32 v185, 0xffff0000, v214
	v_lshlrev_b32_e32 v186, 16, v215
	v_and_b32_e32 v187, 0xffff0000, v215
	v_pk_fma_f32 v[124:125], v[124:125], v[196:197], v[180:181]
	v_pk_fma_f32 v[126:127], v[126:127], v[198:199], v[182:183]
	v_pk_fma_f32 v[120:121], v[120:121], v[200:201], v[184:185]
	v_pk_fma_f32 v[122:123], v[122:123], v[202:203], v[186:187]
	v_cvt_pk_bf16_f32 v123, v122, v123
	v_cvt_pk_bf16_f32 v122, v120, v121
	v_cvt_pk_bf16_f32 v121, v126, v127
	v_cvt_pk_bf16_f32 v120, v124, v125
	global_store_dwordx4 v148, v[120:123], s[74:75]
	v_lshlrev_b32_e32 v180, 16, v216
	v_and_b32_e32 v181, 0xffff0000, v216
	v_lshlrev_b32_e32 v182, 16, v217
	v_and_b32_e32 v183, 0xffff0000, v217
	v_lshlrev_b32_e32 v184, 16, v218
	v_and_b32_e32 v185, 0xffff0000, v218
	v_lshlrev_b32_e32 v186, 16, v219
	v_and_b32_e32 v187, 0xffff0000, v219
	v_pk_fma_f32 v[116:117], v[116:117], v[204:205], v[180:181]
	v_pk_fma_f32 v[118:119], v[118:119], v[206:207], v[182:183]
	v_pk_fma_f32 v[112:113], v[112:113], v[208:209], v[184:185]
	v_pk_fma_f32 v[114:115], v[114:115], v[210:211], v[186:187]
	v_cvt_pk_bf16_f32 v115, v114, v115
	v_cvt_pk_bf16_f32 v114, v112, v113
	v_cvt_pk_bf16_f32 v113, v118, v119
	v_cvt_pk_bf16_f32 v112, v116, v117
	global_store_dwordx4 v148, v[112:115], s[74:75] offset:256
	v_lshlrev_b32_e32 v180, 16, v220
	v_and_b32_e32 v181, 0xffff0000, v220
	v_lshlrev_b32_e32 v182, 16, v221
	v_and_b32_e32 v183, 0xffff0000, v221
	v_lshlrev_b32_e32 v184, 16, v222
	v_and_b32_e32 v185, 0xffff0000, v222
	v_lshlrev_b32_e32 v186, 16, v223
	v_and_b32_e32 v187, 0xffff0000, v223
	v_pk_fma_f32 v[108:109], v[108:109], v[196:197], v[180:181]
	v_pk_fma_f32 v[110:111], v[110:111], v[198:199], v[182:183]
	v_pk_fma_f32 v[104:105], v[104:105], v[200:201], v[184:185]
	v_pk_fma_f32 v[106:107], v[106:107], v[202:203], v[186:187]
	v_cvt_pk_bf16_f32 v107, v106, v107
	v_cvt_pk_bf16_f32 v106, v104, v105
	v_cvt_pk_bf16_f32 v105, v110, v111
	v_cvt_pk_bf16_f32 v104, v108, v109
	v_add_u32_e32 v151, 0x10000, v148
	global_store_dwordx4 v151, v[104:107], s[74:75]
	v_lshlrev_b32_e32 v180, 16, v224
	v_and_b32_e32 v181, 0xffff0000, v224
	v_lshlrev_b32_e32 v182, 16, v225
	v_and_b32_e32 v183, 0xffff0000, v225
	v_lshlrev_b32_e32 v184, 16, v226
	v_and_b32_e32 v185, 0xffff0000, v226
	v_lshlrev_b32_e32 v186, 16, v227
	v_and_b32_e32 v187, 0xffff0000, v227
	v_pk_fma_f32 v[100:101], v[100:101], v[204:205], v[180:181]
	v_pk_fma_f32 v[102:103], v[102:103], v[206:207], v[182:183]
	v_pk_fma_f32 v[96:97], v[96:97], v[208:209], v[184:185]
	v_pk_fma_f32 v[98:99], v[98:99], v[210:211], v[186:187]
	v_cvt_pk_bf16_f32 v99, v98, v99
	v_cvt_pk_bf16_f32 v98, v96, v97
	v_cvt_pk_bf16_f32 v97, v102, v103
	v_cvt_pk_bf16_f32 v96, v100, v101
	v_add_u32_e32 v151, 0x10000, v148
	global_store_dwordx4 v151, v[96:99], s[74:75] offset:256
	v_add_u32_e32 v151, 0x80000, v148
	global_load_dwordx4 v[212:215], v151, s[74:75]
	global_load_dwordx4 v[216:219], v151, s[74:75] offset:256
	v_add_u32_e32 v151, 0x90000, v148
	global_load_dwordx4 v[220:223], v151, s[74:75]
	global_load_dwordx4 v[224:227], v151, s[74:75] offset:256
	v_lshlrev_b32_e32 v180, 16, v164
	v_and_b32_e32 v181, 0xffff0000, v164
	v_lshlrev_b32_e32 v182, 16, v165
	v_and_b32_e32 v183, 0xffff0000, v165
	v_lshlrev_b32_e32 v184, 16, v166
	v_and_b32_e32 v185, 0xffff0000, v166
	v_lshlrev_b32_e32 v186, 16, v167
	v_and_b32_e32 v187, 0xffff0000, v167
	v_pk_fma_f32 v[92:93], v[92:93], v[196:197], v[180:181]
	v_pk_fma_f32 v[94:95], v[94:95], v[198:199], v[182:183]
	v_pk_fma_f32 v[88:89], v[88:89], v[200:201], v[184:185]
	v_pk_fma_f32 v[90:91], v[90:91], v[202:203], v[186:187]
	v_cvt_pk_bf16_f32 v91, v90, v91
	v_cvt_pk_bf16_f32 v90, v88, v89
	v_cvt_pk_bf16_f32 v89, v94, v95
	v_cvt_pk_bf16_f32 v88, v92, v93
	v_add_u32_e32 v151, 0x20000, v148
	global_store_dwordx4 v151, v[88:91], s[74:75]
	v_lshlrev_b32_e32 v180, 16, v168
	v_and_b32_e32 v181, 0xffff0000, v168
	v_lshlrev_b32_e32 v182, 16, v169
	v_and_b32_e32 v183, 0xffff0000, v169
	v_lshlrev_b32_e32 v184, 16, v170
	v_and_b32_e32 v185, 0xffff0000, v170
	v_lshlrev_b32_e32 v186, 16, v171
	v_and_b32_e32 v187, 0xffff0000, v171
	v_pk_fma_f32 v[84:85], v[84:85], v[204:205], v[180:181]
	v_pk_fma_f32 v[86:87], v[86:87], v[206:207], v[182:183]
	v_pk_fma_f32 v[80:81], v[80:81], v[208:209], v[184:185]
	v_pk_fma_f32 v[82:83], v[82:83], v[210:211], v[186:187]
	v_cvt_pk_bf16_f32 v83, v82, v83
	v_cvt_pk_bf16_f32 v82, v80, v81
	v_cvt_pk_bf16_f32 v81, v86, v87
	v_cvt_pk_bf16_f32 v80, v84, v85
	v_add_u32_e32 v151, 0x20000, v148
	global_store_dwordx4 v151, v[80:83], s[74:75] offset:256
	v_lshlrev_b32_e32 v180, 16, v172
	v_and_b32_e32 v181, 0xffff0000, v172
	v_lshlrev_b32_e32 v182, 16, v173
	v_and_b32_e32 v183, 0xffff0000, v173
	v_lshlrev_b32_e32 v184, 16, v174
	v_and_b32_e32 v185, 0xffff0000, v174
	v_lshlrev_b32_e32 v186, 16, v175
	v_and_b32_e32 v187, 0xffff0000, v175
	v_pk_fma_f32 v[76:77], v[76:77], v[196:197], v[180:181]
	v_pk_fma_f32 v[78:79], v[78:79], v[198:199], v[182:183]
	v_pk_fma_f32 v[72:73], v[72:73], v[200:201], v[184:185]
	v_pk_fma_f32 v[74:75], v[74:75], v[202:203], v[186:187]
	v_cvt_pk_bf16_f32 v75, v74, v75
	v_cvt_pk_bf16_f32 v74, v72, v73
	v_cvt_pk_bf16_f32 v73, v78, v79
	v_cvt_pk_bf16_f32 v72, v76, v77
	v_add_u32_e32 v151, 0x30000, v148
	global_store_dwordx4 v151, v[72:75], s[74:75]
	v_lshlrev_b32_e32 v180, 16, v176
	v_and_b32_e32 v181, 0xffff0000, v176
	v_lshlrev_b32_e32 v182, 16, v177
	v_and_b32_e32 v183, 0xffff0000, v177
	v_lshlrev_b32_e32 v184, 16, v178
	v_and_b32_e32 v185, 0xffff0000, v178
	v_lshlrev_b32_e32 v186, 16, v179
	v_and_b32_e32 v187, 0xffff0000, v179
	v_pk_fma_f32 v[68:69], v[68:69], v[204:205], v[180:181]
	v_pk_fma_f32 v[70:71], v[70:71], v[206:207], v[182:183]
	v_pk_fma_f32 v[64:65], v[64:65], v[208:209], v[184:185]
	v_pk_fma_f32 v[66:67], v[66:67], v[210:211], v[186:187]
	v_cvt_pk_bf16_f32 v67, v66, v67
	v_cvt_pk_bf16_f32 v66, v64, v65
	v_cvt_pk_bf16_f32 v65, v70, v71
	v_cvt_pk_bf16_f32 v64, v68, v69
	v_add_u32_e32 v151, 0x30000, v148
	global_store_dwordx4 v151, v[64:67], s[74:75] offset:256
	v_add_u32_e32 v151, 0xa0000, v148
	global_load_dwordx4 v[164:167], v151, s[74:75]
	global_load_dwordx4 v[168:171], v151, s[74:75] offset:256
	v_add_u32_e32 v151, 0xb0000, v148
	global_load_dwordx4 v[172:175], v151, s[74:75]
	global_load_dwordx4 v[176:179], v151, s[74:75] offset:256
	s_waitcnt vmcnt(0)
	v_lshlrev_b32_e32 v180, 16, v212
	v_and_b32_e32 v181, 0xffff0000, v212
	v_lshlrev_b32_e32 v182, 16, v213
	v_and_b32_e32 v183, 0xffff0000, v213
	v_lshlrev_b32_e32 v184, 16, v214
	v_and_b32_e32 v185, 0xffff0000, v214
	v_lshlrev_b32_e32 v186, 16, v215
	v_and_b32_e32 v187, 0xffff0000, v215
	v_pk_fma_f32 v[60:61], v[60:61], v[196:197], v[180:181]
	v_pk_fma_f32 v[62:63], v[62:63], v[198:199], v[182:183]
	v_pk_fma_f32 v[56:57], v[56:57], v[200:201], v[184:185]
	v_pk_fma_f32 v[58:59], v[58:59], v[202:203], v[186:187]
	v_cvt_pk_bf16_f32 v59, v58, v59
	v_cvt_pk_bf16_f32 v58, v56, v57
	v_cvt_pk_bf16_f32 v57, v62, v63
	v_cvt_pk_bf16_f32 v56, v60, v61
	v_add_u32_e32 v151, 0x80000, v148
	global_store_dwordx4 v151, v[56:59], s[74:75]
	v_lshlrev_b32_e32 v180, 16, v216
	v_and_b32_e32 v181, 0xffff0000, v216
	v_lshlrev_b32_e32 v182, 16, v217
	v_and_b32_e32 v183, 0xffff0000, v217
	v_lshlrev_b32_e32 v184, 16, v218
	v_and_b32_e32 v185, 0xffff0000, v218
	v_lshlrev_b32_e32 v186, 16, v219
	v_and_b32_e32 v187, 0xffff0000, v219
	v_pk_fma_f32 v[52:53], v[52:53], v[204:205], v[180:181]
	v_pk_fma_f32 v[54:55], v[54:55], v[206:207], v[182:183]
	v_pk_fma_f32 v[48:49], v[48:49], v[208:209], v[184:185]
	v_pk_fma_f32 v[50:51], v[50:51], v[210:211], v[186:187]
	v_cvt_pk_bf16_f32 v51, v50, v51
	v_cvt_pk_bf16_f32 v50, v48, v49
	v_cvt_pk_bf16_f32 v49, v54, v55
	v_cvt_pk_bf16_f32 v48, v52, v53
	v_add_u32_e32 v151, 0x80000, v148
	global_store_dwordx4 v151, v[48:51], s[74:75] offset:256
	v_lshlrev_b32_e32 v180, 16, v220
	v_and_b32_e32 v181, 0xffff0000, v220
	v_lshlrev_b32_e32 v182, 16, v221
	v_and_b32_e32 v183, 0xffff0000, v221
	v_lshlrev_b32_e32 v184, 16, v222
	v_and_b32_e32 v185, 0xffff0000, v222
	v_lshlrev_b32_e32 v186, 16, v223
	v_and_b32_e32 v187, 0xffff0000, v223
	v_pk_fma_f32 v[44:45], v[44:45], v[196:197], v[180:181]
	v_pk_fma_f32 v[46:47], v[46:47], v[198:199], v[182:183]
	v_pk_fma_f32 v[40:41], v[40:41], v[200:201], v[184:185]
	v_pk_fma_f32 v[42:43], v[42:43], v[202:203], v[186:187]
	v_cvt_pk_bf16_f32 v43, v42, v43
	v_cvt_pk_bf16_f32 v42, v40, v41
	v_cvt_pk_bf16_f32 v41, v46, v47
	v_cvt_pk_bf16_f32 v40, v44, v45
	v_add_u32_e32 v151, 0x90000, v148
	global_store_dwordx4 v151, v[40:43], s[74:75]
	v_lshlrev_b32_e32 v180, 16, v224
	v_and_b32_e32 v181, 0xffff0000, v224
	v_lshlrev_b32_e32 v182, 16, v225
	v_and_b32_e32 v183, 0xffff0000, v225
	v_lshlrev_b32_e32 v184, 16, v226
	v_and_b32_e32 v185, 0xffff0000, v226
	v_lshlrev_b32_e32 v186, 16, v227
	v_and_b32_e32 v187, 0xffff0000, v227
	v_pk_fma_f32 v[36:37], v[36:37], v[204:205], v[180:181]
	v_pk_fma_f32 v[38:39], v[38:39], v[206:207], v[182:183]
	v_pk_fma_f32 v[32:33], v[32:33], v[208:209], v[184:185]
	v_pk_fma_f32 v[34:35], v[34:35], v[210:211], v[186:187]
	v_cvt_pk_bf16_f32 v35, v34, v35
	v_cvt_pk_bf16_f32 v34, v32, v33
	v_cvt_pk_bf16_f32 v33, v38, v39
	v_cvt_pk_bf16_f32 v32, v36, v37
	v_add_u32_e32 v151, 0x90000, v148
	global_store_dwordx4 v151, v[32:35], s[74:75] offset:256
	v_lshlrev_b32_e32 v180, 16, v164
	v_and_b32_e32 v181, 0xffff0000, v164
	v_lshlrev_b32_e32 v182, 16, v165
	v_and_b32_e32 v183, 0xffff0000, v165
	v_lshlrev_b32_e32 v184, 16, v166
	v_and_b32_e32 v185, 0xffff0000, v166
	v_lshlrev_b32_e32 v186, 16, v167
	v_and_b32_e32 v187, 0xffff0000, v167
	v_pk_fma_f32 v[28:29], v[28:29], v[196:197], v[180:181]
	v_pk_fma_f32 v[30:31], v[30:31], v[198:199], v[182:183]
	v_pk_fma_f32 v[24:25], v[24:25], v[200:201], v[184:185]
	v_pk_fma_f32 v[26:27], v[26:27], v[202:203], v[186:187]
	v_cvt_pk_bf16_f32 v27, v26, v27
	v_cvt_pk_bf16_f32 v26, v24, v25
	v_cvt_pk_bf16_f32 v25, v30, v31
	v_cvt_pk_bf16_f32 v24, v28, v29
	v_add_u32_e32 v151, 0xa0000, v148
	global_store_dwordx4 v151, v[24:27], s[74:75]
	v_lshlrev_b32_e32 v180, 16, v168
	v_and_b32_e32 v181, 0xffff0000, v168
	v_lshlrev_b32_e32 v182, 16, v169
	v_and_b32_e32 v183, 0xffff0000, v169
	v_lshlrev_b32_e32 v184, 16, v170
	v_and_b32_e32 v185, 0xffff0000, v170
	v_lshlrev_b32_e32 v186, 16, v171
	v_and_b32_e32 v187, 0xffff0000, v171
	v_pk_fma_f32 v[20:21], v[20:21], v[204:205], v[180:181]
	v_pk_fma_f32 v[22:23], v[22:23], v[206:207], v[182:183]
	v_pk_fma_f32 v[16:17], v[16:17], v[208:209], v[184:185]
	v_pk_fma_f32 v[18:19], v[18:19], v[210:211], v[186:187]
	v_cvt_pk_bf16_f32 v19, v18, v19
	v_cvt_pk_bf16_f32 v18, v16, v17
	v_cvt_pk_bf16_f32 v17, v22, v23
	v_cvt_pk_bf16_f32 v16, v20, v21
	v_add_u32_e32 v151, 0xa0000, v148
	global_store_dwordx4 v151, v[16:19], s[74:75] offset:256
	v_lshlrev_b32_e32 v180, 16, v172
	v_and_b32_e32 v181, 0xffff0000, v172
	v_lshlrev_b32_e32 v182, 16, v173
	v_and_b32_e32 v183, 0xffff0000, v173
	v_lshlrev_b32_e32 v184, 16, v174
	v_and_b32_e32 v185, 0xffff0000, v174
	v_lshlrev_b32_e32 v186, 16, v175
	v_and_b32_e32 v187, 0xffff0000, v175
	v_pk_fma_f32 v[12:13], v[12:13], v[196:197], v[180:181]
	v_pk_fma_f32 v[14:15], v[14:15], v[198:199], v[182:183]
	v_pk_fma_f32 v[8:9], v[8:9], v[200:201], v[184:185]
	v_pk_fma_f32 v[10:11], v[10:11], v[202:203], v[186:187]
	v_cvt_pk_bf16_f32 v11, v10, v11
	v_cvt_pk_bf16_f32 v10, v8, v9
	v_cvt_pk_bf16_f32 v9, v14, v15
	v_cvt_pk_bf16_f32 v8, v12, v13
	v_add_u32_e32 v151, 0xb0000, v148
	global_store_dwordx4 v151, v[8:11], s[74:75]
	v_lshlrev_b32_e32 v180, 16, v176
	v_and_b32_e32 v181, 0xffff0000, v176
	v_lshlrev_b32_e32 v182, 16, v177
	v_and_b32_e32 v183, 0xffff0000, v177
	v_lshlrev_b32_e32 v184, 16, v178
	v_and_b32_e32 v185, 0xffff0000, v178
	v_lshlrev_b32_e32 v186, 16, v179
	v_and_b32_e32 v187, 0xffff0000, v179
	v_pk_fma_f32 v[4:5], v[4:5], v[204:205], v[180:181]
	v_pk_fma_f32 v[6:7], v[6:7], v[206:207], v[182:183]
	v_pk_fma_f32 v[0:1], v[0:1], v[208:209], v[184:185]
	v_pk_fma_f32 v[2:3], v[2:3], v[210:211], v[186:187]
	v_cvt_pk_bf16_f32 v3, v2, v3
	v_cvt_pk_bf16_f32 v2, v0, v1
	v_cvt_pk_bf16_f32 v1, v6, v7
	v_cvt_pk_bf16_f32 v0, v4, v5
	v_add_u32_e32 v151, 0xb0000, v148
	global_store_dwordx4 v151, v[0:3], s[74:75] offset:256

.LBB0_1346:
	ds_read_b128 v[148:151], v158
	ds_read_b128 v[152:155], v158 offset:1024
	ds_read_b128 v[162:165], v158 offset:2048
	ds_read_b128 v[166:169], v158 offset:3072
	s_add_u32 s20, s38, 0xfff80080
	s_addc_u32 s21, s39, -1
	s_cmp_eq_u32 s61, 28
	s_cselect_b32 s21, s17, s21
	s_cselect_b32 s20, s57, s20
	s_cselect_b32 s45, s15, s60
	s_cselect_b32 s44, s58, s59
	v_lshl_add_u64 v[190:191], s[38:39], 0, v[136:137]
	s_add_i32 m0, s37, 0xc000
	ds_read_b128 v[170:173], v159
	ds_read_b128 v[174:177], v159 offset:1024
	ds_read_b128 v[178:181], v159 offset:2048
	ds_read_b128 v[182:185], v159 offset:3072
	ds_read_b128 v[186:189], v159 offset:4096
	ds_read_b128 v[196:199], v159 offset:5120
	ds_read_b128 v[200:203], v159 offset:6144
	ds_read_b128 v[204:207], v159 offset:7168
	global_load_lds_dwordx4 v[190:191], off
	s_add_i32 m0, s37, 0xe000
	v_lshl_add_u64 v[190:191], s[38:39], 0, v[138:139]
	global_load_lds_dwordx4 v[190:191], off
	s_waitcnt lgkmcnt(8)
	s_barrier
	s_waitcnt lgkmcnt(0)
	s_setprio 1
	v_mfma_f32_16x16x32_bf16 v[124:127], v[148:151], v[170:173], v[124:127]
	v_mfma_f32_16x16x32_bf16 v[120:123], v[162:165], v[170:173], v[120:123]
	v_mfma_f32_16x16x32_bf16 v[108:111], v[148:151], v[178:181], v[108:111]
	v_mfma_f32_16x16x32_bf16 v[104:107], v[162:165], v[178:181], v[104:107]
	v_mfma_f32_16x16x32_bf16 v[92:95], v[148:151], v[186:189], v[92:95]
	v_mfma_f32_16x16x32_bf16 v[88:91], v[162:165], v[186:189], v[88:91]
	v_mfma_f32_16x16x32_bf16 v[76:79], v[148:151], v[200:203], v[76:79]
	v_mfma_f32_16x16x32_bf16 v[72:75], v[162:165], v[200:203], v[72:75]
	v_mfma_f32_16x16x32_bf16 v[124:127], v[152:155], v[174:177], v[124:127]
	v_mfma_f32_16x16x32_bf16 v[120:123], v[166:169], v[174:177], v[120:123]
	v_mfma_f32_16x16x32_bf16 v[108:111], v[152:155], v[182:185], v[108:111]
	v_mfma_f32_16x16x32_bf16 v[104:107], v[166:169], v[182:185], v[104:107]
	v_mfma_f32_16x16x32_bf16 v[92:95], v[152:155], v[196:199], v[92:95]
	v_mfma_f32_16x16x32_bf16 v[88:91], v[166:169], v[196:199], v[88:91]
	v_mfma_f32_16x16x32_bf16 v[76:79], v[152:155], v[204:207], v[76:79]
	v_mfma_f32_16x16x32_bf16 v[72:75], v[166:169], v[204:207], v[72:75]
	s_setprio 0
	s_barrier
	s_add_i32 s62, s53, s23
	v_lshl_add_u64 v[190:191], s[44:45], 0, v[132:133]
	s_mov_b32 m0, s62
	ds_read_b128 v[208:211], v160
	ds_read_b128 v[212:215], v160 offset:1024
	ds_read_b128 v[216:219], v160 offset:2048
	ds_read_b128 v[220:223], v160 offset:3072
	global_load_lds_dwordx4 v[190:191], off
	s_add_i32 m0, s62, 0x2000
	v_lshl_add_u64 v[224:225], s[44:45], 0, v[128:129]
	global_load_lds_dwordx4 v[224:225], off
	s_barrier
	s_waitcnt lgkmcnt(0)
	s_setprio 1
	v_mfma_f32_16x16x32_bf16 v[116:119], v[208:211], v[170:173], v[116:119]
	v_mfma_f32_16x16x32_bf16 v[112:115], v[216:219], v[170:173], v[112:115]
	v_mfma_f32_16x16x32_bf16 v[100:103], v[208:211], v[178:181], v[100:103]
	v_mfma_f32_16x16x32_bf16 v[96:99], v[216:219], v[178:181], v[96:99]
	v_mfma_f32_16x16x32_bf16 v[84:87], v[208:211], v[186:189], v[84:87]
	v_mfma_f32_16x16x32_bf16 v[80:83], v[216:219], v[186:189], v[80:83]
	v_mfma_f32_16x16x32_bf16 v[68:71], v[208:211], v[200:203], v[68:71]
	v_mfma_f32_16x16x32_bf16 v[64:67], v[216:219], v[200:203], v[64:67]
	v_mfma_f32_16x16x32_bf16 v[116:119], v[212:215], v[174:177], v[116:119]
	v_mfma_f32_16x16x32_bf16 v[112:115], v[220:223], v[174:177], v[112:115]
	v_mfma_f32_16x16x32_bf16 v[100:103], v[212:215], v[182:185], v[100:103]
	v_mfma_f32_16x16x32_bf16 v[96:99], v[220:223], v[182:185], v[96:99]
	v_mfma_f32_16x16x32_bf16 v[84:87], v[212:215], v[196:199], v[84:87]
	v_mfma_f32_16x16x32_bf16 v[80:83], v[220:223], v[196:199], v[80:83]
	v_mfma_f32_16x16x32_bf16 v[68:71], v[212:215], v[204:207], v[68:71]
	v_mfma_f32_16x16x32_bf16 v[64:67], v[220:223], v[204:207], v[64:67]
	s_setprio 0
	s_mov_b32 m0, s37
	v_lshl_add_u64 v[226:227], s[20:21], 0, v[134:135]
	s_barrier
	ds_read_b128 v[170:173], v159 offset:16384
	ds_read_b128 v[174:177], v159 offset:17408
	ds_read_b128 v[178:181], v159 offset:18432
	ds_read_b128 v[182:185], v159 offset:19456
	ds_read_b128 v[186:189], v159 offset:20480
	ds_read_b128 v[196:199], v159 offset:21504
	ds_read_b128 v[200:203], v159 offset:22528
	ds_read_b128 v[204:207], v159 offset:23552
	global_load_lds_dwordx4 v[226:227], off
	s_mov_b32 m0, s47
	v_lshl_add_u64 v[228:229], s[20:21], 0, v[130:131]
	global_load_lds_dwordx4 v[228:229], off
	s_barrier
	s_waitcnt lgkmcnt(0)
	s_setprio 1
	v_mfma_f32_16x16x32_bf16 v[60:63], v[148:151], v[170:173], v[60:63]
	v_mfma_f32_16x16x32_bf16 v[56:59], v[162:165], v[170:173], v[56:59]
	v_mfma_f32_16x16x32_bf16 v[44:47], v[148:151], v[178:181], v[44:47]
	v_mfma_f32_16x16x32_bf16 v[40:43], v[162:165], v[178:181], v[40:43]
	v_mfma_f32_16x16x32_bf16 v[28:31], v[148:151], v[186:189], v[28:31]
	v_mfma_f32_16x16x32_bf16 v[24:27], v[162:165], v[186:189], v[24:27]
	v_mfma_f32_16x16x32_bf16 v[12:15], v[148:151], v[200:203], v[12:15]
	v_mfma_f32_16x16x32_bf16 v[8:11], v[162:165], v[200:203], v[8:11]
	v_mfma_f32_16x16x32_bf16 v[60:63], v[152:155], v[174:177], v[60:63]
	v_mfma_f32_16x16x32_bf16 v[56:59], v[166:169], v[174:177], v[56:59]
	v_mfma_f32_16x16x32_bf16 v[44:47], v[152:155], v[182:185], v[44:47]
	v_mfma_f32_16x16x32_bf16 v[40:43], v[166:169], v[182:185], v[40:43]
	v_mfma_f32_16x16x32_bf16 v[28:31], v[152:155], v[196:199], v[28:31]
	v_mfma_f32_16x16x32_bf16 v[24:27], v[166:169], v[196:199], v[24:27]
	v_mfma_f32_16x16x32_bf16 v[12:15], v[152:155], v[204:207], v[12:15]
	v_mfma_f32_16x16x32_bf16 v[8:11], v[166:169], v[204:207], v[8:11]
	s_setprio 0
	s_barrier
	s_add_u32 s62, s44, 0x80000
	s_addc_u32 s63, s45, 0
	s_add_i32 s64, s55, s23
	s_mov_b32 m0, s64
	v_lshl_add_u64 v[148:149], s[62:63], 0, v[132:133]
	global_load_lds_dwordx4 v[148:149], off
	s_add_i32 m0, s64, 0x2000
	v_lshl_add_u64 v[148:149], s[62:63], 0, v[128:129]
	global_load_lds_dwordx4 v[148:149], off
	s_waitcnt vmcnt(6)
	s_barrier
	s_setprio 1
	v_mfma_f32_16x16x32_bf16 v[52:55], v[208:211], v[170:173], v[52:55]
	v_mfma_f32_16x16x32_bf16 v[48:51], v[216:219], v[170:173], v[48:51]
	v_mfma_f32_16x16x32_bf16 v[36:39], v[208:211], v[178:181], v[36:39]
	v_mfma_f32_16x16x32_bf16 v[32:35], v[216:219], v[178:181], v[32:35]
	v_mfma_f32_16x16x32_bf16 v[20:23], v[208:211], v[186:189], v[20:23]
	v_mfma_f32_16x16x32_bf16 v[16:19], v[216:219], v[186:189], v[16:19]
	v_mfma_f32_16x16x32_bf16 v[4:7], v[208:211], v[200:203], v[4:7]
	v_mfma_f32_16x16x32_bf16 v[0:3], v[216:219], v[200:203], v[0:3]
	v_mfma_f32_16x16x32_bf16 v[52:55], v[212:215], v[174:177], v[52:55]
	v_mfma_f32_16x16x32_bf16 v[48:51], v[220:223], v[174:177], v[48:51]
	v_mfma_f32_16x16x32_bf16 v[36:39], v[212:215], v[182:185], v[36:39]
	v_mfma_f32_16x16x32_bf16 v[32:35], v[220:223], v[182:185], v[32:35]
	v_mfma_f32_16x16x32_bf16 v[20:23], v[212:215], v[196:199], v[20:23]
	v_mfma_f32_16x16x32_bf16 v[16:19], v[220:223], v[196:199], v[16:19]
	v_mfma_f32_16x16x32_bf16 v[4:7], v[212:215], v[204:207], v[4:7]
	v_mfma_f32_16x16x32_bf16 v[0:3], v[220:223], v[204:207], v[0:3]
	s_setprio 0
	s_add_i32 s62, 0, 0x18000
	v_add_u32_e32 v161, s62, v147
	s_barrier
	ds_read_b128 v[148:151], v161
	ds_read_b128 v[152:155], v161 offset:1024
	ds_read_b128 v[162:165], v161 offset:2048
	ds_read_b128 v[166:169], v161 offset:3072
	s_add_u32 s20, s20, 0x80000
	s_addc_u32 s21, s21, 0
	s_mov_b32 m0, s48
	v_lshl_add_u64 v[208:209], s[20:21], 0, v[134:135]
	ds_read_b128 v[170:173], v159 offset:32768
	ds_read_b128 v[174:177], v159 offset:33792
	ds_read_b128 v[178:181], v159 offset:34816
	ds_read_b128 v[182:185], v159 offset:35840
	ds_read_b128 v[186:189], v159 offset:36864
	ds_read_b128 v[196:199], v159 offset:37888
	ds_read_b128 v[200:203], v159 offset:38912
	ds_read_b128 v[204:207], v159 offset:39936
	global_load_lds_dwordx4 v[208:209], off
	s_mov_b32 m0, s49
	v_lshl_add_u64 v[208:209], s[20:21], 0, v[130:131]
	global_load_lds_dwordx4 v[208:209], off
	s_waitcnt lgkmcnt(8)
	s_barrier
	s_waitcnt lgkmcnt(0)
	s_setprio 1
	v_mfma_f32_16x16x32_bf16 v[124:127], v[148:151], v[170:173], v[124:127]
	v_mfma_f32_16x16x32_bf16 v[120:123], v[162:165], v[170:173], v[120:123]
	v_mfma_f32_16x16x32_bf16 v[108:111], v[148:151], v[178:181], v[108:111]
	v_mfma_f32_16x16x32_bf16 v[104:107], v[162:165], v[178:181], v[104:107]
	v_mfma_f32_16x16x32_bf16 v[92:95], v[148:151], v[186:189], v[92:95]
	v_mfma_f32_16x16x32_bf16 v[88:91], v[162:165], v[186:189], v[88:91]
	v_mfma_f32_16x16x32_bf16 v[76:79], v[148:151], v[200:203], v[76:79]
	v_mfma_f32_16x16x32_bf16 v[72:75], v[162:165], v[200:203], v[72:75]
	v_mfma_f32_16x16x32_bf16 v[124:127], v[152:155], v[174:177], v[124:127]
	v_mfma_f32_16x16x32_bf16 v[120:123], v[166:169], v[174:177], v[120:123]
	v_mfma_f32_16x16x32_bf16 v[108:111], v[152:155], v[182:185], v[108:111]
	v_mfma_f32_16x16x32_bf16 v[104:107], v[166:169], v[182:185], v[104:107]
	v_mfma_f32_16x16x32_bf16 v[92:95], v[152:155], v[196:199], v[92:95]
	v_mfma_f32_16x16x32_bf16 v[88:91], v[166:169], v[196:199], v[88:91]
	v_mfma_f32_16x16x32_bf16 v[76:79], v[152:155], v[204:207], v[76:79]
	v_mfma_f32_16x16x32_bf16 v[72:75], v[166:169], v[204:207], v[72:75]
	s_setprio 0
	s_barrier
	s_add_i32 s63, 0, 0x1c000
	s_add_i32 s20, s62, s23
	v_add_u32_e32 v161, s63, v147
	v_lshl_add_u64 v[190:191], v[190:191], 0, s[10:11]
	s_mov_b32 m0, s20
	ds_read_b128 v[208:211], v161
	ds_read_b128 v[212:215], v161 offset:1024
	ds_read_b128 v[216:219], v161 offset:2048
	ds_read_b128 v[220:223], v161 offset:3072
	global_load_lds_dwordx4 v[190:191], off
	s_add_i32 m0, s20, 0x2000
	v_lshl_add_u64 v[190:191], v[224:225], 0, s[10:11]
	global_load_lds_dwordx4 v[190:191], off
	s_barrier
	s_waitcnt lgkmcnt(0)
	s_setprio 1
	v_mfma_f32_16x16x32_bf16 v[116:119], v[208:211], v[170:173], v[116:119]
	v_mfma_f32_16x16x32_bf16 v[112:115], v[216:219], v[170:173], v[112:115]
	v_mfma_f32_16x16x32_bf16 v[100:103], v[208:211], v[178:181], v[100:103]
	v_mfma_f32_16x16x32_bf16 v[96:99], v[216:219], v[178:181], v[96:99]
	v_mfma_f32_16x16x32_bf16 v[84:87], v[208:211], v[186:189], v[84:87]
	v_mfma_f32_16x16x32_bf16 v[80:83], v[216:219], v[186:189], v[80:83]
	v_mfma_f32_16x16x32_bf16 v[68:71], v[208:211], v[200:203], v[68:71]
	v_mfma_f32_16x16x32_bf16 v[64:67], v[216:219], v[200:203], v[64:67]
	v_mfma_f32_16x16x32_bf16 v[116:119], v[212:215], v[174:177], v[116:119]
	v_mfma_f32_16x16x32_bf16 v[112:115], v[220:223], v[174:177], v[112:115]
	v_mfma_f32_16x16x32_bf16 v[100:103], v[212:215], v[182:185], v[100:103]
	v_mfma_f32_16x16x32_bf16 v[96:99], v[220:223], v[182:185], v[96:99]
	v_mfma_f32_16x16x32_bf16 v[84:87], v[212:215], v[196:199], v[84:87]
	v_mfma_f32_16x16x32_bf16 v[80:83], v[220:223], v[196:199], v[80:83]
	v_mfma_f32_16x16x32_bf16 v[68:71], v[212:215], v[204:207], v[68:71]
	v_mfma_f32_16x16x32_bf16 v[64:67], v[220:223], v[204:207], v[64:67]
	s_setprio 0
	s_mov_b32 m0, s34
	v_lshl_add_u64 v[190:191], v[226:227], 0, s[10:11]
	s_barrier
	ds_read_b128 v[170:173], v159 offset:49152
	ds_read_b128 v[174:177], v159 offset:50176
	ds_read_b128 v[178:181], v159 offset:51200
	ds_read_b128 v[182:185], v159 offset:52224
	ds_read_b128 v[186:189], v159 offset:53248
	ds_read_b128 v[196:199], v159 offset:54272
	ds_read_b128 v[200:203], v159 offset:55296
	ds_read_b128 v[204:207], v159 offset:56320
	global_load_lds_dwordx4 v[190:191], off
	s_mov_b32 m0, s35
	v_lshl_add_u64 v[190:191], v[228:229], 0, s[10:11]
	global_load_lds_dwordx4 v[190:191], off
	s_barrier
	s_waitcnt lgkmcnt(0)
	s_setprio 1
	v_mfma_f32_16x16x32_bf16 v[60:63], v[148:151], v[170:173], v[60:63]
	v_mfma_f32_16x16x32_bf16 v[56:59], v[162:165], v[170:173], v[56:59]
	v_mfma_f32_16x16x32_bf16 v[44:47], v[148:151], v[178:181], v[44:47]
	v_mfma_f32_16x16x32_bf16 v[40:43], v[162:165], v[178:181], v[40:43]
	v_mfma_f32_16x16x32_bf16 v[28:31], v[148:151], v[186:189], v[28:31]
	v_mfma_f32_16x16x32_bf16 v[24:27], v[162:165], v[186:189], v[24:27]
	v_mfma_f32_16x16x32_bf16 v[12:15], v[148:151], v[200:203], v[12:15]
	v_mfma_f32_16x16x32_bf16 v[8:11], v[162:165], v[200:203], v[8:11]
	v_mfma_f32_16x16x32_bf16 v[60:63], v[152:155], v[174:177], v[60:63]
	v_mfma_f32_16x16x32_bf16 v[56:59], v[166:169], v[174:177], v[56:59]
	v_mfma_f32_16x16x32_bf16 v[44:47], v[152:155], v[182:185], v[44:47]
	v_mfma_f32_16x16x32_bf16 v[40:43], v[166:169], v[182:185], v[40:43]
	v_mfma_f32_16x16x32_bf16 v[28:31], v[152:155], v[196:199], v[28:31]
	v_mfma_f32_16x16x32_bf16 v[24:27], v[166:169], v[196:199], v[24:27]
	v_mfma_f32_16x16x32_bf16 v[12:15], v[152:155], v[204:207], v[12:15]
	v_mfma_f32_16x16x32_bf16 v[8:11], v[166:169], v[204:207], v[8:11]
	s_setprio 0
	s_barrier
	s_add_u32 s20, s44, 0x80080
	s_addc_u32 s21, s45, 0
	s_add_i32 s44, s63, s23
	s_mov_b32 m0, s44
	v_lshl_add_u64 v[148:149], s[20:21], 0, v[132:133]
	global_load_lds_dwordx4 v[148:149], off
	s_add_i32 m0, s44, 0x2000
	v_lshl_add_u64 v[148:149], s[20:21], 0, v[128:129]
	global_load_lds_dwordx4 v[148:149], off
	s_waitcnt vmcnt(6)
	s_barrier
	s_setprio 1
	v_mfma_f32_16x16x32_bf16 v[52:55], v[208:211], v[170:173], v[52:55]
	v_mfma_f32_16x16x32_bf16 v[48:51], v[216:219], v[170:173], v[48:51]
	v_mfma_f32_16x16x32_bf16 v[36:39], v[208:211], v[178:181], v[36:39]
	v_mfma_f32_16x16x32_bf16 v[32:35], v[216:219], v[178:181], v[32:35]
	v_mfma_f32_16x16x32_bf16 v[20:23], v[208:211], v[186:189], v[20:23]
	v_mfma_f32_16x16x32_bf16 v[16:19], v[216:219], v[186:189], v[16:19]
	v_mfma_f32_16x16x32_bf16 v[4:7], v[208:211], v[200:203], v[4:7]
	v_mfma_f32_16x16x32_bf16 v[0:3], v[216:219], v[200:203], v[0:3]
	v_mfma_f32_16x16x32_bf16 v[52:55], v[212:215], v[174:177], v[52:55]
	v_mfma_f32_16x16x32_bf16 v[48:51], v[220:223], v[174:177], v[48:51]
	v_mfma_f32_16x16x32_bf16 v[36:39], v[212:215], v[182:185], v[36:39]
	v_mfma_f32_16x16x32_bf16 v[32:35], v[220:223], v[182:185], v[32:35]
	v_mfma_f32_16x16x32_bf16 v[20:23], v[212:215], v[196:199], v[20:23]
	v_mfma_f32_16x16x32_bf16 v[16:19], v[220:223], v[196:199], v[16:19]
	v_mfma_f32_16x16x32_bf16 v[4:7], v[212:215], v[204:207], v[4:7]
	v_mfma_f32_16x16x32_bf16 v[0:3], v[220:223], v[204:207], v[0:3]
	s_setprio 0
	s_add_i32 s61, s61, 2
	s_add_u32 s38, s38, 0x100
	s_addc_u32 s39, s39, 0
	s_add_u32 s59, s59, 0x100
	s_addc_u32 s60, s60, 0
	s_cmp_gt_u32 s61, 29
	s_cbranch_scc1 .Lepi_last_c_out
	s_barrier
	s_branch .LBB0_1346
.Lepi_last_c_out:
	s_cmp_lg_u32 s51, 64
	s_cbranch_scc1 .Lepi_bar_c_out
	s_lshl_b32 s15, s36, 8
	s_add_i32 s15, s15, s51
	v_or_b32_e32 v154, s15, v145
	s_add_i32 s17, s15, 0xffffe000
	v_lshl_or_b32 v150, s33, 8, v157
	s_lshr_b32 s17, s17, 12
	v_lshlrev_b32_e32 v148, 12, v154
	s_add_i32 s17, s17, 1
	s_cmp_gt_i32 s15, s56
	s_cselect_b32 s17, s17, 0
	s_mul_i32 s17, s17, s54
	v_lshl_add_u32 v148, v150, 1, v148
	s_add_u32 s20, s8, s17
	s_addc_u32 s21, s9, 0
	v_lshlrev_b32_e32 v149, 2, v150
	s_nop 0
	global_load_dwordx4 v[196:199], v149, s[20:21]
	global_load_dwordx4 v[200:203], v149, s[20:21] offset:16
	global_load_dwordx4 v[204:207], v149, s[20:21] offset:512
	global_load_dwordx4 v[208:211], v149, s[20:21] offset:528
	global_load_dwordx4 v[212:215], v148, s[74:75]
	global_load_dwordx4 v[216:219], v148, s[74:75] offset:256
	v_add_u32_e32 v151, 0x10000, v148
	global_load_dwordx4 v[220:223], v151, s[74:75]
	global_load_dwordx4 v[224:227], v151, s[74:75] offset:256
	v_add_u32_e32 v151, 0x20000, v148
	global_load_dwordx4 v[164:167], v151, s[74:75]
	global_load_dwordx4 v[168:171], v151, s[74:75] offset:256
	v_add_u32_e32 v151, 0x30000, v148
	global_load_dwordx4 v[172:175], v151, s[74:75]
	global_load_dwordx4 v[176:179], v151, s[74:75] offset:256
	s_waitcnt vmcnt(0)
	v_lshlrev_b32_e32 v180, 16, v212
	v_and_b32_e32 v181, 0xffff0000, v212
	v_lshlrev_b32_e32 v182, 16, v213
	v_and_b32_e32 v183, 0xffff0000, v213
	v_lshlrev_b32_e32 v184, 16, v214
	v_and_b32_e32 v185, 0xffff0000, v214
	v_lshlrev_b32_e32 v186, 16, v215
	v_and_b32_e32 v187, 0xffff0000, v215
	v_pk_fma_f32 v[124:125], v[124:125], v[196:197], v[180:181]
	v_pk_fma_f32 v[126:127], v[126:127], v[198:199], v[182:183]
	v_pk_fma_f32 v[120:121], v[120:121], v[200:201], v[184:185]
	v_pk_fma_f32 v[122:123], v[122:123], v[202:203], v[186:187]
	v_cvt_pk_bf16_f32 v123, v122, v123
	v_cvt_pk_bf16_f32 v122, v120, v121
	v_cvt_pk_bf16_f32 v121, v126, v127
	v_cvt_pk_bf16_f32 v120, v124, v125
	global_store_dwordx4 v148, v[120:123], s[74:75]
	v_lshlrev_b32_e32 v180, 16, v216
	v_and_b32_e32 v181, 0xffff0000, v216
	v_lshlrev_b32_e32 v182, 16, v217
	v_and_b32_e32 v183, 0xffff0000, v217
	v_lshlrev_b32_e32 v184, 16, v218
	v_and_b32_e32 v185, 0xffff0000, v218
	v_lshlrev_b32_e32 v186, 16, v219
	v_and_b32_e32 v187, 0xffff0000, v219
	v_pk_fma_f32 v[116:117], v[116:117], v[204:205], v[180:181]
	v_pk_fma_f32 v[118:119], v[118:119], v[206:207], v[182:183]
	v_pk_fma_f32 v[112:113], v[112:113], v[208:209], v[184:185]
	v_pk_fma_f32 v[114:115], v[114:115], v[210:211], v[186:187]
	v_cvt_pk_bf16_f32 v115, v114, v115
	v_cvt_pk_bf16_f32 v114, v112, v113
	v_cvt_pk_bf16_f32 v113, v118, v119
	v_cvt_pk_bf16_f32 v112, v116, v117
	global_store_dwordx4 v148, v[112:115], s[74:75] offset:256
	v_lshlrev_b32_e32 v180, 16, v220
	v_and_b32_e32 v181, 0xffff0000, v220
	v_lshlrev_b32_e32 v182, 16, v221
	v_and_b32_e32 v183, 0xffff0000, v221
	v_lshlrev_b32_e32 v184, 16, v222
	v_and_b32_e32 v185, 0xffff0000, v222
	v_lshlrev_b32_e32 v186, 16, v223
	v_and_b32_e32 v187, 0xffff0000, v223
	v_pk_fma_f32 v[108:109], v[108:109], v[196:197], v[180:181]
	v_pk_fma_f32 v[110:111], v[110:111], v[198:199], v[182:183]
	v_pk_fma_f32 v[104:105], v[104:105], v[200:201], v[184:185]
	v_pk_fma_f32 v[106:107], v[106:107], v[202:203], v[186:187]
	v_cvt_pk_bf16_f32 v107, v106, v107
	v_cvt_pk_bf16_f32 v106, v104, v105
	v_cvt_pk_bf16_f32 v105, v110, v111
	v_cvt_pk_bf16_f32 v104, v108, v109
	v_add_u32_e32 v151, 0x10000, v148
	global_store_dwordx4 v151, v[104:107], s[74:75]
	v_lshlrev_b32_e32 v180, 16, v224
	v_and_b32_e32 v181, 0xffff0000, v224
	v_lshlrev_b32_e32 v182, 16, v225
	v_and_b32_e32 v183, 0xffff0000, v225
	v_lshlrev_b32_e32 v184, 16, v226
	v_and_b32_e32 v185, 0xffff0000, v226
	v_lshlrev_b32_e32 v186, 16, v227
	v_and_b32_e32 v187, 0xffff0000, v227
	v_pk_fma_f32 v[100:101], v[100:101], v[204:205], v[180:181]
	v_pk_fma_f32 v[102:103], v[102:103], v[206:207], v[182:183]
	v_pk_fma_f32 v[96:97], v[96:97], v[208:209], v[184:185]
	v_pk_fma_f32 v[98:99], v[98:99], v[210:211], v[186:187]
	v_cvt_pk_bf16_f32 v99, v98, v99
	v_cvt_pk_bf16_f32 v98, v96, v97
	v_cvt_pk_bf16_f32 v97, v102, v103
	v_cvt_pk_bf16_f32 v96, v100, v101
	v_add_u32_e32 v151, 0x10000, v148
	global_store_dwordx4 v151, v[96:99], s[74:75] offset:256
	v_add_u32_e32 v151, 0x80000, v148
	global_load_dwordx4 v[212:215], v151, s[74:75]
	global_load_dwordx4 v[216:219], v151, s[74:75] offset:256
	v_add_u32_e32 v151, 0x90000, v148
	global_load_dwordx4 v[220:223], v151, s[74:75]
	global_load_dwordx4 v[224:227], v151, s[74:75] offset:256
	v_lshlrev_b32_e32 v180, 16, v164
	v_and_b32_e32 v181, 0xffff0000, v164
	v_lshlrev_b32_e32 v182, 16, v165
	v_and_b32_e32 v183, 0xffff0000, v165
	v_lshlrev_b32_e32 v184, 16, v166
	v_and_b32_e32 v185, 0xffff0000, v166
	v_lshlrev_b32_e32 v186, 16, v167
	v_and_b32_e32 v187, 0xffff0000, v167
	v_pk_fma_f32 v[92:93], v[92:93], v[196:197], v[180:181]
	v_pk_fma_f32 v[94:95], v[94:95], v[198:199], v[182:183]
	v_pk_fma_f32 v[88:89], v[88:89], v[200:201], v[184:185]
	v_pk_fma_f32 v[90:91], v[90:91], v[202:203], v[186:187]
	v_cvt_pk_bf16_f32 v91, v90, v91
	v_cvt_pk_bf16_f32 v90, v88, v89
	v_cvt_pk_bf16_f32 v89, v94, v95
	v_cvt_pk_bf16_f32 v88, v92, v93
	v_add_u32_e32 v151, 0x20000, v148
	global_store_dwordx4 v151, v[88:91], s[74:75]
	v_lshlrev_b32_e32 v180, 16, v168
	v_and_b32_e32 v181, 0xffff0000, v168
	v_lshlrev_b32_e32 v182, 16, v169
	v_and_b32_e32 v183, 0xffff0000, v169
	v_lshlrev_b32_e32 v184, 16, v170
	v_and_b32_e32 v185, 0xffff0000, v170
	v_lshlrev_b32_e32 v186, 16, v171
	v_and_b32_e32 v187, 0xffff0000, v171
	v_pk_fma_f32 v[84:85], v[84:85], v[204:205], v[180:181]
	v_pk_fma_f32 v[86:87], v[86:87], v[206:207], v[182:183]
	v_pk_fma_f32 v[80:81], v[80:81], v[208:209], v[184:185]
	v_pk_fma_f32 v[82:83], v[82:83], v[210:211], v[186:187]
	v_cvt_pk_bf16_f32 v83, v82, v83
	v_cvt_pk_bf16_f32 v82, v80, v81
	v_cvt_pk_bf16_f32 v81, v86, v87
	v_cvt_pk_bf16_f32 v80, v84, v85
	v_add_u32_e32 v151, 0x20000, v148
	global_store_dwordx4 v151, v[80:83], s[74:75] offset:256
	v_lshlrev_b32_e32 v180, 16, v172
	v_and_b32_e32 v181, 0xffff0000, v172
	v_lshlrev_b32_e32 v182, 16, v173
	v_and_b32_e32 v183, 0xffff0000, v173
	v_lshlrev_b32_e32 v184, 16, v174
	v_and_b32_e32 v185, 0xffff0000, v174
	v_lshlrev_b32_e32 v186, 16, v175
	v_and_b32_e32 v187, 0xffff0000, v175
	v_pk_fma_f32 v[76:77], v[76:77], v[196:197], v[180:181]
	v_pk_fma_f32 v[78:79], v[78:79], v[198:199], v[182:183]
	v_pk_fma_f32 v[72:73], v[72:73], v[200:201], v[184:185]
	v_pk_fma_f32 v[74:75], v[74:75], v[202:203], v[186:187]
	v_cvt_pk_bf16_f32 v75, v74, v75
	v_cvt_pk_bf16_f32 v74, v72, v73
	v_cvt_pk_bf16_f32 v73, v78, v79
	v_cvt_pk_bf16_f32 v72, v76, v77
	v_add_u32_e32 v151, 0x30000, v148
	global_store_dwordx4 v151, v[72:75], s[74:75]
	v_lshlrev_b32_e32 v180, 16, v176
	v_and_b32_e32 v181, 0xffff0000, v176
	v_lshlrev_b32_e32 v182, 16, v177
	v_and_b32_e32 v183, 0xffff0000, v177
	v_lshlrev_b32_e32 v184, 16, v178
	v_and_b32_e32 v185, 0xffff0000, v178
	v_lshlrev_b32_e32 v186, 16, v179
	v_and_b32_e32 v187, 0xffff0000, v179
	v_pk_fma_f32 v[68:69], v[68:69], v[204:205], v[180:181]
	v_pk_fma_f32 v[70:71], v[70:71], v[206:207], v[182:183]
	v_pk_fma_f32 v[64:65], v[64:65], v[208:209], v[184:185]
	v_pk_fma_f32 v[66:67], v[66:67], v[210:211], v[186:187]
	v_cvt_pk_bf16_f32 v67, v66, v67
	v_cvt_pk_bf16_f32 v66, v64, v65
	v_cvt_pk_bf16_f32 v65, v70, v71
	v_cvt_pk_bf16_f32 v64, v68, v69
	v_add_u32_e32 v151, 0x30000, v148
	global_store_dwordx4 v151, v[64:67], s[74:75] offset:256
	v_add_u32_e32 v151, 0xa0000, v148
	global_load_dwordx4 v[164:167], v151, s[74:75]
	global_load_dwordx4 v[168:171], v151, s[74:75] offset:256
	v_add_u32_e32 v151, 0xb0000, v148
	global_load_dwordx4 v[172:175], v151, s[74:75]
	global_load_dwordx4 v[176:179], v151, s[74:75] offset:256
	s_waitcnt vmcnt(0)
	v_lshlrev_b32_e32 v180, 16, v212
	v_and_b32_e32 v181, 0xffff0000, v212
	v_lshlrev_b32_e32 v182, 16, v213
	v_and_b32_e32 v183, 0xffff0000, v213
	v_lshlrev_b32_e32 v184, 16, v214
	v_and_b32_e32 v185, 0xffff0000, v214
	v_lshlrev_b32_e32 v186, 16, v215
	v_and_b32_e32 v187, 0xffff0000, v215
	v_pk_fma_f32 v[60:61], v[60:61], v[196:197], v[180:181]
	v_pk_fma_f32 v[62:63], v[62:63], v[198:199], v[182:183]
	v_pk_fma_f32 v[56:57], v[56:57], v[200:201], v[184:185]
	v_pk_fma_f32 v[58:59], v[58:59], v[202:203], v[186:187]
	v_cvt_pk_bf16_f32 v59, v58, v59
	v_cvt_pk_bf16_f32 v58, v56, v57
	v_cvt_pk_bf16_f32 v57, v62, v63
	v_cvt_pk_bf16_f32 v56, v60, v61
	v_add_u32_e32 v151, 0x80000, v148
	global_store_dwordx4 v151, v[56:59], s[74:75]
	v_lshlrev_b32_e32 v180, 16, v216
	v_and_b32_e32 v181, 0xffff0000, v216
	v_lshlrev_b32_e32 v182, 16, v217
	v_and_b32_e32 v183, 0xffff0000, v217
	v_lshlrev_b32_e32 v184, 16, v218
	v_and_b32_e32 v185, 0xffff0000, v218
	v_lshlrev_b32_e32 v186, 16, v219
	v_and_b32_e32 v187, 0xffff0000, v219
	v_pk_fma_f32 v[52:53], v[52:53], v[204:205], v[180:181]
	v_pk_fma_f32 v[54:55], v[54:55], v[206:207], v[182:183]
	v_pk_fma_f32 v[48:49], v[48:49], v[208:209], v[184:185]
	v_pk_fma_f32 v[50:51], v[50:51], v[210:211], v[186:187]
	v_cvt_pk_bf16_f32 v51, v50, v51
	v_cvt_pk_bf16_f32 v50, v48, v49
	v_cvt_pk_bf16_f32 v49, v54, v55
	v_cvt_pk_bf16_f32 v48, v52, v53
	v_add_u32_e32 v151, 0x80000, v148
	global_store_dwordx4 v151, v[48:51], s[74:75] offset:256
	v_lshlrev_b32_e32 v180, 16, v220
	v_and_b32_e32 v181, 0xffff0000, v220
	v_lshlrev_b32_e32 v182, 16, v221
	v_and_b32_e32 v183, 0xffff0000, v221
	v_lshlrev_b32_e32 v184, 16, v222
	v_and_b32_e32 v185, 0xffff0000, v222
	v_lshlrev_b32_e32 v186, 16, v223
	v_and_b32_e32 v187, 0xffff0000, v223
	v_pk_fma_f32 v[44:45], v[44:45], v[196:197], v[180:181]
	v_pk_fma_f32 v[46:47], v[46:47], v[198:199], v[182:183]
	v_pk_fma_f32 v[40:41], v[40:41], v[200:201], v[184:185]
	v_pk_fma_f32 v[42:43], v[42:43], v[202:203], v[186:187]
	v_cvt_pk_bf16_f32 v43, v42, v43
	v_cvt_pk_bf16_f32 v42, v40, v41
	v_cvt_pk_bf16_f32 v41, v46, v47
	v_cvt_pk_bf16_f32 v40, v44, v45
	v_add_u32_e32 v151, 0x90000, v148
	global_store_dwordx4 v151, v[40:43], s[74:75]
	v_lshlrev_b32_e32 v180, 16, v224
	v_and_b32_e32 v181, 0xffff0000, v224
	v_lshlrev_b32_e32 v182, 16, v225
	v_and_b32_e32 v183, 0xffff0000, v225
	v_lshlrev_b32_e32 v184, 16, v226
	v_and_b32_e32 v185, 0xffff0000, v226
	v_lshlrev_b32_e32 v186, 16, v227
	v_and_b32_e32 v187, 0xffff0000, v227
	v_pk_fma_f32 v[36:37], v[36:37], v[204:205], v[180:181]
	v_pk_fma_f32 v[38:39], v[38:39], v[206:207], v[182:183]
	v_pk_fma_f32 v[32:33], v[32:33], v[208:209], v[184:185]
	v_pk_fma_f32 v[34:35], v[34:35], v[210:211], v[186:187]
	v_cvt_pk_bf16_f32 v35, v34, v35
	v_cvt_pk_bf16_f32 v34, v32, v33
	v_cvt_pk_bf16_f32 v33, v38, v39
	v_cvt_pk_bf16_f32 v32, v36, v37
	v_add_u32_e32 v151, 0x90000, v148
	global_store_dwordx4 v151, v[32:35], s[74:75] offset:256
	v_lshlrev_b32_e32 v180, 16, v164
	v_and_b32_e32 v181, 0xffff0000, v164
	v_lshlrev_b32_e32 v182, 16, v165
	v_and_b32_e32 v183, 0xffff0000, v165
	v_lshlrev_b32_e32 v184, 16, v166
	v_and_b32_e32 v185, 0xffff0000, v166
	v_lshlrev_b32_e32 v186, 16, v167
	v_and_b32_e32 v187, 0xffff0000, v167
	v_pk_fma_f32 v[28:29], v[28:29], v[196:197], v[180:181]
	v_pk_fma_f32 v[30:31], v[30:31], v[198:199], v[182:183]
	v_pk_fma_f32 v[24:25], v[24:25], v[200:201], v[184:185]
	v_pk_fma_f32 v[26:27], v[26:27], v[202:203], v[186:187]
	v_cvt_pk_bf16_f32 v27, v26, v27
	v_cvt_pk_bf16_f32 v26, v24, v25
	v_cvt_pk_bf16_f32 v25, v30, v31
	v_cvt_pk_bf16_f32 v24, v28, v29
	v_add_u32_e32 v151, 0xa0000, v148
	global_store_dwordx4 v151, v[24:27], s[74:75]
	v_lshlrev_b32_e32 v180, 16, v168
	v_and_b32_e32 v181, 0xffff0000, v168
	v_lshlrev_b32_e32 v182, 16, v169
	v_and_b32_e32 v183, 0xffff0000, v169
	v_lshlrev_b32_e32 v184, 16, v170
	v_and_b32_e32 v185, 0xffff0000, v170
	v_lshlrev_b32_e32 v186, 16, v171
	v_and_b32_e32 v187, 0xffff0000, v171
	v_pk_fma_f32 v[20:21], v[20:21], v[204:205], v[180:181]
	v_pk_fma_f32 v[22:23], v[22:23], v[206:207], v[182:183]
	v_pk_fma_f32 v[16:17], v[16:17], v[208:209], v[184:185]
	v_pk_fma_f32 v[18:19], v[18:19], v[210:211], v[186:187]
	v_cvt_pk_bf16_f32 v19, v18, v19
	v_cvt_pk_bf16_f32 v18, v16, v17
	v_cvt_pk_bf16_f32 v17, v22, v23
	v_cvt_pk_bf16_f32 v16, v20, v21
	v_add_u32_e32 v151, 0xa0000, v148
	global_store_dwordx4 v151, v[16:19], s[74:75] offset:256
	v_lshlrev_b32_e32 v180, 16, v172
	v_and_b32_e32 v181, 0xffff0000, v172
	v_lshlrev_b32_e32 v182, 16, v173
	v_and_b32_e32 v183, 0xffff0000, v173
	v_lshlrev_b32_e32 v184, 16, v174
	v_and_b32_e32 v185, 0xffff0000, v174
	v_lshlrev_b32_e32 v186, 16, v175
	v_and_b32_e32 v187, 0xffff0000, v175
	v_pk_fma_f32 v[12:13], v[12:13], v[196:197], v[180:181]
	v_pk_fma_f32 v[14:15], v[14:15], v[198:199], v[182:183]
	v_pk_fma_f32 v[8:9], v[8:9], v[200:201], v[184:185]
	v_pk_fma_f32 v[10:11], v[10:11], v[202:203], v[186:187]
	v_cvt_pk_bf16_f32 v11, v10, v11
	v_cvt_pk_bf16_f32 v10, v8, v9
	v_cvt_pk_bf16_f32 v9, v14, v15
	v_cvt_pk_bf16_f32 v8, v12, v13
	v_add_u32_e32 v151, 0xb0000, v148
	global_store_dwordx4 v151, v[8:11], s[74:75]
	v_lshlrev_b32_e32 v180, 16, v176
	v_and_b32_e32 v181, 0xffff0000, v176
	v_lshlrev_b32_e32 v182, 16, v177
	v_and_b32_e32 v183, 0xffff0000, v177
	v_lshlrev_b32_e32 v184, 16, v178
	v_and_b32_e32 v185, 0xffff0000, v178
	v_lshlrev_b32_e32 v186, 16, v179
	v_and_b32_e32 v187, 0xffff0000, v179
	v_pk_fma_f32 v[4:5], v[4:5], v[204:205], v[180:181]
	v_pk_fma_f32 v[6:7], v[6:7], v[206:207], v[182:183]
	v_pk_fma_f32 v[0:1], v[0:1], v[208:209], v[184:185]
	v_pk_fma_f32 v[2:3], v[2:3], v[210:211], v[186:187]
	v_cvt_pk_bf16_f32 v3, v2, v3
	v_cvt_pk_bf16_f32 v2, v0, v1
	v_cvt_pk_bf16_f32 v1, v6, v7
	v_cvt_pk_bf16_f32 v0, v4, v5
	v_add_u32_e32 v151, 0xb0000, v148
	global_store_dwordx4 v151, v[0:3], s[74:75] offset:256
.Lepi_bar_c_out:
	s_barrier
	s_cmp_lg_u32 s51, 0
	s_cbranch_scc1 .Lepi_g0done_c_out
	s_lshl_b32 s15, s36, 8
	s_add_i32 s15, s15, s51
	v_or_b32_e32 v154, s15, v145
	s_add_i32 s17, s15, 0xffffe000
	v_lshl_or_b32 v150, s33, 8, v157
	s_lshr_b32 s17, s17, 12
	v_lshlrev_b32_e32 v148, 12, v154
	s_add_i32 s17, s17, 1
	s_cmp_gt_i32 s15, s56
	s_cselect_b32 s17, s17, 0
	s_mul_i32 s17, s17, s54
	v_lshl_add_u32 v148, v150, 1, v148
	s_add_u32 s20, s8, s17
	s_addc_u32 s21, s9, 0
	v_lshlrev_b32_e32 v149, 2, v150
	s_nop 0
	global_load_dwordx4 v[196:199], v149, s[20:21]
	global_load_dwordx4 v[200:203], v149, s[20:21] offset:16
	global_load_dwordx4 v[204:207], v149, s[20:21] offset:512
	global_load_dwordx4 v[208:211], v149, s[20:21] offset:528
	global_load_dwordx4 v[212:215], v148, s[74:75]
	global_load_dwordx4 v[216:219], v148, s[74:75] offset:256
	v_add_u32_e32 v151, 0x10000, v148
	global_load_dwordx4 v[220:223], v151, s[74:75]
	global_load_dwordx4 v[224:227], v151, s[74:75] offset:256
	v_add_u32_e32 v151, 0x20000, v148
	global_load_dwordx4 v[164:167], v151, s[74:75]
	global_load_dwordx4 v[168:171], v151, s[74:75] offset:256
	v_add_u32_e32 v151, 0x30000, v148
	global_load_dwordx4 v[172:175], v151, s[74:75]
	global_load_dwordx4 v[176:179], v151, s[74:75] offset:256
	s_waitcnt vmcnt(0)
	v_lshlrev_b32_e32 v180, 16, v212
	v_and_b32_e32 v181, 0xffff0000, v212
	v_lshlrev_b32_e32 v182, 16, v213
	v_and_b32_e32 v183, 0xffff0000, v213
	v_lshlrev_b32_e32 v184, 16, v214
	v_and_b32_e32 v185, 0xffff0000, v214
	v_lshlrev_b32_e32 v186, 16, v215
	v_and_b32_e32 v187, 0xffff0000, v215
	v_pk_fma_f32 v[124:125], v[124:125], v[196:197], v[180:181]
	v_pk_fma_f32 v[126:127], v[126:127], v[198:199], v[182:183]
	v_pk_fma_f32 v[120:121], v[120:121], v[200:201], v[184:185]
	v_pk_fma_f32 v[122:123], v[122:123], v[202:203], v[186:187]
	v_cvt_pk_bf16_f32 v123, v122, v123
	v_cvt_pk_bf16_f32 v122, v120, v121
	v_cvt_pk_bf16_f32 v121, v126, v127
	v_cvt_pk_bf16_f32 v120, v124, v125
	global_store_dwordx4 v148, v[120:123], s[74:75]
	v_lshlrev_b32_e32 v180, 16, v216
	v_and_b32_e32 v181, 0xffff0000, v216
	v_lshlrev_b32_e32 v182, 16, v217
	v_and_b32_e32 v183, 0xffff0000, v217
	v_lshlrev_b32_e32 v184, 16, v218
	v_and_b32_e32 v185, 0xffff0000, v218
	v_lshlrev_b32_e32 v186, 16, v219
	v_and_b32_e32 v187, 0xffff0000, v219
	v_pk_fma_f32 v[116:117], v[116:117], v[204:205], v[180:181]
	v_pk_fma_f32 v[118:119], v[118:119], v[206:207], v[182:183]
	v_pk_fma_f32 v[112:113], v[112:113], v[208:209], v[184:185]
	v_pk_fma_f32 v[114:115], v[114:115], v[210:211], v[186:187]
	v_cvt_pk_bf16_f32 v115, v114, v115
	v_cvt_pk_bf16_f32 v114, v112, v113
	v_cvt_pk_bf16_f32 v113, v118, v119
	v_cvt_pk_bf16_f32 v112, v116, v117
	global_store_dwordx4 v148, v[112:115], s[74:75] offset:256
	v_lshlrev_b32_e32 v180, 16, v220
	v_and_b32_e32 v181, 0xffff0000, v220
	v_lshlrev_b32_e32 v182, 16, v221
	v_and_b32_e32 v183, 0xffff0000, v221
	v_lshlrev_b32_e32 v184, 16, v222
	v_and_b32_e32 v185, 0xffff0000, v222
	v_lshlrev_b32_e32 v186, 16, v223
	v_and_b32_e32 v187, 0xffff0000, v223
	v_pk_fma_f32 v[108:109], v[108:109], v[196:197], v[180:181]
	v_pk_fma_f32 v[110:111], v[110:111], v[198:199], v[182:183]
	v_pk_fma_f32 v[104:105], v[104:105], v[200:201], v[184:185]
	v_pk_fma_f32 v[106:107], v[106:107], v[202:203], v[186:187]
	v_cvt_pk_bf16_f32 v107, v106, v107
	v_cvt_pk_bf16_f32 v106, v104, v105
	v_cvt_pk_bf16_f32 v105, v110, v111
	v_cvt_pk_bf16_f32 v104, v108, v109
	v_add_u32_e32 v151, 0x10000, v148
	global_store_dwordx4 v151, v[104:107], s[74:75]
	v_lshlrev_b32_e32 v180, 16, v224
	v_and_b32_e32 v181, 0xffff0000, v224
	v_lshlrev_b32_e32 v182, 16, v225
	v_and_b32_e32 v183, 0xffff0000, v225
	v_lshlrev_b32_e32 v184, 16, v226
	v_and_b32_e32 v185, 0xffff0000, v226
	v_lshlrev_b32_e32 v186, 16, v227
	v_and_b32_e32 v187, 0xffff0000, v227
	v_pk_fma_f32 v[100:101], v[100:101], v[204:205], v[180:181]
	v_pk_fma_f32 v[102:103], v[102:103], v[206:207], v[182:183]
	v_pk_fma_f32 v[96:97], v[96:97], v[208:209], v[184:185]
	v_pk_fma_f32 v[98:99], v[98:99], v[210:211], v[186:187]
	v_cvt_pk_bf16_f32 v99, v98, v99
	v_cvt_pk_bf16_f32 v98, v96, v97
	v_cvt_pk_bf16_f32 v97, v102, v103
	v_cvt_pk_bf16_f32 v96, v100, v101
	v_add_u32_e32 v151, 0x10000, v148
	global_store_dwordx4 v151, v[96:99], s[74:75] offset:256
	v_add_u32_e32 v151, 0x80000, v148
	global_load_dwordx4 v[212:215], v151, s[74:75]
	global_load_dwordx4 v[216:219], v151, s[74:75] offset:256
	v_add_u32_e32 v151, 0x90000, v148
	global_load_dwordx4 v[220:223], v151, s[74:75]
	global_load_dwordx4 v[224:227], v151, s[74:75] offset:256
	v_lshlrev_b32_e32 v180, 16, v164
	v_and_b32_e32 v181, 0xffff0000, v164
	v_lshlrev_b32_e32 v182, 16, v165
	v_and_b32_e32 v183, 0xffff0000, v165
	v_lshlrev_b32_e32 v184, 16, v166
	v_and_b32_e32 v185, 0xffff0000, v166
	v_lshlrev_b32_e32 v186, 16, v167
	v_and_b32_e32 v187, 0xffff0000, v167
	v_pk_fma_f32 v[92:93], v[92:93], v[196:197], v[180:181]
	v_pk_fma_f32 v[94:95], v[94:95], v[198:199], v[182:183]
	v_pk_fma_f32 v[88:89], v[88:89], v[200:201], v[184:185]
	v_pk_fma_f32 v[90:91], v[90:91], v[202:203], v[186:187]
	v_cvt_pk_bf16_f32 v91, v90, v91
	v_cvt_pk_bf16_f32 v90, v88, v89
	v_cvt_pk_bf16_f32 v89, v94, v95
	v_cvt_pk_bf16_f32 v88, v92, v93
	v_add_u32_e32 v151, 0x20000, v148
	global_store_dwordx4 v151, v[88:91], s[74:75]
	v_lshlrev_b32_e32 v180, 16, v168
	v_and_b32_e32 v181, 0xffff0000, v168
	v_lshlrev_b32_e32 v182, 16, v169
	v_and_b32_e32 v183, 0xffff0000, v169
	v_lshlrev_b32_e32 v184, 16, v170
	v_and_b32_e32 v185, 0xffff0000, v170
	v_lshlrev_b32_e32 v186, 16, v171
	v_and_b32_e32 v187, 0xffff0000, v171
	v_pk_fma_f32 v[84:85], v[84:85], v[204:205], v[180:181]
	v_pk_fma_f32 v[86:87], v[86:87], v[206:207], v[182:183]
	v_pk_fma_f32 v[80:81], v[80:81], v[208:209], v[184:185]
	v_pk_fma_f32 v[82:83], v[82:83], v[210:211], v[186:187]
	v_cvt_pk_bf16_f32 v83, v82, v83
	v_cvt_pk_bf16_f32 v82, v80, v81
	v_cvt_pk_bf16_f32 v81, v86, v87
	v_cvt_pk_bf16_f32 v80, v84, v85
	v_add_u32_e32 v151, 0x20000, v148
	global_store_dwordx4 v151, v[80:83], s[74:75] offset:256
	v_lshlrev_b32_e32 v180, 16, v172
	v_and_b32_e32 v181, 0xffff0000, v172
	v_lshlrev_b32_e32 v182, 16, v173
	v_and_b32_e32 v183, 0xffff0000, v173
	v_lshlrev_b32_e32 v184, 16, v174
	v_and_b32_e32 v185, 0xffff0000, v174
	v_lshlrev_b32_e32 v186, 16, v175
	v_and_b32_e32 v187, 0xffff0000, v175
	v_pk_fma_f32 v[76:77], v[76:77], v[196:197], v[180:181]
	v_pk_fma_f32 v[78:79], v[78:79], v[198:199], v[182:183]
	v_pk_fma_f32 v[72:73], v[72:73], v[200:201], v[184:185]
	v_pk_fma_f32 v[74:75], v[74:75], v[202:203], v[186:187]
	v_cvt_pk_bf16_f32 v75, v74, v75
	v_cvt_pk_bf16_f32 v74, v72, v73
	v_cvt_pk_bf16_f32 v73, v78, v79
	v_cvt_pk_bf16_f32 v72, v76, v77
	v_add_u32_e32 v151, 0x30000, v148
	global_store_dwordx4 v151, v[72:75], s[74:75]
	v_lshlrev_b32_e32 v180, 16, v176
	v_and_b32_e32 v181, 0xffff0000, v176
	v_lshlrev_b32_e32 v182, 16, v177
	v_and_b32_e32 v183, 0xffff0000, v177
	v_lshlrev_b32_e32 v184, 16, v178
	v_and_b32_e32 v185, 0xffff0000, v178
	v_lshlrev_b32_e32 v186, 16, v179
	v_and_b32_e32 v187, 0xffff0000, v179
	v_pk_fma_f32 v[68:69], v[68:69], v[204:205], v[180:181]
	v_pk_fma_f32 v[70:71], v[70:71], v[206:207], v[182:183]
	v_pk_fma_f32 v[64:65], v[64:65], v[208:209], v[184:185]
	v_pk_fma_f32 v[66:67], v[66:67], v[210:211], v[186:187]
	v_cvt_pk_bf16_f32 v67, v66, v67
	v_cvt_pk_bf16_f32 v66, v64, v65
	v_cvt_pk_bf16_f32 v65, v70, v71
	v_cvt_pk_bf16_f32 v64, v68, v69
	v_add_u32_e32 v151, 0x30000, v148
	global_store_dwordx4 v151, v[64:67], s[74:75] offset:256
	v_add_u32_e32 v151, 0xa0000, v148
	global_load_dwordx4 v[164:167], v151, s[74:75]
	global_load_dwordx4 v[168:171], v151, s[74:75] offset:256
	v_add_u32_e32 v151, 0xb0000, v148
	global_load_dwordx4 v[172:175], v151, s[74:75]
	global_load_dwordx4 v[176:179], v151, s[74:75] offset:256
	s_waitcnt vmcnt(0)
	v_lshlrev_b32_e32 v180, 16, v212
	v_and_b32_e32 v181, 0xffff0000, v212
	v_lshlrev_b32_e32 v182, 16, v213
	v_and_b32_e32 v183, 0xffff0000, v213
	v_lshlrev_b32_e32 v184, 16, v214
	v_and_b32_e32 v185, 0xffff0000, v214
	v_lshlrev_b32_e32 v186, 16, v215
	v_and_b32_e32 v187, 0xffff0000, v215
	v_pk_fma_f32 v[60:61], v[60:61], v[196:197], v[180:181]
	v_pk_fma_f32 v[62:63], v[62:63], v[198:199], v[182:183]
	v_pk_fma_f32 v[56:57], v[56:57], v[200:201], v[184:185]
	v_pk_fma_f32 v[58:59], v[58:59], v[202:203], v[186:187]
	v_cvt_pk_bf16_f32 v59, v58, v59
	v_cvt_pk_bf16_f32 v58, v56, v57
	v_cvt_pk_bf16_f32 v57, v62, v63
	v_cvt_pk_bf16_f32 v56, v60, v61
	v_add_u32_e32 v151, 0x80000, v148
	global_store_dwordx4 v151, v[56:59], s[74:75]
	v_lshlrev_b32_e32 v180, 16, v216
	v_and_b32_e32 v181, 0xffff0000, v216
	v_lshlrev_b32_e32 v182, 16, v217
	v_and_b32_e32 v183, 0xffff0000, v217
	v_lshlrev_b32_e32 v184, 16, v218
	v_and_b32_e32 v185, 0xffff0000, v218
	v_lshlrev_b32_e32 v186, 16, v219
	v_and_b32_e32 v187, 0xffff0000, v219
	v_pk_fma_f32 v[52:53], v[52:53], v[204:205], v[180:181]
	v_pk_fma_f32 v[54:55], v[54:55], v[206:207], v[182:183]
	v_pk_fma_f32 v[48:49], v[48:49], v[208:209], v[184:185]
	v_pk_fma_f32 v[50:51], v[50:51], v[210:211], v[186:187]
	v_cvt_pk_bf16_f32 v51, v50, v51
	v_cvt_pk_bf16_f32 v50, v48, v49
	v_cvt_pk_bf16_f32 v49, v54, v55
	v_cvt_pk_bf16_f32 v48, v52, v53
	v_add_u32_e32 v151, 0x80000, v148
	global_store_dwordx4 v151, v[48:51], s[74:75] offset:256
	v_lshlrev_b32_e32 v180, 16, v220
	v_and_b32_e32 v181, 0xffff0000, v220
	v_lshlrev_b32_e32 v182, 16, v221
	v_and_b32_e32 v183, 0xffff0000, v221
	v_lshlrev_b32_e32 v184, 16, v222
	v_and_b32_e32 v185, 0xffff0000, v222
	v_lshlrev_b32_e32 v186, 16, v223
	v_and_b32_e32 v187, 0xffff0000, v223
	v_pk_fma_f32 v[44:45], v[44:45], v[196:197], v[180:181]
	v_pk_fma_f32 v[46:47], v[46:47], v[198:199], v[182:183]
	v_pk_fma_f32 v[40:41], v[40:41], v[200:201], v[184:185]
	v_pk_fma_f32 v[42:43], v[42:43], v[202:203], v[186:187]
	v_cvt_pk_bf16_f32 v43, v42, v43
	v_cvt_pk_bf16_f32 v42, v40, v41
	v_cvt_pk_bf16_f32 v41, v46, v47
	v_cvt_pk_bf16_f32 v40, v44, v45
	v_add_u32_e32 v151, 0x90000, v148
	global_store_dwordx4 v151, v[40:43], s[74:75]
	v_lshlrev_b32_e32 v180, 16, v224
	v_and_b32_e32 v181, 0xffff0000, v224
	v_lshlrev_b32_e32 v182, 16, v225
	v_and_b32_e32 v183, 0xffff0000, v225
	v_lshlrev_b32_e32 v184, 16, v226
	v_and_b32_e32 v185, 0xffff0000, v226
	v_lshlrev_b32_e32 v186, 16, v227
	v_and_b32_e32 v187, 0xffff0000, v227
	v_pk_fma_f32 v[36:37], v[36:37], v[204:205], v[180:181]
	v_pk_fma_f32 v[38:39], v[38:39], v[206:207], v[182:183]
	v_pk_fma_f32 v[32:33], v[32:33], v[208:209], v[184:185]
	v_pk_fma_f32 v[34:35], v[34:35], v[210:211], v[186:187]
	v_cvt_pk_bf16_f32 v35, v34, v35
	v_cvt_pk_bf16_f32 v34, v32, v33
	v_cvt_pk_bf16_f32 v33, v38, v39
	v_cvt_pk_bf16_f32 v32, v36, v37
	v_add_u32_e32 v151, 0x90000, v148
	global_store_dwordx4 v151, v[32:35], s[74:75] offset:256
	v_lshlrev_b32_e32 v180, 16, v164
	v_and_b32_e32 v181, 0xffff0000, v164
	v_lshlrev_b32_e32 v182, 16, v165
	v_and_b32_e32 v183, 0xffff0000, v165
	v_lshlrev_b32_e32 v184, 16, v166
	v_and_b32_e32 v185, 0xffff0000, v166
	v_lshlrev_b32_e32 v186, 16, v167
	v_and_b32_e32 v187, 0xffff0000, v167
	v_pk_fma_f32 v[28:29], v[28:29], v[196:197], v[180:181]
	v_pk_fma_f32 v[30:31], v[30:31], v[198:199], v[182:183]
	v_pk_fma_f32 v[24:25], v[24:25], v[200:201], v[184:185]
	v_pk_fma_f32 v[26:27], v[26:27], v[202:203], v[186:187]
	v_cvt_pk_bf16_f32 v27, v26, v27
	v_cvt_pk_bf16_f32 v26, v24, v25
	v_cvt_pk_bf16_f32 v25, v30, v31
	v_cvt_pk_bf16_f32 v24, v28, v29
	v_add_u32_e32 v151, 0xa0000, v148
	global_store_dwordx4 v151, v[24:27], s[74:75]
	v_lshlrev_b32_e32 v180, 16, v168
	v_and_b32_e32 v181, 0xffff0000, v168
	v_lshlrev_b32_e32 v182, 16, v169
	v_and_b32_e32 v183, 0xffff0000, v169
	v_lshlrev_b32_e32 v184, 16, v170
	v_and_b32_e32 v185, 0xffff0000, v170
	v_lshlrev_b32_e32 v186, 16, v171
	v_and_b32_e32 v187, 0xffff0000, v171
	v_pk_fma_f32 v[20:21], v[20:21], v[204:205], v[180:181]
	v_pk_fma_f32 v[22:23], v[22:23], v[206:207], v[182:183]
	v_pk_fma_f32 v[16:17], v[16:17], v[208:209], v[184:185]
	v_pk_fma_f32 v[18:19], v[18:19], v[210:211], v[186:187]
	v_cvt_pk_bf16_f32 v19, v18, v19
	v_cvt_pk_bf16_f32 v18, v16, v17
	v_cvt_pk_bf16_f32 v17, v22, v23
	v_cvt_pk_bf16_f32 v16, v20, v21
	v_add_u32_e32 v151, 0xa0000, v148
	global_store_dwordx4 v151, v[16:19], s[74:75] offset:256
	v_lshlrev_b32_e32 v180, 16, v172
	v_and_b32_e32 v181, 0xffff0000, v172
	v_lshlrev_b32_e32 v182, 16, v173
	v_and_b32_e32 v183, 0xffff0000, v173
	v_lshlrev_b32_e32 v184, 16, v174
	v_and_b32_e32 v185, 0xffff0000, v174
	v_lshlrev_b32_e32 v186, 16, v175
	v_and_b32_e32 v187, 0xffff0000, v175
	v_pk_fma_f32 v[12:13], v[12:13], v[196:197], v[180:181]
	v_pk_fma_f32 v[14:15], v[14:15], v[198:199], v[182:183]
	v_pk_fma_f32 v[8:9], v[8:9], v[200:201], v[184:185]
	v_pk_fma_f32 v[10:11], v[10:11], v[202:203], v[186:187]
	v_cvt_pk_bf16_f32 v11, v10, v11
	v_cvt_pk_bf16_f32 v10, v8, v9
	v_cvt_pk_bf16_f32 v9, v14, v15
	v_cvt_pk_bf16_f32 v8, v12, v13
	v_add_u32_e32 v151, 0xb0000, v148
	global_store_dwordx4 v151, v[8:11], s[74:75]
	v_lshlrev_b32_e32 v180, 16, v176
	v_and_b32_e32 v181, 0xffff0000, v176
	v_lshlrev_b32_e32 v182, 16, v177
	v_and_b32_e32 v183, 0xffff0000, v177
	v_lshlrev_b32_e32 v184, 16, v178
	v_and_b32_e32 v185, 0xffff0000, v178
	v_lshlrev_b32_e32 v186, 16, v179
	v_and_b32_e32 v187, 0xffff0000, v179
	v_pk_fma_f32 v[4:5], v[4:5], v[204:205], v[180:181]
	v_pk_fma_f32 v[6:7], v[6:7], v[206:207], v[182:183]
	v_pk_fma_f32 v[0:1], v[0:1], v[208:209], v[184:185]
	v_pk_fma_f32 v[2:3], v[2:3], v[210:211], v[186:187]
	v_cvt_pk_bf16_f32 v3, v2, v3
	v_cvt_pk_bf16_f32 v2, v0, v1
	v_cvt_pk_bf16_f32 v1, v6, v7
	v_cvt_pk_bf16_f32 v0, v4, v5
	v_add_u32_e32 v151, 0xb0000, v148
	global_store_dwordx4 v151, v[0:3], s[74:75] offset:256

.LBB0_1402:
	ds_read_b128 v[154:157], v151
	ds_read_b128 v[158:161], v151 offset:1024
	ds_read_b128 v[162:165], v151 offset:2048
	ds_read_b128 v[166:169], v151 offset:3072
	s_add_u32 s20, s26, 0xfff80080
	s_addc_u32 s21, s27, -1
	s_cmp_eq_u32 s52, 28
	s_cselect_b32 s21, s15, s21
	s_cselect_b32 s20, s48, s20
	s_cselect_b32 s37, s11, s51
	s_cselect_b32 s36, s49, s50
	v_lshl_add_u64 v[148:149], s[26:27], 0, v[136:137]
	s_add_i32 m0, s25, 0xc000
	ds_read_b128 v[170:173], v152
	ds_read_b128 v[174:177], v152 offset:1024
	ds_read_b128 v[178:181], v152 offset:2048
	ds_read_b128 v[182:185], v152 offset:3072
	ds_read_b128 v[186:189], v152 offset:4096
	ds_read_b128 v[196:199], v152 offset:5120
	ds_read_b128 v[200:203], v152 offset:6144
	ds_read_b128 v[204:207], v152 offset:7168
	global_load_lds_dwordx4 v[148:149], off
	s_add_i32 m0, s25, 0xe000
	v_lshl_add_u64 v[148:149], s[26:27], 0, v[138:139]
	global_load_lds_dwordx4 v[148:149], off
	s_waitcnt lgkmcnt(8)
	s_barrier
	s_waitcnt lgkmcnt(0)
	s_setprio 1
	v_mfma_f32_16x16x32_bf16 v[124:127], v[154:157], v[170:173], v[124:127]
	v_mfma_f32_16x16x32_bf16 v[120:123], v[162:165], v[170:173], v[120:123]
	v_mfma_f32_16x16x32_bf16 v[108:111], v[154:157], v[178:181], v[108:111]
	v_mfma_f32_16x16x32_bf16 v[104:107], v[162:165], v[178:181], v[104:107]
	v_mfma_f32_16x16x32_bf16 v[92:95], v[154:157], v[186:189], v[92:95]
	v_mfma_f32_16x16x32_bf16 v[88:91], v[162:165], v[186:189], v[88:91]
	v_mfma_f32_16x16x32_bf16 v[76:79], v[154:157], v[200:203], v[76:79]
	v_mfma_f32_16x16x32_bf16 v[72:75], v[162:165], v[200:203], v[72:75]
	v_mfma_f32_16x16x32_bf16 v[124:127], v[158:161], v[174:177], v[124:127]
	v_mfma_f32_16x16x32_bf16 v[120:123], v[166:169], v[174:177], v[120:123]
	v_mfma_f32_16x16x32_bf16 v[108:111], v[158:161], v[182:185], v[108:111]
	v_mfma_f32_16x16x32_bf16 v[104:107], v[166:169], v[182:185], v[104:107]
	v_mfma_f32_16x16x32_bf16 v[92:95], v[158:161], v[196:199], v[92:95]
	v_mfma_f32_16x16x32_bf16 v[88:91], v[166:169], v[196:199], v[88:91]
	v_mfma_f32_16x16x32_bf16 v[76:79], v[158:161], v[204:207], v[76:79]
	v_mfma_f32_16x16x32_bf16 v[72:75], v[166:169], v[204:207], v[72:75]
	s_setprio 0
	s_barrier
	s_add_i32 s53, s46, s23
	v_lshl_add_u64 v[148:149], s[36:37], 0, v[132:133]
	s_mov_b32 m0, s53
	ds_read_b128 v[208:211], v153
	ds_read_b128 v[212:215], v153 offset:1024
	ds_read_b128 v[216:219], v153 offset:2048
	ds_read_b128 v[220:223], v153 offset:3072
	global_load_lds_dwordx4 v[148:149], off
	s_add_i32 m0, s53, 0x2000
	v_lshl_add_u64 v[190:191], s[36:37], 0, v[128:129]
	global_load_lds_dwordx4 v[190:191], off
	s_barrier
	s_waitcnt lgkmcnt(0)
	s_setprio 1
	v_mfma_f32_16x16x32_bf16 v[116:119], v[208:211], v[170:173], v[116:119]
	v_mfma_f32_16x16x32_bf16 v[112:115], v[216:219], v[170:173], v[112:115]
	v_mfma_f32_16x16x32_bf16 v[100:103], v[208:211], v[178:181], v[100:103]
	v_mfma_f32_16x16x32_bf16 v[96:99], v[216:219], v[178:181], v[96:99]
	v_mfma_f32_16x16x32_bf16 v[84:87], v[208:211], v[186:189], v[84:87]
	v_mfma_f32_16x16x32_bf16 v[80:83], v[216:219], v[186:189], v[80:83]
	v_mfma_f32_16x16x32_bf16 v[68:71], v[208:211], v[200:203], v[68:71]
	v_mfma_f32_16x16x32_bf16 v[64:67], v[216:219], v[200:203], v[64:67]
	v_mfma_f32_16x16x32_bf16 v[116:119], v[212:215], v[174:177], v[116:119]
	v_mfma_f32_16x16x32_bf16 v[112:115], v[220:223], v[174:177], v[112:115]
	v_mfma_f32_16x16x32_bf16 v[100:103], v[212:215], v[182:185], v[100:103]
	v_mfma_f32_16x16x32_bf16 v[96:99], v[220:223], v[182:185], v[96:99]
	v_mfma_f32_16x16x32_bf16 v[84:87], v[212:215], v[196:199], v[84:87]
	v_mfma_f32_16x16x32_bf16 v[80:83], v[220:223], v[196:199], v[80:83]
	v_mfma_f32_16x16x32_bf16 v[68:71], v[212:215], v[204:207], v[68:71]
	v_mfma_f32_16x16x32_bf16 v[64:67], v[220:223], v[204:207], v[64:67]
	s_setprio 0
	s_mov_b32 m0, s25
	v_lshl_add_u64 v[224:225], s[20:21], 0, v[134:135]
	s_barrier
	ds_read_b128 v[170:173], v152 offset:16384
	ds_read_b128 v[174:177], v152 offset:17408
	ds_read_b128 v[178:181], v152 offset:18432
	ds_read_b128 v[182:185], v152 offset:19456
	ds_read_b128 v[186:189], v152 offset:20480
	ds_read_b128 v[196:199], v152 offset:21504
	ds_read_b128 v[200:203], v152 offset:22528
	ds_read_b128 v[204:207], v152 offset:23552
	global_load_lds_dwordx4 v[224:225], off
	s_mov_b32 m0, s35
	v_lshl_add_u64 v[226:227], s[20:21], 0, v[130:131]
	global_load_lds_dwordx4 v[226:227], off
	s_barrier
	s_waitcnt lgkmcnt(0)
	s_setprio 1
	v_mfma_f32_16x16x32_bf16 v[60:63], v[154:157], v[170:173], v[60:63]
	v_mfma_f32_16x16x32_bf16 v[56:59], v[162:165], v[170:173], v[56:59]
	v_mfma_f32_16x16x32_bf16 v[44:47], v[154:157], v[178:181], v[44:47]
	v_mfma_f32_16x16x32_bf16 v[40:43], v[162:165], v[178:181], v[40:43]
	v_mfma_f32_16x16x32_bf16 v[28:31], v[154:157], v[186:189], v[28:31]
	v_mfma_f32_16x16x32_bf16 v[24:27], v[162:165], v[186:189], v[24:27]
	v_mfma_f32_16x16x32_bf16 v[12:15], v[154:157], v[200:203], v[12:15]
	v_mfma_f32_16x16x32_bf16 v[8:11], v[162:165], v[200:203], v[8:11]
	v_mfma_f32_16x16x32_bf16 v[60:63], v[158:161], v[174:177], v[60:63]
	v_mfma_f32_16x16x32_bf16 v[56:59], v[166:169], v[174:177], v[56:59]
	v_mfma_f32_16x16x32_bf16 v[44:47], v[158:161], v[182:185], v[44:47]
	v_mfma_f32_16x16x32_bf16 v[40:43], v[166:169], v[182:185], v[40:43]
	v_mfma_f32_16x16x32_bf16 v[28:31], v[158:161], v[196:199], v[28:31]
	v_mfma_f32_16x16x32_bf16 v[24:27], v[166:169], v[196:199], v[24:27]
	v_mfma_f32_16x16x32_bf16 v[12:15], v[158:161], v[204:207], v[12:15]
	v_mfma_f32_16x16x32_bf16 v[8:11], v[166:169], v[204:207], v[8:11]
	s_setprio 0
	s_barrier
	s_add_u32 s54, s36, 0x80000
	s_addc_u32 s55, s37, 0
	s_add_i32 s53, s47, s23
	s_mov_b32 m0, s53
	v_lshl_add_u64 v[154:155], s[54:55], 0, v[132:133]
	global_load_lds_dwordx4 v[154:155], off
	s_add_i32 m0, s53, 0x2000
	v_lshl_add_u64 v[154:155], s[54:55], 0, v[128:129]
	global_load_lds_dwordx4 v[154:155], off
	s_waitcnt vmcnt(6)
	s_barrier
	s_setprio 1
	v_mfma_f32_16x16x32_bf16 v[52:55], v[208:211], v[170:173], v[52:55]
	v_mfma_f32_16x16x32_bf16 v[48:51], v[216:219], v[170:173], v[48:51]
	v_mfma_f32_16x16x32_bf16 v[36:39], v[208:211], v[178:181], v[36:39]
	v_mfma_f32_16x16x32_bf16 v[32:35], v[216:219], v[178:181], v[32:35]
	v_mfma_f32_16x16x32_bf16 v[20:23], v[208:211], v[186:189], v[20:23]
	v_mfma_f32_16x16x32_bf16 v[16:19], v[216:219], v[186:189], v[16:19]
	v_mfma_f32_16x16x32_bf16 v[4:7], v[208:211], v[200:203], v[4:7]
	v_mfma_f32_16x16x32_bf16 v[0:3], v[216:219], v[200:203], v[0:3]
	v_mfma_f32_16x16x32_bf16 v[52:55], v[212:215], v[174:177], v[52:55]
	v_mfma_f32_16x16x32_bf16 v[48:51], v[220:223], v[174:177], v[48:51]
	v_mfma_f32_16x16x32_bf16 v[36:39], v[212:215], v[182:185], v[36:39]
	v_mfma_f32_16x16x32_bf16 v[32:35], v[220:223], v[182:185], v[32:35]
	v_mfma_f32_16x16x32_bf16 v[20:23], v[212:215], v[196:199], v[20:23]
	v_mfma_f32_16x16x32_bf16 v[16:19], v[220:223], v[196:199], v[16:19]
	v_mfma_f32_16x16x32_bf16 v[4:7], v[212:215], v[204:207], v[4:7]
	v_mfma_f32_16x16x32_bf16 v[0:3], v[220:223], v[204:207], v[0:3]
	s_setprio 0
	s_add_i32 s53, 0, 0x18000
	v_add_u32_e32 v166, s53, v147
	s_barrier
	ds_read_b128 v[154:157], v166
	ds_read_b128 v[158:161], v166 offset:1024
	ds_read_b128 v[162:165], v166 offset:2048
	ds_read_b128 v[166:169], v166 offset:3072
	s_add_u32 s20, s20, 0x80000
	s_addc_u32 s21, s21, 0
	s_mov_b32 m0, s38
	v_lshl_add_u64 v[208:209], s[20:21], 0, v[134:135]
	ds_read_b128 v[170:173], v152 offset:32768
	ds_read_b128 v[174:177], v152 offset:33792
	ds_read_b128 v[178:181], v152 offset:34816
	ds_read_b128 v[182:185], v152 offset:35840
	ds_read_b128 v[186:189], v152 offset:36864
	ds_read_b128 v[196:199], v152 offset:37888
	ds_read_b128 v[200:203], v152 offset:38912
	ds_read_b128 v[204:207], v152 offset:39936
	global_load_lds_dwordx4 v[208:209], off
	s_mov_b32 m0, s39
	v_lshl_add_u64 v[208:209], s[20:21], 0, v[130:131]
	global_load_lds_dwordx4 v[208:209], off
	s_waitcnt lgkmcnt(8)
	s_barrier
	s_waitcnt lgkmcnt(0)
	s_setprio 1
	v_mfma_f32_16x16x32_bf16 v[124:127], v[154:157], v[170:173], v[124:127]
	v_mfma_f32_16x16x32_bf16 v[120:123], v[162:165], v[170:173], v[120:123]
	v_mfma_f32_16x16x32_bf16 v[108:111], v[154:157], v[178:181], v[108:111]
	v_mfma_f32_16x16x32_bf16 v[104:107], v[162:165], v[178:181], v[104:107]
	v_mfma_f32_16x16x32_bf16 v[92:95], v[154:157], v[186:189], v[92:95]
	v_mfma_f32_16x16x32_bf16 v[88:91], v[162:165], v[186:189], v[88:91]
	v_mfma_f32_16x16x32_bf16 v[76:79], v[154:157], v[200:203], v[76:79]
	v_mfma_f32_16x16x32_bf16 v[72:75], v[162:165], v[200:203], v[72:75]
	v_mfma_f32_16x16x32_bf16 v[124:127], v[158:161], v[174:177], v[124:127]
	v_mfma_f32_16x16x32_bf16 v[120:123], v[166:169], v[174:177], v[120:123]
	v_mfma_f32_16x16x32_bf16 v[108:111], v[158:161], v[182:185], v[108:111]
	v_mfma_f32_16x16x32_bf16 v[104:107], v[166:169], v[182:185], v[104:107]
	v_mfma_f32_16x16x32_bf16 v[92:95], v[158:161], v[196:199], v[92:95]
	v_mfma_f32_16x16x32_bf16 v[88:91], v[166:169], v[196:199], v[88:91]
	v_mfma_f32_16x16x32_bf16 v[76:79], v[158:161], v[204:207], v[76:79]
	v_mfma_f32_16x16x32_bf16 v[72:75], v[166:169], v[204:207], v[72:75]
	s_setprio 0
	s_barrier
	s_add_i32 s54, 0, 0x1c000
	s_add_i32 s20, s53, s23
	v_add_u32_e32 v193, s54, v147
	v_lshl_add_u64 v[148:149], v[148:149], 0, s[8:9]
	s_mov_b32 m0, s20
	ds_read_b128 v[208:211], v193
	ds_read_b128 v[212:215], v193 offset:1024
	ds_read_b128 v[216:219], v193 offset:2048
	ds_read_b128 v[220:223], v193 offset:3072
	global_load_lds_dwordx4 v[148:149], off
	s_add_i32 m0, s20, 0x2000
	v_lshl_add_u64 v[148:149], v[190:191], 0, s[8:9]
	global_load_lds_dwordx4 v[148:149], off
	s_barrier
	s_waitcnt lgkmcnt(0)
	s_setprio 1
	v_mfma_f32_16x16x32_bf16 v[116:119], v[208:211], v[170:173], v[116:119]
	v_mfma_f32_16x16x32_bf16 v[112:115], v[216:219], v[170:173], v[112:115]
	v_mfma_f32_16x16x32_bf16 v[100:103], v[208:211], v[178:181], v[100:103]
	v_mfma_f32_16x16x32_bf16 v[96:99], v[216:219], v[178:181], v[96:99]
	v_mfma_f32_16x16x32_bf16 v[84:87], v[208:211], v[186:189], v[84:87]
	v_mfma_f32_16x16x32_bf16 v[80:83], v[216:219], v[186:189], v[80:83]
	v_mfma_f32_16x16x32_bf16 v[68:71], v[208:211], v[200:203], v[68:71]
	v_mfma_f32_16x16x32_bf16 v[64:67], v[216:219], v[200:203], v[64:67]
	v_mfma_f32_16x16x32_bf16 v[116:119], v[212:215], v[174:177], v[116:119]
	v_mfma_f32_16x16x32_bf16 v[112:115], v[220:223], v[174:177], v[112:115]
	v_mfma_f32_16x16x32_bf16 v[100:103], v[212:215], v[182:185], v[100:103]
	v_mfma_f32_16x16x32_bf16 v[96:99], v[220:223], v[182:185], v[96:99]
	v_mfma_f32_16x16x32_bf16 v[84:87], v[212:215], v[196:199], v[84:87]
	v_mfma_f32_16x16x32_bf16 v[80:83], v[220:223], v[196:199], v[80:83]
	v_mfma_f32_16x16x32_bf16 v[68:71], v[212:215], v[204:207], v[68:71]
	v_mfma_f32_16x16x32_bf16 v[64:67], v[220:223], v[204:207], v[64:67]
	s_setprio 0
	s_mov_b32 m0, s41
	v_lshl_add_u64 v[148:149], v[224:225], 0, s[8:9]
	s_barrier
	ds_read_b128 v[170:173], v152 offset:49152
	ds_read_b128 v[174:177], v152 offset:50176
	ds_read_b128 v[178:181], v152 offset:51200
	ds_read_b128 v[182:185], v152 offset:52224
	ds_read_b128 v[186:189], v152 offset:53248
	ds_read_b128 v[196:199], v152 offset:54272
	ds_read_b128 v[200:203], v152 offset:55296
	ds_read_b128 v[204:207], v152 offset:56320
	global_load_lds_dwordx4 v[148:149], off
	s_mov_b32 m0, s44
	v_lshl_add_u64 v[148:149], v[226:227], 0, s[8:9]
	global_load_lds_dwordx4 v[148:149], off
	s_barrier
	s_waitcnt lgkmcnt(0)
	s_setprio 1
	v_mfma_f32_16x16x32_bf16 v[60:63], v[154:157], v[170:173], v[60:63]
	v_mfma_f32_16x16x32_bf16 v[56:59], v[162:165], v[170:173], v[56:59]
	v_mfma_f32_16x16x32_bf16 v[44:47], v[154:157], v[178:181], v[44:47]
	v_mfma_f32_16x16x32_bf16 v[40:43], v[162:165], v[178:181], v[40:43]
	v_mfma_f32_16x16x32_bf16 v[28:31], v[154:157], v[186:189], v[28:31]
	v_mfma_f32_16x16x32_bf16 v[24:27], v[162:165], v[186:189], v[24:27]
	v_mfma_f32_16x16x32_bf16 v[12:15], v[154:157], v[200:203], v[12:15]
	v_mfma_f32_16x16x32_bf16 v[8:11], v[162:165], v[200:203], v[8:11]
	v_mfma_f32_16x16x32_bf16 v[60:63], v[158:161], v[174:177], v[60:63]
	v_mfma_f32_16x16x32_bf16 v[56:59], v[166:169], v[174:177], v[56:59]
	v_mfma_f32_16x16x32_bf16 v[44:47], v[158:161], v[182:185], v[44:47]
	v_mfma_f32_16x16x32_bf16 v[40:43], v[166:169], v[182:185], v[40:43]
	v_mfma_f32_16x16x32_bf16 v[28:31], v[158:161], v[196:199], v[28:31]
	v_mfma_f32_16x16x32_bf16 v[24:27], v[166:169], v[196:199], v[24:27]
	v_mfma_f32_16x16x32_bf16 v[12:15], v[158:161], v[204:207], v[12:15]
	v_mfma_f32_16x16x32_bf16 v[8:11], v[166:169], v[204:207], v[8:11]
	s_setprio 0
	s_barrier
	s_add_u32 s20, s36, 0x80080
	s_addc_u32 s21, s37, 0
	s_add_i32 s36, s54, s23
	s_mov_b32 m0, s36
	v_lshl_add_u64 v[148:149], s[20:21], 0, v[132:133]
	global_load_lds_dwordx4 v[148:149], off
	s_add_i32 m0, s36, 0x2000
	v_lshl_add_u64 v[148:149], s[20:21], 0, v[128:129]
	global_load_lds_dwordx4 v[148:149], off
	s_waitcnt vmcnt(6)
	s_barrier
	s_setprio 1
	v_mfma_f32_16x16x32_bf16 v[52:55], v[208:211], v[170:173], v[52:55]
	v_mfma_f32_16x16x32_bf16 v[48:51], v[216:219], v[170:173], v[48:51]
	v_mfma_f32_16x16x32_bf16 v[36:39], v[208:211], v[178:181], v[36:39]
	v_mfma_f32_16x16x32_bf16 v[32:35], v[216:219], v[178:181], v[32:35]
	v_mfma_f32_16x16x32_bf16 v[20:23], v[208:211], v[186:189], v[20:23]
	v_mfma_f32_16x16x32_bf16 v[16:19], v[216:219], v[186:189], v[16:19]
	v_mfma_f32_16x16x32_bf16 v[4:7], v[208:211], v[200:203], v[4:7]
	v_mfma_f32_16x16x32_bf16 v[0:3], v[216:219], v[200:203], v[0:3]
	v_mfma_f32_16x16x32_bf16 v[52:55], v[212:215], v[174:177], v[52:55]
	v_mfma_f32_16x16x32_bf16 v[48:51], v[220:223], v[174:177], v[48:51]
	v_mfma_f32_16x16x32_bf16 v[36:39], v[212:215], v[182:185], v[36:39]
	v_mfma_f32_16x16x32_bf16 v[32:35], v[220:223], v[182:185], v[32:35]
	v_mfma_f32_16x16x32_bf16 v[20:23], v[212:215], v[196:199], v[20:23]
	v_mfma_f32_16x16x32_bf16 v[16:19], v[220:223], v[196:199], v[16:19]
	v_mfma_f32_16x16x32_bf16 v[4:7], v[212:215], v[204:207], v[4:7]
	v_mfma_f32_16x16x32_bf16 v[0:3], v[220:223], v[204:207], v[0:3]
	s_setprio 0
	s_add_i32 s52, s52, 2
	s_add_u32 s26, s26, 0x100
	s_addc_u32 s27, s27, 0
	s_add_u32 s50, s50, 0x100
	s_addc_u32 s51, s51, 0
	s_cmp_gt_u32 s52, 29
	s_cbranch_scc1 .Ldup_last_mlpin1
	s_barrier
	s_branch .LBB0_1402
.Ldup_last_mlpin1:
	s_cmpk_gt_u32 s12, 0xff
	s_cbranch_scc0 .Ldup_bar_mlpin1
	v_lshl_add_u32 v148, s24, 8, v145
	v_max_f32_e32 v124, v124, v124
	v_max_f32_e32 v120, v120, v120
	v_ashrrev_i32_e32 v149, 31, v148
	v_max_f32_e32 v124, 0, v124
	v_max_f32_e32 v120, 0, v120
	v_lshlrev_b64 v[156:157], 14, v[148:149]
	v_mul_f32_e32 v149, v124, v124
	v_mul_f32_e32 v124, v120, v120
	v_max_f32_e32 v120, v125, v125
	v_max_f32_e32 v121, v121, v121
	v_max_f32_e32 v120, 0, v120
	v_max_f32_e32 v121, 0, v121
	v_mul_f32_e32 v158, v120, v120
	v_mul_f32_e32 v159, v121, v121
	v_max_f32_e32 v120, v126, v126
	v_max_f32_e32 v121, v122, v122
	v_max_f32_e32 v120, 0, v120
	v_max_f32_e32 v121, 0, v121
	v_lshl_or_b32 v154, s33, 8, v150
	v_mul_f32_e32 v160, v120, v120
	v_mul_f32_e32 v125, v121, v121
	v_max_f32_e32 v120, v127, v127
	v_max_f32_e32 v121, v123, v123
	v_max_f32_e32 v116, v116, v116
	v_max_f32_e32 v112, v112, v112
	v_max_f32_e32 v117, v117, v117
	v_max_f32_e32 v113, v113, v113
	v_max_f32_e32 v118, v118, v118
	v_max_f32_e32 v114, v114, v114
	v_max_f32_e32 v119, v119, v119
	v_max_f32_e32 v115, v115, v115
	v_ashrrev_i32_e32 v155, 31, v154
	v_max_f32_e32 v120, 0, v120
	v_max_f32_e32 v121, 0, v121
	v_max_f32_e32 v116, 0, v116
	v_max_f32_e32 v112, 0, v112
	v_max_f32_e32 v117, 0, v117
	v_max_f32_e32 v113, 0, v113
	v_max_f32_e32 v118, 0, v118
	v_max_f32_e32 v114, 0, v114
	v_max_f32_e32 v119, 0, v119
	v_max_f32_e32 v115, 0, v115
	v_mul_f32_e32 v161, v120, v120
	v_mul_f32_e32 v162, v121, v121
	v_lshl_add_u64 v[122:123], s[28:29], 0, v[156:157]
	v_lshlrev_b64 v[120:121], 1, v[154:155]
	v_mul_f32_e32 v116, v116, v116
	v_mul_f32_e32 v112, v112, v112
	v_mul_f32_e32 v117, v117, v117
	v_mul_f32_e32 v113, v113, v113
	v_mul_f32_e32 v118, v118, v118
	v_mul_f32_e32 v114, v114, v114
	v_mul_f32_e32 v119, v119, v119
	v_mul_f32_e32 v115, v115, v115
	v_max_f32_e32 v104, v104, v104
	v_lshl_add_u64 v[126:127], v[122:123], 0, v[120:121]
	v_cvt_pk_bf16_f32 v115, v114, v115
	v_cvt_pk_bf16_f32 v114, v112, v113
	v_cvt_pk_bf16_f32 v113, v118, v119
	v_cvt_pk_bf16_f32 v112, v116, v117
	v_max_f32_e32 v104, 0, v104
	global_store_dwordx4 v[126:127], v[112:115], off offset:256
	v_max_f32_e32 v105, v105, v105
	v_max_f32_e32 v105, 0, v105
	v_mul_f32_e32 v115, v104, v104
	v_max_f32_e32 v104, v109, v109
	v_max_f32_e32 v104, 0, v104
	v_mul_f32_e32 v116, v104, v104
	v_mul_f32_e32 v117, v105, v105
	v_max_f32_e32 v104, v110, v110
	v_max_f32_e32 v105, v106, v106
	v_or_b32_e32 v112, 16, v148
	v_max_f32_e32 v104, 0, v104
	v_max_f32_e32 v105, 0, v105
	v_ashrrev_i32_e32 v113, 31, v112
	v_mul_f32_e32 v110, v104, v104
	v_mul_f32_e32 v106, v105, v105
	v_max_f32_e32 v104, v111, v111
	v_max_f32_e32 v105, v107, v107
	v_max_f32_e32 v100, v100, v100
	v_max_f32_e32 v96, v96, v96
	v_max_f32_e32 v101, v101, v101
	v_max_f32_e32 v97, v97, v97
	v_max_f32_e32 v102, v102, v102
	v_max_f32_e32 v98, v98, v98
	v_max_f32_e32 v103, v103, v103
	v_max_f32_e32 v99, v99, v99
	v_lshlrev_b64 v[112:113], 14, v[112:113]
	v_max_f32_e32 v108, v108, v108
	v_max_f32_e32 v104, 0, v104
	v_max_f32_e32 v105, 0, v105
	v_max_f32_e32 v100, 0, v100
	v_max_f32_e32 v96, 0, v96
	v_max_f32_e32 v101, 0, v101
	v_max_f32_e32 v97, 0, v97
	v_max_f32_e32 v102, 0, v102
	v_max_f32_e32 v98, 0, v98
	v_max_f32_e32 v103, 0, v103
	v_max_f32_e32 v99, 0, v99
	v_max_f32_e32 v108, 0, v108
	v_mul_f32_e32 v111, v104, v104
	v_mul_f32_e32 v107, v105, v105
	v_lshl_add_u64 v[104:105], s[28:29], 0, v[112:113]
	v_mul_f32_e32 v100, v100, v100
	v_mul_f32_e32 v96, v96, v96
	v_mul_f32_e32 v101, v101, v101
	v_mul_f32_e32 v97, v97, v97
	v_mul_f32_e32 v102, v102, v102
	v_mul_f32_e32 v98, v98, v98
	v_mul_f32_e32 v103, v103, v103
	v_mul_f32_e32 v99, v99, v99
	v_max_f32_e32 v88, v88, v88
	v_mul_f32_e32 v114, v108, v108
	v_lshl_add_u64 v[108:109], v[104:105], 0, v[120:121]
	v_cvt_pk_bf16_f32 v99, v98, v99
	v_cvt_pk_bf16_f32 v98, v96, v97
	v_cvt_pk_bf16_f32 v97, v102, v103
	v_cvt_pk_bf16_f32 v96, v100, v101
	v_max_f32_e32 v88, 0, v88
	global_store_dwordx4 v[108:109], v[96:99], off offset:256
	v_max_f32_e32 v89, v89, v89
	v_max_f32_e32 v89, 0, v89
	v_mul_f32_e32 v99, v88, v88
	v_max_f32_e32 v88, v93, v93
	v_max_f32_e32 v88, 0, v88
	v_mul_f32_e32 v100, v88, v88
	v_mul_f32_e32 v101, v89, v89
	v_max_f32_e32 v88, v94, v94
	v_max_f32_e32 v89, v90, v90
	v_or_b32_e32 v96, 32, v148
	v_max_f32_e32 v88, 0, v88
	v_max_f32_e32 v89, 0, v89
	v_ashrrev_i32_e32 v97, 31, v96
	v_mul_f32_e32 v94, v88, v88
	v_mul_f32_e32 v90, v89, v89
	v_max_f32_e32 v88, v95, v95
	v_max_f32_e32 v89, v91, v91
	v_max_f32_e32 v84, v84, v84
	v_max_f32_e32 v80, v80, v80
	v_max_f32_e32 v85, v85, v85
	v_max_f32_e32 v81, v81, v81
	v_max_f32_e32 v86, v86, v86
	v_max_f32_e32 v82, v82, v82
	v_max_f32_e32 v87, v87, v87
	v_max_f32_e32 v83, v83, v83
	v_lshlrev_b64 v[96:97], 14, v[96:97]
	v_max_f32_e32 v92, v92, v92
	v_max_f32_e32 v88, 0, v88
	v_max_f32_e32 v89, 0, v89
	v_max_f32_e32 v84, 0, v84
	v_max_f32_e32 v80, 0, v80
	v_max_f32_e32 v85, 0, v85
	v_max_f32_e32 v81, 0, v81
	v_max_f32_e32 v86, 0, v86
	v_max_f32_e32 v82, 0, v82
	v_max_f32_e32 v87, 0, v87
	v_max_f32_e32 v83, 0, v83
	v_max_f32_e32 v92, 0, v92
	v_mul_f32_e32 v95, v88, v88
	v_mul_f32_e32 v91, v89, v89
	v_lshl_add_u64 v[88:89], s[28:29], 0, v[96:97]
	v_mul_f32_e32 v84, v84, v84
	v_mul_f32_e32 v80, v80, v80
	v_mul_f32_e32 v85, v85, v85
	v_mul_f32_e32 v81, v81, v81
	v_mul_f32_e32 v86, v86, v86
	v_mul_f32_e32 v82, v82, v82
	v_mul_f32_e32 v87, v87, v87
	v_mul_f32_e32 v83, v83, v83
	v_max_f32_e32 v72, v72, v72
	v_mul_f32_e32 v98, v92, v92
	v_lshl_add_u64 v[92:93], v[88:89], 0, v[120:121]
	v_cvt_pk_bf16_f32 v83, v82, v83
	v_cvt_pk_bf16_f32 v82, v80, v81
	v_cvt_pk_bf16_f32 v81, v86, v87
	v_cvt_pk_bf16_f32 v80, v84, v85
	v_max_f32_e32 v72, 0, v72
	global_store_dwordx4 v[92:93], v[80:83], off offset:256
	v_max_f32_e32 v73, v73, v73
	v_max_f32_e32 v73, 0, v73
	v_mul_f32_e32 v83, v72, v72
	v_max_f32_e32 v72, v77, v77
	v_max_f32_e32 v72, 0, v72
	v_mul_f32_e32 v84, v72, v72
	v_mul_f32_e32 v85, v73, v73
	v_max_f32_e32 v72, v78, v78
	v_max_f32_e32 v73, v74, v74
	v_or_b32_e32 v80, 48, v148
	v_max_f32_e32 v72, 0, v72
	v_max_f32_e32 v73, 0, v73
	v_ashrrev_i32_e32 v81, 31, v80
	v_mul_f32_e32 v78, v72, v72
	v_mul_f32_e32 v74, v73, v73
	v_max_f32_e32 v72, v79, v79
	v_max_f32_e32 v73, v75, v75
	v_max_f32_e32 v68, v68, v68
	v_max_f32_e32 v64, v64, v64
	v_max_f32_e32 v69, v69, v69
	v_max_f32_e32 v65, v65, v65
	v_max_f32_e32 v70, v70, v70
	v_max_f32_e32 v66, v66, v66
	v_max_f32_e32 v71, v71, v71
	v_max_f32_e32 v67, v67, v67
	v_lshlrev_b64 v[80:81], 14, v[80:81]
	v_max_f32_e32 v76, v76, v76
	v_max_f32_e32 v72, 0, v72
	v_max_f32_e32 v73, 0, v73
	v_max_f32_e32 v68, 0, v68
	v_max_f32_e32 v64, 0, v64
	v_max_f32_e32 v69, 0, v69
	v_max_f32_e32 v65, 0, v65
	v_max_f32_e32 v70, 0, v70
	v_max_f32_e32 v66, 0, v66
	v_max_f32_e32 v71, 0, v71
	v_max_f32_e32 v67, 0, v67
	v_max_f32_e32 v76, 0, v76
	v_mul_f32_e32 v79, v72, v72
	v_mul_f32_e32 v75, v73, v73
	v_lshl_add_u64 v[72:73], s[28:29], 0, v[80:81]
	v_mul_f32_e32 v68, v68, v68
	v_mul_f32_e32 v64, v64, v64
	v_mul_f32_e32 v69, v69, v69
	v_mul_f32_e32 v65, v65, v65
	v_mul_f32_e32 v70, v70, v70
	v_mul_f32_e32 v66, v66, v66
	v_mul_f32_e32 v71, v71, v71
	v_mul_f32_e32 v67, v67, v67
	v_max_f32_e32 v56, v56, v56
	v_mul_f32_e32 v82, v76, v76
	v_lshl_add_u64 v[76:77], v[72:73], 0, v[120:121]
	v_cvt_pk_bf16_f32 v67, v66, v67
	v_cvt_pk_bf16_f32 v66, v64, v65
	v_cvt_pk_bf16_f32 v65, v70, v71
	v_cvt_pk_bf16_f32 v64, v68, v69
	v_max_f32_e32 v56, 0, v56
	global_store_dwordx4 v[76:77], v[64:67], off offset:256
	v_max_f32_e32 v57, v57, v57
	v_max_f32_e32 v57, 0, v57
	v_mul_f32_e32 v67, v56, v56
	v_max_f32_e32 v56, v61, v61
	v_max_f32_e32 v56, 0, v56
	v_mul_f32_e32 v68, v56, v56
	v_mul_f32_e32 v69, v57, v57
	v_max_f32_e32 v56, v62, v62
	v_max_f32_e32 v57, v58, v58
	v_add_u32_e32 v64, 0x80, v148
	v_max_f32_e32 v56, 0, v56
	v_max_f32_e32 v57, 0, v57
	v_ashrrev_i32_e32 v65, 31, v64
	v_mul_f32_e32 v62, v56, v56
	v_mul_f32_e32 v58, v57, v57
	v_max_f32_e32 v56, v63, v63
	v_max_f32_e32 v57, v59, v59
	v_max_f32_e32 v52, v52, v52
	v_max_f32_e32 v48, v48, v48
	v_max_f32_e32 v53, v53, v53
	v_max_f32_e32 v49, v49, v49
	v_max_f32_e32 v54, v54, v54
	v_max_f32_e32 v50, v50, v50
	v_max_f32_e32 v55, v55, v55
	v_max_f32_e32 v51, v51, v51
	v_lshlrev_b64 v[64:65], 14, v[64:65]
	v_max_f32_e32 v60, v60, v60
	v_max_f32_e32 v56, 0, v56
	v_max_f32_e32 v57, 0, v57
	v_max_f32_e32 v52, 0, v52
	v_max_f32_e32 v48, 0, v48
	v_max_f32_e32 v53, 0, v53
	v_max_f32_e32 v49, 0, v49
	v_max_f32_e32 v54, 0, v54
	v_max_f32_e32 v50, 0, v50
	v_max_f32_e32 v55, 0, v55
	v_max_f32_e32 v51, 0, v51
	v_max_f32_e32 v60, 0, v60
	v_mul_f32_e32 v63, v56, v56
	v_mul_f32_e32 v59, v57, v57
	v_lshl_add_u64 v[56:57], s[28:29], 0, v[64:65]
	v_mul_f32_e32 v52, v52, v52
	v_mul_f32_e32 v48, v48, v48
	v_mul_f32_e32 v53, v53, v53
	v_mul_f32_e32 v49, v49, v49
	v_mul_f32_e32 v54, v54, v54
	v_mul_f32_e32 v50, v50, v50
	v_mul_f32_e32 v55, v55, v55
	v_mul_f32_e32 v51, v51, v51
	v_max_f32_e32 v40, v40, v40
	v_mul_f32_e32 v66, v60, v60
	v_lshl_add_u64 v[60:61], v[56:57], 0, v[120:121]
	v_cvt_pk_bf16_f32 v51, v50, v51
	v_cvt_pk_bf16_f32 v50, v48, v49
	v_cvt_pk_bf16_f32 v49, v54, v55
	v_cvt_pk_bf16_f32 v48, v52, v53
	v_max_f32_e32 v40, 0, v40
	global_store_dwordx4 v[60:61], v[48:51], off offset:256
	v_max_f32_e32 v41, v41, v41
	v_max_f32_e32 v41, 0, v41
	v_mul_f32_e32 v51, v40, v40
	v_max_f32_e32 v40, v45, v45
	v_max_f32_e32 v40, 0, v40
	v_mul_f32_e32 v52, v40, v40
	v_mul_f32_e32 v53, v41, v41
	v_max_f32_e32 v40, v46, v46
	v_max_f32_e32 v41, v42, v42
	v_add_u32_e32 v48, 0x90, v148
	v_max_f32_e32 v40, 0, v40
	v_max_f32_e32 v41, 0, v41
	v_ashrrev_i32_e32 v49, 31, v48
	v_mul_f32_e32 v46, v40, v40
	v_mul_f32_e32 v42, v41, v41
	v_max_f32_e32 v40, v47, v47
	v_max_f32_e32 v41, v43, v43
	v_max_f32_e32 v36, v36, v36
	v_max_f32_e32 v32, v32, v32
	v_max_f32_e32 v37, v37, v37
	v_max_f32_e32 v33, v33, v33
	v_max_f32_e32 v38, v38, v38
	v_max_f32_e32 v34, v34, v34
	v_max_f32_e32 v39, v39, v39
	v_max_f32_e32 v35, v35, v35
	v_lshlrev_b64 v[48:49], 14, v[48:49]
	v_max_f32_e32 v44, v44, v44
	v_max_f32_e32 v40, 0, v40
	v_max_f32_e32 v41, 0, v41
	v_max_f32_e32 v36, 0, v36
	v_max_f32_e32 v32, 0, v32
	v_max_f32_e32 v37, 0, v37
	v_max_f32_e32 v33, 0, v33
	v_max_f32_e32 v38, 0, v38
	v_max_f32_e32 v34, 0, v34
	v_max_f32_e32 v39, 0, v39
	v_max_f32_e32 v35, 0, v35
	v_max_f32_e32 v44, 0, v44
	v_mul_f32_e32 v47, v40, v40
	v_mul_f32_e32 v43, v41, v41
	v_lshl_add_u64 v[40:41], s[28:29], 0, v[48:49]
	v_mul_f32_e32 v36, v36, v36
	v_mul_f32_e32 v32, v32, v32
	v_mul_f32_e32 v37, v37, v37
	v_mul_f32_e32 v33, v33, v33
	v_mul_f32_e32 v38, v38, v38
	v_mul_f32_e32 v34, v34, v34
	v_mul_f32_e32 v39, v39, v39
	v_mul_f32_e32 v35, v35, v35
	v_max_f32_e32 v24, v24, v24
	v_mul_f32_e32 v50, v44, v44
	v_lshl_add_u64 v[44:45], v[40:41], 0, v[120:121]
	v_cvt_pk_bf16_f32 v35, v34, v35
	v_cvt_pk_bf16_f32 v34, v32, v33
	v_cvt_pk_bf16_f32 v33, v38, v39
	v_cvt_pk_bf16_f32 v32, v36, v37
	v_max_f32_e32 v24, 0, v24
	global_store_dwordx4 v[44:45], v[32:35], off offset:256
	v_max_f32_e32 v25, v25, v25
	v_max_f32_e32 v25, 0, v25
	v_mul_f32_e32 v35, v24, v24
	v_max_f32_e32 v24, v29, v29
	v_max_f32_e32 v24, 0, v24
	v_mul_f32_e32 v36, v24, v24
	v_mul_f32_e32 v37, v25, v25
	v_max_f32_e32 v24, v30, v30
	v_max_f32_e32 v25, v26, v26
	v_add_u32_e32 v32, 0xa0, v148
	v_max_f32_e32 v24, 0, v24
	v_max_f32_e32 v25, 0, v25
	v_ashrrev_i32_e32 v33, 31, v32
	v_mul_f32_e32 v30, v24, v24
	v_mul_f32_e32 v26, v25, v25
	v_max_f32_e32 v24, v31, v31
	v_max_f32_e32 v25, v27, v27
	v_max_f32_e32 v20, v20, v20
	v_max_f32_e32 v16, v16, v16
	v_max_f32_e32 v21, v21, v21
	v_max_f32_e32 v17, v17, v17
	v_max_f32_e32 v22, v22, v22
	v_max_f32_e32 v18, v18, v18
	v_max_f32_e32 v23, v23, v23
	v_max_f32_e32 v19, v19, v19
	v_lshlrev_b64 v[32:33], 14, v[32:33]
	v_max_f32_e32 v28, v28, v28
	v_max_f32_e32 v24, 0, v24
	v_max_f32_e32 v25, 0, v25
	v_max_f32_e32 v20, 0, v20
	v_max_f32_e32 v16, 0, v16
	v_max_f32_e32 v21, 0, v21
	v_max_f32_e32 v17, 0, v17
	v_max_f32_e32 v22, 0, v22
	v_max_f32_e32 v18, 0, v18
	v_max_f32_e32 v23, 0, v23
	v_max_f32_e32 v19, 0, v19
	v_max_f32_e32 v28, 0, v28
	v_mul_f32_e32 v31, v24, v24
	v_mul_f32_e32 v27, v25, v25
	v_lshl_add_u64 v[24:25], s[28:29], 0, v[32:33]
	v_mul_f32_e32 v20, v20, v20
	v_mul_f32_e32 v16, v16, v16
	v_mul_f32_e32 v21, v21, v21
	v_mul_f32_e32 v17, v17, v17
	v_mul_f32_e32 v22, v22, v22
	v_mul_f32_e32 v18, v18, v18
	v_mul_f32_e32 v23, v23, v23
	v_mul_f32_e32 v19, v19, v19
	v_max_f32_e32 v8, v8, v8
	v_mul_f32_e32 v34, v28, v28
	v_lshl_add_u64 v[28:29], v[24:25], 0, v[120:121]
	v_cvt_pk_bf16_f32 v19, v18, v19
	v_cvt_pk_bf16_f32 v18, v16, v17
	v_cvt_pk_bf16_f32 v17, v22, v23
	v_cvt_pk_bf16_f32 v16, v20, v21
	v_max_f32_e32 v8, 0, v8
	global_store_dwordx4 v[28:29], v[16:19], off offset:256
	v_max_f32_e32 v9, v9, v9
	v_max_f32_e32 v9, 0, v9
	v_mul_f32_e32 v19, v8, v8
	v_max_f32_e32 v8, v13, v13
	v_max_f32_e32 v8, 0, v8
	v_mul_f32_e32 v20, v8, v8
	v_mul_f32_e32 v21, v9, v9
	v_max_f32_e32 v8, v14, v14
	v_max_f32_e32 v9, v10, v10
	v_add_u32_e32 v16, 0xb0, v148
	v_max_f32_e32 v8, 0, v8
	v_max_f32_e32 v9, 0, v9
	v_ashrrev_i32_e32 v17, 31, v16
	v_max_f32_e32 v12, v12, v12
	v_mul_f32_e32 v14, v8, v8
	v_mul_f32_e32 v10, v9, v9
	v_max_f32_e32 v8, v15, v15
	v_max_f32_e32 v9, v11, v11
	v_max_f32_e32 v4, v4, v4
	v_max_f32_e32 v0, v0, v0
	v_max_f32_e32 v5, v5, v5
	v_max_f32_e32 v1, v1, v1
	v_max_f32_e32 v6, v6, v6
	v_max_f32_e32 v2, v2, v2
	v_max_f32_e32 v7, v7, v7
	v_max_f32_e32 v3, v3, v3
	v_lshlrev_b64 v[16:17], 14, v[16:17]
	v_max_f32_e32 v12, 0, v12
	v_max_f32_e32 v8, 0, v8
	v_max_f32_e32 v9, 0, v9
	v_max_f32_e32 v4, 0, v4
	v_max_f32_e32 v0, 0, v0
	v_max_f32_e32 v5, 0, v5
	v_max_f32_e32 v1, 0, v1
	v_max_f32_e32 v6, 0, v6
	v_max_f32_e32 v2, 0, v2
	v_max_f32_e32 v7, 0, v7
	v_max_f32_e32 v3, 0, v3
	v_mul_f32_e32 v18, v12, v12
	v_mul_f32_e32 v15, v8, v8
	v_mul_f32_e32 v11, v9, v9
	v_lshl_add_u64 v[8:9], s[28:29], 0, v[16:17]
	v_mul_f32_e32 v4, v4, v4
	v_mul_f32_e32 v0, v0, v0
	v_mul_f32_e32 v5, v5, v5
	v_mul_f32_e32 v1, v1, v1
	v_mul_f32_e32 v6, v6, v6
	v_mul_f32_e32 v2, v2, v2
	v_mul_f32_e32 v7, v7, v7
	v_mul_f32_e32 v3, v3, v3
	v_cvt_pk_bf16_f32 v125, v125, v162
	v_cvt_pk_bf16_f32 v124, v124, v159
	v_cvt_pk_bf16_f32 v123, v160, v161
	v_cvt_pk_bf16_f32 v122, v149, v158
	v_cvt_pk_bf16_f32 v107, v106, v107
	v_cvt_pk_bf16_f32 v106, v115, v117
	v_cvt_pk_bf16_f32 v105, v110, v111
	v_cvt_pk_bf16_f32 v104, v114, v116
	v_cvt_pk_bf16_f32 v91, v90, v91
	v_cvt_pk_bf16_f32 v90, v99, v101
	v_cvt_pk_bf16_f32 v89, v94, v95
	v_cvt_pk_bf16_f32 v88, v98, v100
	v_cvt_pk_bf16_f32 v75, v74, v75
	v_cvt_pk_bf16_f32 v74, v83, v85
	v_cvt_pk_bf16_f32 v73, v78, v79
	v_cvt_pk_bf16_f32 v72, v82, v84
	v_cvt_pk_bf16_f32 v59, v58, v59
	v_cvt_pk_bf16_f32 v58, v67, v69
	v_cvt_pk_bf16_f32 v57, v62, v63
	v_cvt_pk_bf16_f32 v56, v66, v68
	v_cvt_pk_bf16_f32 v43, v42, v43
	v_cvt_pk_bf16_f32 v42, v51, v53
	v_cvt_pk_bf16_f32 v41, v46, v47
	v_cvt_pk_bf16_f32 v40, v50, v52
	v_cvt_pk_bf16_f32 v27, v26, v27
	v_cvt_pk_bf16_f32 v26, v35, v37
	v_cvt_pk_bf16_f32 v25, v30, v31
	v_cvt_pk_bf16_f32 v24, v34, v36
	v_lshl_add_u64 v[12:13], v[8:9], 0, v[120:121]
	v_cvt_pk_bf16_f32 v11, v10, v11
	v_cvt_pk_bf16_f32 v10, v19, v21
	v_cvt_pk_bf16_f32 v9, v14, v15
	v_cvt_pk_bf16_f32 v8, v18, v20
	v_cvt_pk_bf16_f32 v3, v2, v3
	v_cvt_pk_bf16_f32 v2, v0, v1
	v_cvt_pk_bf16_f32 v1, v6, v7
	v_cvt_pk_bf16_f32 v0, v4, v5
	global_store_dwordx4 v[126:127], v[122:125], off
	global_store_dwordx4 v[108:109], v[104:107], off
	global_store_dwordx4 v[92:93], v[88:91], off
	global_store_dwordx4 v[76:77], v[72:75], off
	global_store_dwordx4 v[60:61], v[56:59], off
	global_store_dwordx4 v[44:45], v[40:43], off
	global_store_dwordx4 v[28:29], v[24:27], off
	global_store_dwordx4 v[12:13], v[8:11], off
	global_store_dwordx4 v[12:13], v[0:3], off offset:256
.Ldup_bar_mlpin1:
	s_barrier
	s_cmpk_gt_u32 s12, 0xff
	s_cbranch_scc1 .Ldup_done_mlpin1
	v_lshl_add_u32 v148, s24, 8, v145
	v_max_f32_e32 v124, v124, v124
	v_max_f32_e32 v120, v120, v120
	v_ashrrev_i32_e32 v149, 31, v148
	v_max_f32_e32 v124, 0, v124
	v_max_f32_e32 v120, 0, v120
	v_lshlrev_b64 v[156:157], 14, v[148:149]
	v_mul_f32_e32 v149, v124, v124
	v_mul_f32_e32 v124, v120, v120
	v_max_f32_e32 v120, v125, v125
	v_max_f32_e32 v121, v121, v121
	v_max_f32_e32 v120, 0, v120
	v_max_f32_e32 v121, 0, v121
	v_mul_f32_e32 v158, v120, v120
	v_mul_f32_e32 v159, v121, v121
	v_max_f32_e32 v120, v126, v126
	v_max_f32_e32 v121, v122, v122
	v_max_f32_e32 v120, 0, v120
	v_max_f32_e32 v121, 0, v121
	v_lshl_or_b32 v154, s33, 8, v150
	v_mul_f32_e32 v160, v120, v120
	v_mul_f32_e32 v125, v121, v121
	v_max_f32_e32 v120, v127, v127
	v_max_f32_e32 v121, v123, v123
	v_max_f32_e32 v116, v116, v116
	v_max_f32_e32 v112, v112, v112
	v_max_f32_e32 v117, v117, v117
	v_max_f32_e32 v113, v113, v113
	v_max_f32_e32 v118, v118, v118
	v_max_f32_e32 v114, v114, v114
	v_max_f32_e32 v119, v119, v119
	v_max_f32_e32 v115, v115, v115
	v_ashrrev_i32_e32 v155, 31, v154
	v_max_f32_e32 v120, 0, v120
	v_max_f32_e32 v121, 0, v121
	v_max_f32_e32 v116, 0, v116
	v_max_f32_e32 v112, 0, v112
	v_max_f32_e32 v117, 0, v117
	v_max_f32_e32 v113, 0, v113
	v_max_f32_e32 v118, 0, v118
	v_max_f32_e32 v114, 0, v114
	v_max_f32_e32 v119, 0, v119
	v_max_f32_e32 v115, 0, v115
	v_mul_f32_e32 v161, v120, v120
	v_mul_f32_e32 v162, v121, v121
	v_lshl_add_u64 v[122:123], s[28:29], 0, v[156:157]
	v_lshlrev_b64 v[120:121], 1, v[154:155]
	v_mul_f32_e32 v116, v116, v116
	v_mul_f32_e32 v112, v112, v112
	v_mul_f32_e32 v117, v117, v117
	v_mul_f32_e32 v113, v113, v113
	v_mul_f32_e32 v118, v118, v118
	v_mul_f32_e32 v114, v114, v114
	v_mul_f32_e32 v119, v119, v119
	v_mul_f32_e32 v115, v115, v115
	v_max_f32_e32 v104, v104, v104
	v_lshl_add_u64 v[126:127], v[122:123], 0, v[120:121]
	v_cvt_pk_bf16_f32 v115, v114, v115
	v_cvt_pk_bf16_f32 v114, v112, v113
	v_cvt_pk_bf16_f32 v113, v118, v119
	v_cvt_pk_bf16_f32 v112, v116, v117
	v_max_f32_e32 v104, 0, v104
	global_store_dwordx4 v[126:127], v[112:115], off offset:256
	v_max_f32_e32 v105, v105, v105
	v_max_f32_e32 v105, 0, v105
	v_mul_f32_e32 v115, v104, v104
	v_max_f32_e32 v104, v109, v109
	v_max_f32_e32 v104, 0, v104
	v_mul_f32_e32 v116, v104, v104
	v_mul_f32_e32 v117, v105, v105
	v_max_f32_e32 v104, v110, v110
	v_max_f32_e32 v105, v106, v106
	v_or_b32_e32 v112, 16, v148
	v_max_f32_e32 v104, 0, v104
	v_max_f32_e32 v105, 0, v105
	v_ashrrev_i32_e32 v113, 31, v112
	v_mul_f32_e32 v110, v104, v104
	v_mul_f32_e32 v106, v105, v105
	v_max_f32_e32 v104, v111, v111
	v_max_f32_e32 v105, v107, v107
	v_max_f32_e32 v100, v100, v100
	v_max_f32_e32 v96, v96, v96
	v_max_f32_e32 v101, v101, v101
	v_max_f32_e32 v97, v97, v97
	v_max_f32_e32 v102, v102, v102
	v_max_f32_e32 v98, v98, v98
	v_max_f32_e32 v103, v103, v103
	v_max_f32_e32 v99, v99, v99
	v_lshlrev_b64 v[112:113], 14, v[112:113]
	v_max_f32_e32 v108, v108, v108
	v_max_f32_e32 v104, 0, v104
	v_max_f32_e32 v105, 0, v105
	v_max_f32_e32 v100, 0, v100
	v_max_f32_e32 v96, 0, v96
	v_max_f32_e32 v101, 0, v101
	v_max_f32_e32 v97, 0, v97
	v_max_f32_e32 v102, 0, v102
	v_max_f32_e32 v98, 0, v98
	v_max_f32_e32 v103, 0, v103
	v_max_f32_e32 v99, 0, v99
	v_max_f32_e32 v108, 0, v108
	v_mul_f32_e32 v111, v104, v104
	v_mul_f32_e32 v107, v105, v105
	v_lshl_add_u64 v[104:105], s[28:29], 0, v[112:113]
	v_mul_f32_e32 v100, v100, v100
	v_mul_f32_e32 v96, v96, v96
	v_mul_f32_e32 v101, v101, v101
	v_mul_f32_e32 v97, v97, v97
	v_mul_f32_e32 v102, v102, v102
	v_mul_f32_e32 v98, v98, v98
	v_mul_f32_e32 v103, v103, v103
	v_mul_f32_e32 v99, v99, v99
	v_max_f32_e32 v88, v88, v88
	v_mul_f32_e32 v114, v108, v108
	v_lshl_add_u64 v[108:109], v[104:105], 0, v[120:121]
	v_cvt_pk_bf16_f32 v99, v98, v99
	v_cvt_pk_bf16_f32 v98, v96, v97
	v_cvt_pk_bf16_f32 v97, v102, v103
	v_cvt_pk_bf16_f32 v96, v100, v101
	v_max_f32_e32 v88, 0, v88
	global_store_dwordx4 v[108:109], v[96:99], off offset:256
	v_max_f32_e32 v89, v89, v89
	v_max_f32_e32 v89, 0, v89
	v_mul_f32_e32 v99, v88, v88
	v_max_f32_e32 v88, v93, v93
	v_max_f32_e32 v88, 0, v88
	v_mul_f32_e32 v100, v88, v88
	v_mul_f32_e32 v101, v89, v89
	v_max_f32_e32 v88, v94, v94
	v_max_f32_e32 v89, v90, v90
	v_or_b32_e32 v96, 32, v148
	v_max_f32_e32 v88, 0, v88
	v_max_f32_e32 v89, 0, v89
	v_ashrrev_i32_e32 v97, 31, v96
	v_mul_f32_e32 v94, v88, v88
	v_mul_f32_e32 v90, v89, v89
	v_max_f32_e32 v88, v95, v95
	v_max_f32_e32 v89, v91, v91
	v_max_f32_e32 v84, v84, v84
	v_max_f32_e32 v80, v80, v80
	v_max_f32_e32 v85, v85, v85
	v_max_f32_e32 v81, v81, v81
	v_max_f32_e32 v86, v86, v86
	v_max_f32_e32 v82, v82, v82
	v_max_f32_e32 v87, v87, v87
	v_max_f32_e32 v83, v83, v83
	v_lshlrev_b64 v[96:97], 14, v[96:97]
	v_max_f32_e32 v92, v92, v92
	v_max_f32_e32 v88, 0, v88
	v_max_f32_e32 v89, 0, v89
	v_max_f32_e32 v84, 0, v84
	v_max_f32_e32 v80, 0, v80
	v_max_f32_e32 v85, 0, v85
	v_max_f32_e32 v81, 0, v81
	v_max_f32_e32 v86, 0, v86
	v_max_f32_e32 v82, 0, v82
	v_max_f32_e32 v87, 0, v87
	v_max_f32_e32 v83, 0, v83
	v_max_f32_e32 v92, 0, v92
	v_mul_f32_e32 v95, v88, v88
	v_mul_f32_e32 v91, v89, v89
	v_lshl_add_u64 v[88:89], s[28:29], 0, v[96:97]
	v_mul_f32_e32 v84, v84, v84
	v_mul_f32_e32 v80, v80, v80
	v_mul_f32_e32 v85, v85, v85
	v_mul_f32_e32 v81, v81, v81
	v_mul_f32_e32 v86, v86, v86
	v_mul_f32_e32 v82, v82, v82
	v_mul_f32_e32 v87, v87, v87
	v_mul_f32_e32 v83, v83, v83
	v_max_f32_e32 v72, v72, v72
	v_mul_f32_e32 v98, v92, v92
	v_lshl_add_u64 v[92:93], v[88:89], 0, v[120:121]
	v_cvt_pk_bf16_f32 v83, v82, v83
	v_cvt_pk_bf16_f32 v82, v80, v81
	v_cvt_pk_bf16_f32 v81, v86, v87
	v_cvt_pk_bf16_f32 v80, v84, v85
	v_max_f32_e32 v72, 0, v72
	global_store_dwordx4 v[92:93], v[80:83], off offset:256
	v_max_f32_e32 v73, v73, v73
	v_max_f32_e32 v73, 0, v73
	v_mul_f32_e32 v83, v72, v72
	v_max_f32_e32 v72, v77, v77
	v_max_f32_e32 v72, 0, v72
	v_mul_f32_e32 v84, v72, v72
	v_mul_f32_e32 v85, v73, v73
	v_max_f32_e32 v72, v78, v78
	v_max_f32_e32 v73, v74, v74
	v_or_b32_e32 v80, 48, v148
	v_max_f32_e32 v72, 0, v72
	v_max_f32_e32 v73, 0, v73
	v_ashrrev_i32_e32 v81, 31, v80
	v_mul_f32_e32 v78, v72, v72
	v_mul_f32_e32 v74, v73, v73
	v_max_f32_e32 v72, v79, v79
	v_max_f32_e32 v73, v75, v75
	v_max_f32_e32 v68, v68, v68
	v_max_f32_e32 v64, v64, v64
	v_max_f32_e32 v69, v69, v69
	v_max_f32_e32 v65, v65, v65
	v_max_f32_e32 v70, v70, v70
	v_max_f32_e32 v66, v66, v66
	v_max_f32_e32 v71, v71, v71
	v_max_f32_e32 v67, v67, v67
	v_lshlrev_b64 v[80:81], 14, v[80:81]
	v_max_f32_e32 v76, v76, v76
	v_max_f32_e32 v72, 0, v72
	v_max_f32_e32 v73, 0, v73
	v_max_f32_e32 v68, 0, v68
	v_max_f32_e32 v64, 0, v64
	v_max_f32_e32 v69, 0, v69
	v_max_f32_e32 v65, 0, v65
	v_max_f32_e32 v70, 0, v70
	v_max_f32_e32 v66, 0, v66
	v_max_f32_e32 v71, 0, v71
	v_max_f32_e32 v67, 0, v67
	v_max_f32_e32 v76, 0, v76
	v_mul_f32_e32 v79, v72, v72
	v_mul_f32_e32 v75, v73, v73
	v_lshl_add_u64 v[72:73], s[28:29], 0, v[80:81]
	v_mul_f32_e32 v68, v68, v68
	v_mul_f32_e32 v64, v64, v64
	v_mul_f32_e32 v69, v69, v69
	v_mul_f32_e32 v65, v65, v65
	v_mul_f32_e32 v70, v70, v70
	v_mul_f32_e32 v66, v66, v66
	v_mul_f32_e32 v71, v71, v71
	v_mul_f32_e32 v67, v67, v67
	v_max_f32_e32 v56, v56, v56
	v_mul_f32_e32 v82, v76, v76
	v_lshl_add_u64 v[76:77], v[72:73], 0, v[120:121]
	v_cvt_pk_bf16_f32 v67, v66, v67
	v_cvt_pk_bf16_f32 v66, v64, v65
	v_cvt_pk_bf16_f32 v65, v70, v71
	v_cvt_pk_bf16_f32 v64, v68, v69
	v_max_f32_e32 v56, 0, v56
	global_store_dwordx4 v[76:77], v[64:67], off offset:256
	v_max_f32_e32 v57, v57, v57
	v_max_f32_e32 v57, 0, v57
	v_mul_f32_e32 v67, v56, v56
	v_max_f32_e32 v56, v61, v61
	v_max_f32_e32 v56, 0, v56
	v_mul_f32_e32 v68, v56, v56
	v_mul_f32_e32 v69, v57, v57
	v_max_f32_e32 v56, v62, v62
	v_max_f32_e32 v57, v58, v58
	v_add_u32_e32 v64, 0x80, v148
	v_max_f32_e32 v56, 0, v56
	v_max_f32_e32 v57, 0, v57
	v_ashrrev_i32_e32 v65, 31, v64
	v_mul_f32_e32 v62, v56, v56
	v_mul_f32_e32 v58, v57, v57
	v_max_f32_e32 v56, v63, v63
	v_max_f32_e32 v57, v59, v59
	v_max_f32_e32 v52, v52, v52
	v_max_f32_e32 v48, v48, v48
	v_max_f32_e32 v53, v53, v53
	v_max_f32_e32 v49, v49, v49
	v_max_f32_e32 v54, v54, v54
	v_max_f32_e32 v50, v50, v50
	v_max_f32_e32 v55, v55, v55
	v_max_f32_e32 v51, v51, v51
	v_lshlrev_b64 v[64:65], 14, v[64:65]
	v_max_f32_e32 v60, v60, v60
	v_max_f32_e32 v56, 0, v56
	v_max_f32_e32 v57, 0, v57
	v_max_f32_e32 v52, 0, v52
	v_max_f32_e32 v48, 0, v48
	v_max_f32_e32 v53, 0, v53
	v_max_f32_e32 v49, 0, v49
	v_max_f32_e32 v54, 0, v54
	v_max_f32_e32 v50, 0, v50
	v_max_f32_e32 v55, 0, v55
	v_max_f32_e32 v51, 0, v51
	v_max_f32_e32 v60, 0, v60
	v_mul_f32_e32 v63, v56, v56
	v_mul_f32_e32 v59, v57, v57
	v_lshl_add_u64 v[56:57], s[28:29], 0, v[64:65]
	v_mul_f32_e32 v52, v52, v52
	v_mul_f32_e32 v48, v48, v48
	v_mul_f32_e32 v53, v53, v53
	v_mul_f32_e32 v49, v49, v49
	v_mul_f32_e32 v54, v54, v54
	v_mul_f32_e32 v50, v50, v50
	v_mul_f32_e32 v55, v55, v55
	v_mul_f32_e32 v51, v51, v51
	v_max_f32_e32 v40, v40, v40
	v_mul_f32_e32 v66, v60, v60
	v_lshl_add_u64 v[60:61], v[56:57], 0, v[120:121]
	v_cvt_pk_bf16_f32 v51, v50, v51
	v_cvt_pk_bf16_f32 v50, v48, v49
	v_cvt_pk_bf16_f32 v49, v54, v55
	v_cvt_pk_bf16_f32 v48, v52, v53
	v_max_f32_e32 v40, 0, v40
	global_store_dwordx4 v[60:61], v[48:51], off offset:256
	v_max_f32_e32 v41, v41, v41
	v_max_f32_e32 v41, 0, v41
	v_mul_f32_e32 v51, v40, v40
	v_max_f32_e32 v40, v45, v45
	v_max_f32_e32 v40, 0, v40
	v_mul_f32_e32 v52, v40, v40
	v_mul_f32_e32 v53, v41, v41
	v_max_f32_e32 v40, v46, v46
	v_max_f32_e32 v41, v42, v42
	v_add_u32_e32 v48, 0x90, v148
	v_max_f32_e32 v40, 0, v40
	v_max_f32_e32 v41, 0, v41
	v_ashrrev_i32_e32 v49, 31, v48
	v_mul_f32_e32 v46, v40, v40
	v_mul_f32_e32 v42, v41, v41
	v_max_f32_e32 v40, v47, v47
	v_max_f32_e32 v41, v43, v43
	v_max_f32_e32 v36, v36, v36
	v_max_f32_e32 v32, v32, v32
	v_max_f32_e32 v37, v37, v37
	v_max_f32_e32 v33, v33, v33
	v_max_f32_e32 v38, v38, v38
	v_max_f32_e32 v34, v34, v34
	v_max_f32_e32 v39, v39, v39
	v_max_f32_e32 v35, v35, v35
	v_lshlrev_b64 v[48:49], 14, v[48:49]
	v_max_f32_e32 v44, v44, v44
	v_max_f32_e32 v40, 0, v40
	v_max_f32_e32 v41, 0, v41
	v_max_f32_e32 v36, 0, v36
	v_max_f32_e32 v32, 0, v32
	v_max_f32_e32 v37, 0, v37
	v_max_f32_e32 v33, 0, v33
	v_max_f32_e32 v38, 0, v38
	v_max_f32_e32 v34, 0, v34
	v_max_f32_e32 v39, 0, v39
	v_max_f32_e32 v35, 0, v35
	v_max_f32_e32 v44, 0, v44
	v_mul_f32_e32 v47, v40, v40
	v_mul_f32_e32 v43, v41, v41
	v_lshl_add_u64 v[40:41], s[28:29], 0, v[48:49]
	v_mul_f32_e32 v36, v36, v36
	v_mul_f32_e32 v32, v32, v32
	v_mul_f32_e32 v37, v37, v37
	v_mul_f32_e32 v33, v33, v33
	v_mul_f32_e32 v38, v38, v38
	v_mul_f32_e32 v34, v34, v34
	v_mul_f32_e32 v39, v39, v39
	v_mul_f32_e32 v35, v35, v35
	v_max_f32_e32 v24, v24, v24
	v_mul_f32_e32 v50, v44, v44
	v_lshl_add_u64 v[44:45], v[40:41], 0, v[120:121]
	v_cvt_pk_bf16_f32 v35, v34, v35
	v_cvt_pk_bf16_f32 v34, v32, v33
	v_cvt_pk_bf16_f32 v33, v38, v39
	v_cvt_pk_bf16_f32 v32, v36, v37
	v_max_f32_e32 v24, 0, v24
	global_store_dwordx4 v[44:45], v[32:35], off offset:256
	v_max_f32_e32 v25, v25, v25
	v_max_f32_e32 v25, 0, v25
	v_mul_f32_e32 v35, v24, v24
	v_max_f32_e32 v24, v29, v29
	v_max_f32_e32 v24, 0, v24
	v_mul_f32_e32 v36, v24, v24
	v_mul_f32_e32 v37, v25, v25
	v_max_f32_e32 v24, v30, v30
	v_max_f32_e32 v25, v26, v26
	v_add_u32_e32 v32, 0xa0, v148
	v_max_f32_e32 v24, 0, v24
	v_max_f32_e32 v25, 0, v25
	v_ashrrev_i32_e32 v33, 31, v32
	v_mul_f32_e32 v30, v24, v24
	v_mul_f32_e32 v26, v25, v25
	v_max_f32_e32 v24, v31, v31
	v_max_f32_e32 v25, v27, v27
	v_max_f32_e32 v20, v20, v20
	v_max_f32_e32 v16, v16, v16
	v_max_f32_e32 v21, v21, v21
	v_max_f32_e32 v17, v17, v17
	v_max_f32_e32 v22, v22, v22
	v_max_f32_e32 v18, v18, v18
	v_max_f32_e32 v23, v23, v23
	v_max_f32_e32 v19, v19, v19
	v_lshlrev_b64 v[32:33], 14, v[32:33]
	v_max_f32_e32 v28, v28, v28
	v_max_f32_e32 v24, 0, v24
	v_max_f32_e32 v25, 0, v25
	v_max_f32_e32 v20, 0, v20
	v_max_f32_e32 v16, 0, v16
	v_max_f32_e32 v21, 0, v21
	v_max_f32_e32 v17, 0, v17
	v_max_f32_e32 v22, 0, v22
	v_max_f32_e32 v18, 0, v18
	v_max_f32_e32 v23, 0, v23
	v_max_f32_e32 v19, 0, v19
	v_max_f32_e32 v28, 0, v28
	v_mul_f32_e32 v31, v24, v24
	v_mul_f32_e32 v27, v25, v25
	v_lshl_add_u64 v[24:25], s[28:29], 0, v[32:33]
	v_mul_f32_e32 v20, v20, v20
	v_mul_f32_e32 v16, v16, v16
	v_mul_f32_e32 v21, v21, v21
	v_mul_f32_e32 v17, v17, v17
	v_mul_f32_e32 v22, v22, v22
	v_mul_f32_e32 v18, v18, v18
	v_mul_f32_e32 v23, v23, v23
	v_mul_f32_e32 v19, v19, v19
	v_max_f32_e32 v8, v8, v8
	v_mul_f32_e32 v34, v28, v28
	v_lshl_add_u64 v[28:29], v[24:25], 0, v[120:121]
	v_cvt_pk_bf16_f32 v19, v18, v19
	v_cvt_pk_bf16_f32 v18, v16, v17
	v_cvt_pk_bf16_f32 v17, v22, v23
	v_cvt_pk_bf16_f32 v16, v20, v21
	v_max_f32_e32 v8, 0, v8
	global_store_dwordx4 v[28:29], v[16:19], off offset:256
	v_max_f32_e32 v9, v9, v9
	v_max_f32_e32 v9, 0, v9
	v_mul_f32_e32 v19, v8, v8
	v_max_f32_e32 v8, v13, v13
	v_max_f32_e32 v8, 0, v8
	v_mul_f32_e32 v20, v8, v8
	v_mul_f32_e32 v21, v9, v9
	v_max_f32_e32 v8, v14, v14
	v_max_f32_e32 v9, v10, v10
	v_add_u32_e32 v16, 0xb0, v148
	v_max_f32_e32 v8, 0, v8
	v_max_f32_e32 v9, 0, v9
	v_ashrrev_i32_e32 v17, 31, v16
	v_max_f32_e32 v12, v12, v12
	v_mul_f32_e32 v14, v8, v8
	v_mul_f32_e32 v10, v9, v9
	v_max_f32_e32 v8, v15, v15
	v_max_f32_e32 v9, v11, v11
	v_max_f32_e32 v4, v4, v4
	v_max_f32_e32 v0, v0, v0
	v_max_f32_e32 v5, v5, v5
	v_max_f32_e32 v1, v1, v1
	v_max_f32_e32 v6, v6, v6
	v_max_f32_e32 v2, v2, v2
	v_max_f32_e32 v7, v7, v7
	v_max_f32_e32 v3, v3, v3
	v_lshlrev_b64 v[16:17], 14, v[16:17]
	v_max_f32_e32 v12, 0, v12
	v_max_f32_e32 v8, 0, v8
	v_max_f32_e32 v9, 0, v9
	v_max_f32_e32 v4, 0, v4
	v_max_f32_e32 v0, 0, v0
	v_max_f32_e32 v5, 0, v5
	v_max_f32_e32 v1, 0, v1
	v_max_f32_e32 v6, 0, v6
	v_max_f32_e32 v2, 0, v2
	v_max_f32_e32 v7, 0, v7
	v_max_f32_e32 v3, 0, v3
	v_mul_f32_e32 v18, v12, v12
	v_mul_f32_e32 v15, v8, v8
	v_mul_f32_e32 v11, v9, v9
	v_lshl_add_u64 v[8:9], s[28:29], 0, v[16:17]
	v_mul_f32_e32 v4, v4, v4
	v_mul_f32_e32 v0, v0, v0
	v_mul_f32_e32 v5, v5, v5
	v_mul_f32_e32 v1, v1, v1
	v_mul_f32_e32 v6, v6, v6
	v_mul_f32_e32 v2, v2, v2
	v_mul_f32_e32 v7, v7, v7
	v_mul_f32_e32 v3, v3, v3
	v_cvt_pk_bf16_f32 v125, v125, v162
	v_cvt_pk_bf16_f32 v124, v124, v159
	v_cvt_pk_bf16_f32 v123, v160, v161
	v_cvt_pk_bf16_f32 v122, v149, v158
	v_cvt_pk_bf16_f32 v107, v106, v107
	v_cvt_pk_bf16_f32 v106, v115, v117
	v_cvt_pk_bf16_f32 v105, v110, v111
	v_cvt_pk_bf16_f32 v104, v114, v116
	v_cvt_pk_bf16_f32 v91, v90, v91
	v_cvt_pk_bf16_f32 v90, v99, v101
	v_cvt_pk_bf16_f32 v89, v94, v95
	v_cvt_pk_bf16_f32 v88, v98, v100
	v_cvt_pk_bf16_f32 v75, v74, v75
	v_cvt_pk_bf16_f32 v74, v83, v85
	v_cvt_pk_bf16_f32 v73, v78, v79
	v_cvt_pk_bf16_f32 v72, v82, v84
	v_cvt_pk_bf16_f32 v59, v58, v59
	v_cvt_pk_bf16_f32 v58, v67, v69
	v_cvt_pk_bf16_f32 v57, v62, v63
	v_cvt_pk_bf16_f32 v56, v66, v68
	v_cvt_pk_bf16_f32 v43, v42, v43
	v_cvt_pk_bf16_f32 v42, v51, v53
	v_cvt_pk_bf16_f32 v41, v46, v47
	v_cvt_pk_bf16_f32 v40, v50, v52
	v_cvt_pk_bf16_f32 v27, v26, v27
	v_cvt_pk_bf16_f32 v26, v35, v37
	v_cvt_pk_bf16_f32 v25, v30, v31
	v_cvt_pk_bf16_f32 v24, v34, v36
	v_lshl_add_u64 v[12:13], v[8:9], 0, v[120:121]
	v_cvt_pk_bf16_f32 v11, v10, v11
	v_cvt_pk_bf16_f32 v10, v19, v21
	v_cvt_pk_bf16_f32 v9, v14, v15
	v_cvt_pk_bf16_f32 v8, v18, v20
	v_cvt_pk_bf16_f32 v3, v2, v3
	v_cvt_pk_bf16_f32 v2, v0, v1
	v_cvt_pk_bf16_f32 v1, v6, v7
	v_cvt_pk_bf16_f32 v0, v4, v5
	global_store_dwordx4 v[126:127], v[122:125], off
	global_store_dwordx4 v[108:109], v[104:107], off
	global_store_dwordx4 v[92:93], v[88:91], off
	global_store_dwordx4 v[76:77], v[72:75], off
	global_store_dwordx4 v[60:61], v[56:59], off
	global_store_dwordx4 v[44:45], v[40:43], off
	global_store_dwordx4 v[28:29], v[24:27], off
	global_store_dwordx4 v[12:13], v[8:11], off
	global_store_dwordx4 v[12:13], v[0:3], off offset:256

.LBB0_1433:
	ds_read_b128 v[148:151], v158
	ds_read_b128 v[152:155], v158 offset:1024
	ds_read_b128 v[162:165], v158 offset:2048
	ds_read_b128 v[166:169], v158 offset:3072
	s_add_u32 s20, s26, 0xffe00080
	s_addc_u32 s21, s27, -1
	s_cmpk_eq_i32 s53, 0x7c
	s_cselect_b32 s21, s15, s21
	s_cselect_b32 s20, s49, s20
	s_cselect_b32 s31, s11, s52
	s_cselect_b32 s30, s50, s51
	v_lshl_add_u64 v[204:205], s[26:27], 0, v[136:137]
	s_add_i32 m0, s25, 0xc000
	ds_read_b128 v[170:173], v159
	ds_read_b128 v[174:177], v159 offset:1024
	ds_read_b128 v[178:181], v159 offset:2048
	ds_read_b128 v[182:185], v159 offset:3072
	ds_read_b128 v[186:189], v159 offset:4096
	ds_read_b128 v[190:193], v159 offset:5120
	ds_read_b128 v[196:199], v159 offset:6144
	ds_read_b128 v[200:203], v159 offset:7168
	global_load_lds_dwordx4 v[204:205], off
	s_add_i32 m0, s25, 0xe000
	v_lshl_add_u64 v[204:205], s[26:27], 0, v[138:139]
	global_load_lds_dwordx4 v[204:205], off
	s_waitcnt lgkmcnt(8)
	s_barrier
	s_waitcnt lgkmcnt(0)
	s_setprio 1
	v_mfma_f32_16x16x32_bf16 v[124:127], v[148:151], v[170:173], v[124:127]
	v_mfma_f32_16x16x32_bf16 v[120:123], v[162:165], v[170:173], v[120:123]
	v_mfma_f32_16x16x32_bf16 v[108:111], v[148:151], v[178:181], v[108:111]
	v_mfma_f32_16x16x32_bf16 v[104:107], v[162:165], v[178:181], v[104:107]
	v_mfma_f32_16x16x32_bf16 v[92:95], v[148:151], v[186:189], v[92:95]
	v_mfma_f32_16x16x32_bf16 v[88:91], v[162:165], v[186:189], v[88:91]
	v_mfma_f32_16x16x32_bf16 v[76:79], v[148:151], v[196:199], v[76:79]
	v_mfma_f32_16x16x32_bf16 v[72:75], v[162:165], v[196:199], v[72:75]
	v_mfma_f32_16x16x32_bf16 v[124:127], v[152:155], v[174:177], v[124:127]
	v_mfma_f32_16x16x32_bf16 v[120:123], v[166:169], v[174:177], v[120:123]
	v_mfma_f32_16x16x32_bf16 v[108:111], v[152:155], v[182:185], v[108:111]
	v_mfma_f32_16x16x32_bf16 v[104:107], v[166:169], v[182:185], v[104:107]
	v_mfma_f32_16x16x32_bf16 v[92:95], v[152:155], v[190:193], v[92:95]
	v_mfma_f32_16x16x32_bf16 v[88:91], v[166:169], v[190:193], v[88:91]
	v_mfma_f32_16x16x32_bf16 v[76:79], v[152:155], v[200:203], v[76:79]
	v_mfma_f32_16x16x32_bf16 v[72:75], v[166:169], v[200:203], v[72:75]
	s_setprio 0
	s_barrier
	s_add_i32 s54, s45, s23
	v_lshl_add_u64 v[220:221], s[30:31], 0, v[132:133]
	s_mov_b32 m0, s54
	ds_read_b128 v[204:207], v160
	ds_read_b128 v[208:211], v160 offset:1024
	ds_read_b128 v[212:215], v160 offset:2048
	ds_read_b128 v[216:219], v160 offset:3072
	global_load_lds_dwordx4 v[220:221], off
	s_add_i32 m0, s54, 0x2000
	v_lshl_add_u64 v[222:223], s[30:31], 0, v[128:129]
	global_load_lds_dwordx4 v[222:223], off
	s_barrier
	s_waitcnt lgkmcnt(0)
	s_setprio 1
	v_mfma_f32_16x16x32_bf16 v[116:119], v[204:207], v[170:173], v[116:119]
	v_mfma_f32_16x16x32_bf16 v[112:115], v[212:215], v[170:173], v[112:115]
	v_mfma_f32_16x16x32_bf16 v[100:103], v[204:207], v[178:181], v[100:103]
	v_mfma_f32_16x16x32_bf16 v[96:99], v[212:215], v[178:181], v[96:99]
	v_mfma_f32_16x16x32_bf16 v[84:87], v[204:207], v[186:189], v[84:87]
	v_mfma_f32_16x16x32_bf16 v[80:83], v[212:215], v[186:189], v[80:83]
	v_mfma_f32_16x16x32_bf16 v[68:71], v[204:207], v[196:199], v[68:71]
	v_mfma_f32_16x16x32_bf16 v[64:67], v[212:215], v[196:199], v[64:67]
	v_mfma_f32_16x16x32_bf16 v[116:119], v[208:211], v[174:177], v[116:119]
	v_mfma_f32_16x16x32_bf16 v[112:115], v[216:219], v[174:177], v[112:115]
	v_mfma_f32_16x16x32_bf16 v[100:103], v[208:211], v[182:185], v[100:103]
	v_mfma_f32_16x16x32_bf16 v[96:99], v[216:219], v[182:185], v[96:99]
	v_mfma_f32_16x16x32_bf16 v[84:87], v[208:211], v[190:193], v[84:87]
	v_mfma_f32_16x16x32_bf16 v[80:83], v[216:219], v[190:193], v[80:83]
	v_mfma_f32_16x16x32_bf16 v[68:71], v[208:211], v[200:203], v[68:71]
	v_mfma_f32_16x16x32_bf16 v[64:67], v[216:219], v[200:203], v[64:67]
	s_setprio 0
	s_mov_b32 m0, s25
	v_lshl_add_u64 v[224:225], s[20:21], 0, v[134:135]
	s_barrier
	ds_read_b128 v[170:173], v159 offset:16384
	ds_read_b128 v[174:177], v159 offset:17408
	ds_read_b128 v[178:181], v159 offset:18432
	ds_read_b128 v[182:185], v159 offset:19456
	ds_read_b128 v[186:189], v159 offset:20480
	ds_read_b128 v[190:193], v159 offset:21504
	ds_read_b128 v[196:199], v159 offset:22528
	ds_read_b128 v[200:203], v159 offset:23552
	global_load_lds_dwordx4 v[224:225], off
	s_mov_b32 m0, s37
	v_lshl_add_u64 v[226:227], s[20:21], 0, v[130:131]
	global_load_lds_dwordx4 v[226:227], off
	s_barrier
	s_waitcnt lgkmcnt(0)
	s_setprio 1
	v_mfma_f32_16x16x32_bf16 v[60:63], v[148:151], v[170:173], v[60:63]
	v_mfma_f32_16x16x32_bf16 v[56:59], v[162:165], v[170:173], v[56:59]
	v_mfma_f32_16x16x32_bf16 v[44:47], v[148:151], v[178:181], v[44:47]
	v_mfma_f32_16x16x32_bf16 v[40:43], v[162:165], v[178:181], v[40:43]
	v_mfma_f32_16x16x32_bf16 v[28:31], v[148:151], v[186:189], v[28:31]
	v_mfma_f32_16x16x32_bf16 v[24:27], v[162:165], v[186:189], v[24:27]
	v_mfma_f32_16x16x32_bf16 v[12:15], v[148:151], v[196:199], v[12:15]
	v_mfma_f32_16x16x32_bf16 v[8:11], v[162:165], v[196:199], v[8:11]
	v_mfma_f32_16x16x32_bf16 v[60:63], v[152:155], v[174:177], v[60:63]
	v_mfma_f32_16x16x32_bf16 v[56:59], v[166:169], v[174:177], v[56:59]
	v_mfma_f32_16x16x32_bf16 v[44:47], v[152:155], v[182:185], v[44:47]
	v_mfma_f32_16x16x32_bf16 v[40:43], v[166:169], v[182:185], v[40:43]
	v_mfma_f32_16x16x32_bf16 v[28:31], v[152:155], v[190:193], v[28:31]
	v_mfma_f32_16x16x32_bf16 v[24:27], v[166:169], v[190:193], v[24:27]
	v_mfma_f32_16x16x32_bf16 v[12:15], v[152:155], v[200:203], v[12:15]
	v_mfma_f32_16x16x32_bf16 v[8:11], v[166:169], v[200:203], v[8:11]
	s_setprio 0
	s_barrier
	s_add_u32 s54, s30, 0x200000
	s_addc_u32 s55, s31, 0
	s_add_i32 s56, s47, s23
	s_mov_b32 m0, s56
	v_lshl_add_u64 v[148:149], s[54:55], 0, v[132:133]
	global_load_lds_dwordx4 v[148:149], off
	s_add_i32 m0, s56, 0x2000
	v_lshl_add_u64 v[148:149], s[54:55], 0, v[128:129]
	global_load_lds_dwordx4 v[148:149], off
	s_waitcnt vmcnt(6)
	s_barrier
	s_setprio 1
	v_mfma_f32_16x16x32_bf16 v[52:55], v[204:207], v[170:173], v[52:55]
	v_mfma_f32_16x16x32_bf16 v[48:51], v[212:215], v[170:173], v[48:51]
	v_mfma_f32_16x16x32_bf16 v[36:39], v[204:207], v[178:181], v[36:39]
	v_mfma_f32_16x16x32_bf16 v[32:35], v[212:215], v[178:181], v[32:35]
	v_mfma_f32_16x16x32_bf16 v[20:23], v[204:207], v[186:189], v[20:23]
	v_mfma_f32_16x16x32_bf16 v[16:19], v[212:215], v[186:189], v[16:19]
	v_mfma_f32_16x16x32_bf16 v[4:7], v[204:207], v[196:199], v[4:7]
	v_mfma_f32_16x16x32_bf16 v[0:3], v[212:215], v[196:199], v[0:3]
	v_mfma_f32_16x16x32_bf16 v[52:55], v[208:211], v[174:177], v[52:55]
	v_mfma_f32_16x16x32_bf16 v[48:51], v[216:219], v[174:177], v[48:51]
	v_mfma_f32_16x16x32_bf16 v[36:39], v[208:211], v[182:185], v[36:39]
	v_mfma_f32_16x16x32_bf16 v[32:35], v[216:219], v[182:185], v[32:35]
	v_mfma_f32_16x16x32_bf16 v[20:23], v[208:211], v[190:193], v[20:23]
	v_mfma_f32_16x16x32_bf16 v[16:19], v[216:219], v[190:193], v[16:19]
	v_mfma_f32_16x16x32_bf16 v[4:7], v[208:211], v[200:203], v[4:7]
	v_mfma_f32_16x16x32_bf16 v[0:3], v[216:219], v[200:203], v[0:3]
	s_setprio 0
	s_add_i32 s54, 0, 0x18000
	v_add_u32_e32 v161, s54, v147
	s_barrier
	ds_read_b128 v[148:151], v161
	ds_read_b128 v[152:155], v161 offset:1024
	ds_read_b128 v[162:165], v161 offset:2048
	ds_read_b128 v[166:169], v161 offset:3072
	s_add_u32 s20, s20, 0x200000
	s_addc_u32 s21, s21, 0
	s_mov_b32 m0, s38
	v_lshl_add_u64 v[204:205], s[20:21], 0, v[134:135]
	ds_read_b128 v[170:173], v159 offset:32768
	ds_read_b128 v[174:177], v159 offset:33792
	ds_read_b128 v[178:181], v159 offset:34816
	ds_read_b128 v[182:185], v159 offset:35840
	ds_read_b128 v[186:189], v159 offset:36864
	ds_read_b128 v[190:193], v159 offset:37888
	ds_read_b128 v[196:199], v159 offset:38912
	ds_read_b128 v[200:203], v159 offset:39936
	global_load_lds_dwordx4 v[204:205], off
	s_mov_b32 m0, s39
	v_lshl_add_u64 v[204:205], s[20:21], 0, v[130:131]
	global_load_lds_dwordx4 v[204:205], off
	s_waitcnt lgkmcnt(8)
	s_barrier
	s_waitcnt lgkmcnt(0)
	s_setprio 1
	v_mfma_f32_16x16x32_bf16 v[124:127], v[148:151], v[170:173], v[124:127]
	v_mfma_f32_16x16x32_bf16 v[120:123], v[162:165], v[170:173], v[120:123]
	v_mfma_f32_16x16x32_bf16 v[108:111], v[148:151], v[178:181], v[108:111]
	v_mfma_f32_16x16x32_bf16 v[104:107], v[162:165], v[178:181], v[104:107]
	v_mfma_f32_16x16x32_bf16 v[92:95], v[148:151], v[186:189], v[92:95]
	v_mfma_f32_16x16x32_bf16 v[88:91], v[162:165], v[186:189], v[88:91]
	v_mfma_f32_16x16x32_bf16 v[76:79], v[148:151], v[196:199], v[76:79]
	v_mfma_f32_16x16x32_bf16 v[72:75], v[162:165], v[196:199], v[72:75]
	v_mfma_f32_16x16x32_bf16 v[124:127], v[152:155], v[174:177], v[124:127]
	v_mfma_f32_16x16x32_bf16 v[120:123], v[166:169], v[174:177], v[120:123]
	v_mfma_f32_16x16x32_bf16 v[108:111], v[152:155], v[182:185], v[108:111]
	v_mfma_f32_16x16x32_bf16 v[104:107], v[166:169], v[182:185], v[104:107]
	v_mfma_f32_16x16x32_bf16 v[92:95], v[152:155], v[190:193], v[92:95]
	v_mfma_f32_16x16x32_bf16 v[88:91], v[166:169], v[190:193], v[88:91]
	v_mfma_f32_16x16x32_bf16 v[76:79], v[152:155], v[200:203], v[76:79]
	v_mfma_f32_16x16x32_bf16 v[72:75], v[166:169], v[200:203], v[72:75]
	s_setprio 0
	s_barrier
	s_add_i32 s55, 0, 0x1c000
	s_add_i32 s20, s54, s23
	v_add_u32_e32 v161, s55, v147
	v_lshl_add_u64 v[220:221], v[220:221], 0, s[8:9]
	s_mov_b32 m0, s20
	ds_read_b128 v[204:207], v161
	ds_read_b128 v[208:211], v161 offset:1024
	ds_read_b128 v[212:215], v161 offset:2048
	ds_read_b128 v[216:219], v161 offset:3072
	global_load_lds_dwordx4 v[220:221], off
	s_add_i32 m0, s20, 0x2000
	v_lshl_add_u64 v[220:221], v[222:223], 0, s[8:9]
	global_load_lds_dwordx4 v[220:221], off
	s_barrier
	s_waitcnt lgkmcnt(0)
	s_setprio 1
	v_mfma_f32_16x16x32_bf16 v[116:119], v[204:207], v[170:173], v[116:119]
	v_mfma_f32_16x16x32_bf16 v[112:115], v[212:215], v[170:173], v[112:115]
	v_mfma_f32_16x16x32_bf16 v[100:103], v[204:207], v[178:181], v[100:103]
	v_mfma_f32_16x16x32_bf16 v[96:99], v[212:215], v[178:181], v[96:99]
	v_mfma_f32_16x16x32_bf16 v[84:87], v[204:207], v[186:189], v[84:87]
	v_mfma_f32_16x16x32_bf16 v[80:83], v[212:215], v[186:189], v[80:83]
	v_mfma_f32_16x16x32_bf16 v[68:71], v[204:207], v[196:199], v[68:71]
	v_mfma_f32_16x16x32_bf16 v[64:67], v[212:215], v[196:199], v[64:67]
	v_mfma_f32_16x16x32_bf16 v[116:119], v[208:211], v[174:177], v[116:119]
	v_mfma_f32_16x16x32_bf16 v[112:115], v[216:219], v[174:177], v[112:115]
	v_mfma_f32_16x16x32_bf16 v[100:103], v[208:211], v[182:185], v[100:103]
	v_mfma_f32_16x16x32_bf16 v[96:99], v[216:219], v[182:185], v[96:99]
	v_mfma_f32_16x16x32_bf16 v[84:87], v[208:211], v[190:193], v[84:87]
	v_mfma_f32_16x16x32_bf16 v[80:83], v[216:219], v[190:193], v[80:83]
	v_mfma_f32_16x16x32_bf16 v[68:71], v[208:211], v[200:203], v[68:71]
	v_mfma_f32_16x16x32_bf16 v[64:67], v[216:219], v[200:203], v[64:67]
	s_setprio 0
	s_mov_b32 m0, s35
	v_lshl_add_u64 v[220:221], v[224:225], 0, s[8:9]
	s_barrier
	ds_read_b128 v[170:173], v159 offset:49152
	ds_read_b128 v[174:177], v159 offset:50176
	ds_read_b128 v[178:181], v159 offset:51200
	ds_read_b128 v[182:185], v159 offset:52224
	ds_read_b128 v[186:189], v159 offset:53248
	ds_read_b128 v[190:193], v159 offset:54272
	ds_read_b128 v[196:199], v159 offset:55296
	ds_read_b128 v[200:203], v159 offset:56320
	global_load_lds_dwordx4 v[220:221], off
	s_mov_b32 m0, s41
	v_lshl_add_u64 v[220:221], v[226:227], 0, s[8:9]
	global_load_lds_dwordx4 v[220:221], off
	s_barrier
	s_waitcnt lgkmcnt(0)
	s_setprio 1
	v_mfma_f32_16x16x32_bf16 v[60:63], v[148:151], v[170:173], v[60:63]
	v_mfma_f32_16x16x32_bf16 v[56:59], v[162:165], v[170:173], v[56:59]
	v_mfma_f32_16x16x32_bf16 v[44:47], v[148:151], v[178:181], v[44:47]
	v_mfma_f32_16x16x32_bf16 v[40:43], v[162:165], v[178:181], v[40:43]
	v_mfma_f32_16x16x32_bf16 v[28:31], v[148:151], v[186:189], v[28:31]
	v_mfma_f32_16x16x32_bf16 v[24:27], v[162:165], v[186:189], v[24:27]
	v_mfma_f32_16x16x32_bf16 v[12:15], v[148:151], v[196:199], v[12:15]
	v_mfma_f32_16x16x32_bf16 v[8:11], v[162:165], v[196:199], v[8:11]
	v_mfma_f32_16x16x32_bf16 v[60:63], v[152:155], v[174:177], v[60:63]
	v_mfma_f32_16x16x32_bf16 v[56:59], v[166:169], v[174:177], v[56:59]
	v_mfma_f32_16x16x32_bf16 v[44:47], v[152:155], v[182:185], v[44:47]
	v_mfma_f32_16x16x32_bf16 v[40:43], v[166:169], v[182:185], v[40:43]
	v_mfma_f32_16x16x32_bf16 v[28:31], v[152:155], v[190:193], v[28:31]
	v_mfma_f32_16x16x32_bf16 v[24:27], v[166:169], v[190:193], v[24:27]
	v_mfma_f32_16x16x32_bf16 v[12:15], v[152:155], v[200:203], v[12:15]
	v_mfma_f32_16x16x32_bf16 v[8:11], v[166:169], v[200:203], v[8:11]
	s_setprio 0
	s_barrier
	s_add_u32 s20, s30, 0x200080
	s_addc_u32 s21, s31, 0
	s_add_i32 s30, s55, s23
	s_mov_b32 m0, s30
	v_lshl_add_u64 v[148:149], s[20:21], 0, v[132:133]
	global_load_lds_dwordx4 v[148:149], off
	s_add_i32 m0, s30, 0x2000
	v_lshl_add_u64 v[148:149], s[20:21], 0, v[128:129]
	global_load_lds_dwordx4 v[148:149], off
	s_waitcnt vmcnt(6)
	s_barrier
	s_setprio 1
	v_mfma_f32_16x16x32_bf16 v[52:55], v[204:207], v[170:173], v[52:55]
	v_mfma_f32_16x16x32_bf16 v[48:51], v[212:215], v[170:173], v[48:51]
	v_mfma_f32_16x16x32_bf16 v[36:39], v[204:207], v[178:181], v[36:39]
	v_mfma_f32_16x16x32_bf16 v[32:35], v[212:215], v[178:181], v[32:35]
	v_mfma_f32_16x16x32_bf16 v[20:23], v[204:207], v[186:189], v[20:23]
	v_mfma_f32_16x16x32_bf16 v[16:19], v[212:215], v[186:189], v[16:19]
	v_mfma_f32_16x16x32_bf16 v[4:7], v[204:207], v[196:199], v[4:7]
	v_mfma_f32_16x16x32_bf16 v[0:3], v[212:215], v[196:199], v[0:3]
	v_mfma_f32_16x16x32_bf16 v[52:55], v[208:211], v[174:177], v[52:55]
	v_mfma_f32_16x16x32_bf16 v[48:51], v[216:219], v[174:177], v[48:51]
	v_mfma_f32_16x16x32_bf16 v[36:39], v[208:211], v[182:185], v[36:39]
	v_mfma_f32_16x16x32_bf16 v[32:35], v[216:219], v[182:185], v[32:35]
	v_mfma_f32_16x16x32_bf16 v[20:23], v[208:211], v[190:193], v[20:23]
	v_mfma_f32_16x16x32_bf16 v[16:19], v[216:219], v[190:193], v[16:19]
	v_mfma_f32_16x16x32_bf16 v[4:7], v[208:211], v[200:203], v[4:7]
	v_mfma_f32_16x16x32_bf16 v[0:3], v[216:219], v[200:203], v[0:3]
	s_setprio 0
	s_add_i32 s53, s53, 2
	s_add_u32 s26, s26, 0x100
	s_addc_u32 s27, s27, 0
	s_add_u32 s51, s51, 0x100
	s_addc_u32 s52, s52, 0
	s_cmpk_gt_u32 s53, 0x7d
	s_cbranch_scc1 .Lepi_last_mlpout1
	s_barrier
	s_branch .LBB0_1433
.Lepi_last_mlpout1:
	s_cmp_lg_u32 s34, 64
	s_cbranch_scc1 .Lepi_bar_mlpout1
	s_lshl_b32 s11, s24, 8
	s_add_i32 s11, s11, s34
	v_or_b32_e32 v154, s11, v145
	s_add_i32 s15, s11, 0xffffe000
	v_lshl_or_b32 v150, s33, 8, v157
	s_lshr_b32 s15, s15, 12
	v_lshlrev_b32_e32 v148, 12, v154
	s_add_i32 s15, s15, 1
	s_cmp_gt_i32 s11, s48
	s_cselect_b32 s15, s15, 0
	s_mul_i32 s15, s15, s46
	v_lshl_add_u32 v148, v150, 1, v148
	s_add_u32 s20, s6, s15
	s_addc_u32 s21, s7, 0
	v_lshlrev_b32_e32 v149, 2, v150
	s_nop 0
	global_load_dwordx4 v[196:199], v149, s[20:21]
	global_load_dwordx4 v[200:203], v149, s[20:21] offset:16
	global_load_dwordx4 v[204:207], v149, s[20:21] offset:512
	global_load_dwordx4 v[208:211], v149, s[20:21] offset:528
	global_load_dwordx4 v[212:215], v148, s[74:75]
	global_load_dwordx4 v[216:219], v148, s[74:75] offset:256
	v_add_u32_e32 v151, 0x10000, v148
	global_load_dwordx4 v[220:223], v151, s[74:75]
	global_load_dwordx4 v[224:227], v151, s[74:75] offset:256
	v_add_u32_e32 v151, 0x20000, v148
	global_load_dwordx4 v[164:167], v151, s[74:75]
	global_load_dwordx4 v[168:171], v151, s[74:75] offset:256
	v_add_u32_e32 v151, 0x30000, v148
	global_load_dwordx4 v[172:175], v151, s[74:75]
	global_load_dwordx4 v[176:179], v151, s[74:75] offset:256
	s_waitcnt vmcnt(0)
	v_lshlrev_b32_e32 v180, 16, v212
	v_and_b32_e32 v181, 0xffff0000, v212
	v_lshlrev_b32_e32 v182, 16, v213
	v_and_b32_e32 v183, 0xffff0000, v213
	v_lshlrev_b32_e32 v184, 16, v214
	v_and_b32_e32 v185, 0xffff0000, v214
	v_lshlrev_b32_e32 v186, 16, v215
	v_and_b32_e32 v187, 0xffff0000, v215
	v_pk_fma_f32 v[124:125], v[124:125], v[196:197], v[180:181]
	v_pk_fma_f32 v[126:127], v[126:127], v[198:199], v[182:183]
	v_pk_fma_f32 v[120:121], v[120:121], v[200:201], v[184:185]
	v_pk_fma_f32 v[122:123], v[122:123], v[202:203], v[186:187]
	v_cvt_pk_bf16_f32 v123, v122, v123
	v_cvt_pk_bf16_f32 v122, v120, v121
	v_cvt_pk_bf16_f32 v121, v126, v127
	v_cvt_pk_bf16_f32 v120, v124, v125
	global_store_dwordx4 v148, v[120:123], s[42:43]
	v_lshlrev_b32_e32 v180, 16, v216
	v_and_b32_e32 v181, 0xffff0000, v216
	v_lshlrev_b32_e32 v182, 16, v217
	v_and_b32_e32 v183, 0xffff0000, v217
	v_lshlrev_b32_e32 v184, 16, v218
	v_and_b32_e32 v185, 0xffff0000, v218
	v_lshlrev_b32_e32 v186, 16, v219
	v_and_b32_e32 v187, 0xffff0000, v219
	v_pk_fma_f32 v[116:117], v[116:117], v[204:205], v[180:181]
	v_pk_fma_f32 v[118:119], v[118:119], v[206:207], v[182:183]
	v_pk_fma_f32 v[112:113], v[112:113], v[208:209], v[184:185]
	v_pk_fma_f32 v[114:115], v[114:115], v[210:211], v[186:187]
	v_cvt_pk_bf16_f32 v115, v114, v115
	v_cvt_pk_bf16_f32 v114, v112, v113
	v_cvt_pk_bf16_f32 v113, v118, v119
	v_cvt_pk_bf16_f32 v112, v116, v117
	global_store_dwordx4 v148, v[112:115], s[42:43] offset:256
	v_lshlrev_b32_e32 v180, 16, v220
	v_and_b32_e32 v181, 0xffff0000, v220
	v_lshlrev_b32_e32 v182, 16, v221
	v_and_b32_e32 v183, 0xffff0000, v221
	v_lshlrev_b32_e32 v184, 16, v222
	v_and_b32_e32 v185, 0xffff0000, v222
	v_lshlrev_b32_e32 v186, 16, v223
	v_and_b32_e32 v187, 0xffff0000, v223
	v_pk_fma_f32 v[108:109], v[108:109], v[196:197], v[180:181]
	v_pk_fma_f32 v[110:111], v[110:111], v[198:199], v[182:183]
	v_pk_fma_f32 v[104:105], v[104:105], v[200:201], v[184:185]
	v_pk_fma_f32 v[106:107], v[106:107], v[202:203], v[186:187]
	v_cvt_pk_bf16_f32 v107, v106, v107
	v_cvt_pk_bf16_f32 v106, v104, v105
	v_cvt_pk_bf16_f32 v105, v110, v111
	v_cvt_pk_bf16_f32 v104, v108, v109
	v_add_u32_e32 v151, 0x10000, v148
	global_store_dwordx4 v151, v[104:107], s[42:43]
	v_lshlrev_b32_e32 v180, 16, v224
	v_and_b32_e32 v181, 0xffff0000, v224
	v_lshlrev_b32_e32 v182, 16, v225
	v_and_b32_e32 v183, 0xffff0000, v225
	v_lshlrev_b32_e32 v184, 16, v226
	v_and_b32_e32 v185, 0xffff0000, v226
	v_lshlrev_b32_e32 v186, 16, v227
	v_and_b32_e32 v187, 0xffff0000, v227
	v_pk_fma_f32 v[100:101], v[100:101], v[204:205], v[180:181]
	v_pk_fma_f32 v[102:103], v[102:103], v[206:207], v[182:183]
	v_pk_fma_f32 v[96:97], v[96:97], v[208:209], v[184:185]
	v_pk_fma_f32 v[98:99], v[98:99], v[210:211], v[186:187]
	v_cvt_pk_bf16_f32 v99, v98, v99
	v_cvt_pk_bf16_f32 v98, v96, v97
	v_cvt_pk_bf16_f32 v97, v102, v103
	v_cvt_pk_bf16_f32 v96, v100, v101
	v_add_u32_e32 v151, 0x10000, v148
	global_store_dwordx4 v151, v[96:99], s[42:43] offset:256
	v_add_u32_e32 v151, 0x80000, v148
	global_load_dwordx4 v[212:215], v151, s[74:75]
	global_load_dwordx4 v[216:219], v151, s[74:75] offset:256
	v_add_u32_e32 v151, 0x90000, v148
	global_load_dwordx4 v[220:223], v151, s[74:75]
	global_load_dwordx4 v[224:227], v151, s[74:75] offset:256
	v_lshlrev_b32_e32 v180, 16, v164
	v_and_b32_e32 v181, 0xffff0000, v164
	v_lshlrev_b32_e32 v182, 16, v165
	v_and_b32_e32 v183, 0xffff0000, v165
	v_lshlrev_b32_e32 v184, 16, v166
	v_and_b32_e32 v185, 0xffff0000, v166
	v_lshlrev_b32_e32 v186, 16, v167
	v_and_b32_e32 v187, 0xffff0000, v167
	v_pk_fma_f32 v[92:93], v[92:93], v[196:197], v[180:181]
	v_pk_fma_f32 v[94:95], v[94:95], v[198:199], v[182:183]
	v_pk_fma_f32 v[88:89], v[88:89], v[200:201], v[184:185]
	v_pk_fma_f32 v[90:91], v[90:91], v[202:203], v[186:187]
	v_cvt_pk_bf16_f32 v91, v90, v91
	v_cvt_pk_bf16_f32 v90, v88, v89
	v_cvt_pk_bf16_f32 v89, v94, v95
	v_cvt_pk_bf16_f32 v88, v92, v93
	v_add_u32_e32 v151, 0x20000, v148
	global_store_dwordx4 v151, v[88:91], s[42:43]
	v_lshlrev_b32_e32 v180, 16, v168
	v_and_b32_e32 v181, 0xffff0000, v168
	v_lshlrev_b32_e32 v182, 16, v169
	v_and_b32_e32 v183, 0xffff0000, v169
	v_lshlrev_b32_e32 v184, 16, v170
	v_and_b32_e32 v185, 0xffff0000, v170
	v_lshlrev_b32_e32 v186, 16, v171
	v_and_b32_e32 v187, 0xffff0000, v171
	v_pk_fma_f32 v[84:85], v[84:85], v[204:205], v[180:181]
	v_pk_fma_f32 v[86:87], v[86:87], v[206:207], v[182:183]
	v_pk_fma_f32 v[80:81], v[80:81], v[208:209], v[184:185]
	v_pk_fma_f32 v[82:83], v[82:83], v[210:211], v[186:187]
	v_cvt_pk_bf16_f32 v83, v82, v83
	v_cvt_pk_bf16_f32 v82, v80, v81
	v_cvt_pk_bf16_f32 v81, v86, v87
	v_cvt_pk_bf16_f32 v80, v84, v85
	v_add_u32_e32 v151, 0x20000, v148
	global_store_dwordx4 v151, v[80:83], s[42:43] offset:256
	v_lshlrev_b32_e32 v180, 16, v172
	v_and_b32_e32 v181, 0xffff0000, v172
	v_lshlrev_b32_e32 v182, 16, v173
	v_and_b32_e32 v183, 0xffff0000, v173
	v_lshlrev_b32_e32 v184, 16, v174
	v_and_b32_e32 v185, 0xffff0000, v174
	v_lshlrev_b32_e32 v186, 16, v175
	v_and_b32_e32 v187, 0xffff0000, v175
	v_pk_fma_f32 v[76:77], v[76:77], v[196:197], v[180:181]
	v_pk_fma_f32 v[78:79], v[78:79], v[198:199], v[182:183]
	v_pk_fma_f32 v[72:73], v[72:73], v[200:201], v[184:185]
	v_pk_fma_f32 v[74:75], v[74:75], v[202:203], v[186:187]
	v_cvt_pk_bf16_f32 v75, v74, v75
	v_cvt_pk_bf16_f32 v74, v72, v73
	v_cvt_pk_bf16_f32 v73, v78, v79
	v_cvt_pk_bf16_f32 v72, v76, v77
	v_add_u32_e32 v151, 0x30000, v148
	global_store_dwordx4 v151, v[72:75], s[42:43]
	v_lshlrev_b32_e32 v180, 16, v176
	v_and_b32_e32 v181, 0xffff0000, v176
	v_lshlrev_b32_e32 v182, 16, v177
	v_and_b32_e32 v183, 0xffff0000, v177
	v_lshlrev_b32_e32 v184, 16, v178
	v_and_b32_e32 v185, 0xffff0000, v178
	v_lshlrev_b32_e32 v186, 16, v179
	v_and_b32_e32 v187, 0xffff0000, v179
	v_pk_fma_f32 v[68:69], v[68:69], v[204:205], v[180:181]
	v_pk_fma_f32 v[70:71], v[70:71], v[206:207], v[182:183]
	v_pk_fma_f32 v[64:65], v[64:65], v[208:209], v[184:185]
	v_pk_fma_f32 v[66:67], v[66:67], v[210:211], v[186:187]
	v_cvt_pk_bf16_f32 v67, v66, v67
	v_cvt_pk_bf16_f32 v66, v64, v65
	v_cvt_pk_bf16_f32 v65, v70, v71
	v_cvt_pk_bf16_f32 v64, v68, v69
	v_add_u32_e32 v151, 0x30000, v148
	global_store_dwordx4 v151, v[64:67], s[42:43] offset:256
	v_add_u32_e32 v151, 0xa0000, v148
	global_load_dwordx4 v[164:167], v151, s[74:75]
	global_load_dwordx4 v[168:171], v151, s[74:75] offset:256
	v_add_u32_e32 v151, 0xb0000, v148
	global_load_dwordx4 v[172:175], v151, s[74:75]
	global_load_dwordx4 v[176:179], v151, s[74:75] offset:256
	s_waitcnt vmcnt(0)
	v_lshlrev_b32_e32 v180, 16, v212
	v_and_b32_e32 v181, 0xffff0000, v212
	v_lshlrev_b32_e32 v182, 16, v213
	v_and_b32_e32 v183, 0xffff0000, v213
	v_lshlrev_b32_e32 v184, 16, v214
	v_and_b32_e32 v185, 0xffff0000, v214
	v_lshlrev_b32_e32 v186, 16, v215
	v_and_b32_e32 v187, 0xffff0000, v215
	v_pk_fma_f32 v[60:61], v[60:61], v[196:197], v[180:181]
	v_pk_fma_f32 v[62:63], v[62:63], v[198:199], v[182:183]
	v_pk_fma_f32 v[56:57], v[56:57], v[200:201], v[184:185]
	v_pk_fma_f32 v[58:59], v[58:59], v[202:203], v[186:187]
	v_cvt_pk_bf16_f32 v59, v58, v59
	v_cvt_pk_bf16_f32 v58, v56, v57
	v_cvt_pk_bf16_f32 v57, v62, v63
	v_cvt_pk_bf16_f32 v56, v60, v61
	v_add_u32_e32 v151, 0x80000, v148
	global_store_dwordx4 v151, v[56:59], s[42:43]
	v_lshlrev_b32_e32 v180, 16, v216
	v_and_b32_e32 v181, 0xffff0000, v216
	v_lshlrev_b32_e32 v182, 16, v217
	v_and_b32_e32 v183, 0xffff0000, v217
	v_lshlrev_b32_e32 v184, 16, v218
	v_and_b32_e32 v185, 0xffff0000, v218
	v_lshlrev_b32_e32 v186, 16, v219
	v_and_b32_e32 v187, 0xffff0000, v219
	v_pk_fma_f32 v[52:53], v[52:53], v[204:205], v[180:181]
	v_pk_fma_f32 v[54:55], v[54:55], v[206:207], v[182:183]
	v_pk_fma_f32 v[48:49], v[48:49], v[208:209], v[184:185]
	v_pk_fma_f32 v[50:51], v[50:51], v[210:211], v[186:187]
	v_cvt_pk_bf16_f32 v51, v50, v51
	v_cvt_pk_bf16_f32 v50, v48, v49
	v_cvt_pk_bf16_f32 v49, v54, v55
	v_cvt_pk_bf16_f32 v48, v52, v53
	v_add_u32_e32 v151, 0x80000, v148
	global_store_dwordx4 v151, v[48:51], s[42:43] offset:256
	v_lshlrev_b32_e32 v180, 16, v220
	v_and_b32_e32 v181, 0xffff0000, v220
	v_lshlrev_b32_e32 v182, 16, v221
	v_and_b32_e32 v183, 0xffff0000, v221
	v_lshlrev_b32_e32 v184, 16, v222
	v_and_b32_e32 v185, 0xffff0000, v222
	v_lshlrev_b32_e32 v186, 16, v223
	v_and_b32_e32 v187, 0xffff0000, v223
	v_pk_fma_f32 v[44:45], v[44:45], v[196:197], v[180:181]
	v_pk_fma_f32 v[46:47], v[46:47], v[198:199], v[182:183]
	v_pk_fma_f32 v[40:41], v[40:41], v[200:201], v[184:185]
	v_pk_fma_f32 v[42:43], v[42:43], v[202:203], v[186:187]
	v_cvt_pk_bf16_f32 v43, v42, v43
	v_cvt_pk_bf16_f32 v42, v40, v41
	v_cvt_pk_bf16_f32 v41, v46, v47
	v_cvt_pk_bf16_f32 v40, v44, v45
	v_add_u32_e32 v151, 0x90000, v148
	global_store_dwordx4 v151, v[40:43], s[42:43]
	v_lshlrev_b32_e32 v180, 16, v224
	v_and_b32_e32 v181, 0xffff0000, v224
	v_lshlrev_b32_e32 v182, 16, v225
	v_and_b32_e32 v183, 0xffff0000, v225
	v_lshlrev_b32_e32 v184, 16, v226
	v_and_b32_e32 v185, 0xffff0000, v226
	v_lshlrev_b32_e32 v186, 16, v227
	v_and_b32_e32 v187, 0xffff0000, v227
	v_pk_fma_f32 v[36:37], v[36:37], v[204:205], v[180:181]
	v_pk_fma_f32 v[38:39], v[38:39], v[206:207], v[182:183]
	v_pk_fma_f32 v[32:33], v[32:33], v[208:209], v[184:185]
	v_pk_fma_f32 v[34:35], v[34:35], v[210:211], v[186:187]
	v_cvt_pk_bf16_f32 v35, v34, v35
	v_cvt_pk_bf16_f32 v34, v32, v33
	v_cvt_pk_bf16_f32 v33, v38, v39
	v_cvt_pk_bf16_f32 v32, v36, v37
	v_add_u32_e32 v151, 0x90000, v148
	global_store_dwordx4 v151, v[32:35], s[42:43] offset:256
	v_lshlrev_b32_e32 v180, 16, v164
	v_and_b32_e32 v181, 0xffff0000, v164
	v_lshlrev_b32_e32 v182, 16, v165
	v_and_b32_e32 v183, 0xffff0000, v165
	v_lshlrev_b32_e32 v184, 16, v166
	v_and_b32_e32 v185, 0xffff0000, v166
	v_lshlrev_b32_e32 v186, 16, v167
	v_and_b32_e32 v187, 0xffff0000, v167
	v_pk_fma_f32 v[28:29], v[28:29], v[196:197], v[180:181]
	v_pk_fma_f32 v[30:31], v[30:31], v[198:199], v[182:183]
	v_pk_fma_f32 v[24:25], v[24:25], v[200:201], v[184:185]
	v_pk_fma_f32 v[26:27], v[26:27], v[202:203], v[186:187]
	v_cvt_pk_bf16_f32 v27, v26, v27
	v_cvt_pk_bf16_f32 v26, v24, v25
	v_cvt_pk_bf16_f32 v25, v30, v31
	v_cvt_pk_bf16_f32 v24, v28, v29
	v_add_u32_e32 v151, 0xa0000, v148
	global_store_dwordx4 v151, v[24:27], s[42:43]
	v_lshlrev_b32_e32 v180, 16, v168
	v_and_b32_e32 v181, 0xffff0000, v168
	v_lshlrev_b32_e32 v182, 16, v169
	v_and_b32_e32 v183, 0xffff0000, v169
	v_lshlrev_b32_e32 v184, 16, v170
	v_and_b32_e32 v185, 0xffff0000, v170
	v_lshlrev_b32_e32 v186, 16, v171
	v_and_b32_e32 v187, 0xffff0000, v171
	v_pk_fma_f32 v[20:21], v[20:21], v[204:205], v[180:181]
	v_pk_fma_f32 v[22:23], v[22:23], v[206:207], v[182:183]
	v_pk_fma_f32 v[16:17], v[16:17], v[208:209], v[184:185]
	v_pk_fma_f32 v[18:19], v[18:19], v[210:211], v[186:187]
	v_cvt_pk_bf16_f32 v19, v18, v19
	v_cvt_pk_bf16_f32 v18, v16, v17
	v_cvt_pk_bf16_f32 v17, v22, v23
	v_cvt_pk_bf16_f32 v16, v20, v21
	v_add_u32_e32 v151, 0xa0000, v148
	global_store_dwordx4 v151, v[16:19], s[42:43] offset:256
	v_lshlrev_b32_e32 v180, 16, v172
	v_and_b32_e32 v181, 0xffff0000, v172
	v_lshlrev_b32_e32 v182, 16, v173
	v_and_b32_e32 v183, 0xffff0000, v173
	v_lshlrev_b32_e32 v184, 16, v174
	v_and_b32_e32 v185, 0xffff0000, v174
	v_lshlrev_b32_e32 v186, 16, v175
	v_and_b32_e32 v187, 0xffff0000, v175
	v_pk_fma_f32 v[12:13], v[12:13], v[196:197], v[180:181]
	v_pk_fma_f32 v[14:15], v[14:15], v[198:199], v[182:183]
	v_pk_fma_f32 v[8:9], v[8:9], v[200:201], v[184:185]
	v_pk_fma_f32 v[10:11], v[10:11], v[202:203], v[186:187]
	v_cvt_pk_bf16_f32 v11, v10, v11
	v_cvt_pk_bf16_f32 v10, v8, v9
	v_cvt_pk_bf16_f32 v9, v14, v15
	v_cvt_pk_bf16_f32 v8, v12, v13
	v_add_u32_e32 v151, 0xb0000, v148
	global_store_dwordx4 v151, v[8:11], s[42:43]
	v_lshlrev_b32_e32 v180, 16, v176
	v_and_b32_e32 v181, 0xffff0000, v176
	v_lshlrev_b32_e32 v182, 16, v177
	v_and_b32_e32 v183, 0xffff0000, v177
	v_lshlrev_b32_e32 v184, 16, v178
	v_and_b32_e32 v185, 0xffff0000, v178
	v_lshlrev_b32_e32 v186, 16, v179
	v_and_b32_e32 v187, 0xffff0000, v179
	v_pk_fma_f32 v[4:5], v[4:5], v[204:205], v[180:181]
	v_pk_fma_f32 v[6:7], v[6:7], v[206:207], v[182:183]
	v_pk_fma_f32 v[0:1], v[0:1], v[208:209], v[184:185]
	v_pk_fma_f32 v[2:3], v[2:3], v[210:211], v[186:187]
	v_cvt_pk_bf16_f32 v3, v2, v3
	v_cvt_pk_bf16_f32 v2, v0, v1
	v_cvt_pk_bf16_f32 v1, v6, v7
	v_cvt_pk_bf16_f32 v0, v4, v5
	v_add_u32_e32 v151, 0xb0000, v148
	global_store_dwordx4 v151, v[0:3], s[42:43] offset:256
.Lepi_bar_mlpout1:
	s_barrier
	s_cmp_lg_u32 s34, 0
	s_cbranch_scc1 .Lepi_g0done_mlpout1
	s_lshl_b32 s11, s24, 8
	s_add_i32 s11, s11, s34
	v_or_b32_e32 v154, s11, v145
	s_add_i32 s15, s11, 0xffffe000
	v_lshl_or_b32 v150, s33, 8, v157
	s_lshr_b32 s15, s15, 12
	v_lshlrev_b32_e32 v148, 12, v154
	s_add_i32 s15, s15, 1
	s_cmp_gt_i32 s11, s48
	s_cselect_b32 s15, s15, 0
	s_mul_i32 s15, s15, s46
	v_lshl_add_u32 v148, v150, 1, v148
	s_add_u32 s20, s6, s15
	s_addc_u32 s21, s7, 0
	v_lshlrev_b32_e32 v149, 2, v150
	s_nop 0
	global_load_dwordx4 v[196:199], v149, s[20:21]
	global_load_dwordx4 v[200:203], v149, s[20:21] offset:16
	global_load_dwordx4 v[204:207], v149, s[20:21] offset:512
	global_load_dwordx4 v[208:211], v149, s[20:21] offset:528
	global_load_dwordx4 v[212:215], v148, s[74:75]
	global_load_dwordx4 v[216:219], v148, s[74:75] offset:256
	v_add_u32_e32 v151, 0x10000, v148
	global_load_dwordx4 v[220:223], v151, s[74:75]
	global_load_dwordx4 v[224:227], v151, s[74:75] offset:256
	v_add_u32_e32 v151, 0x20000, v148
	global_load_dwordx4 v[164:167], v151, s[74:75]
	global_load_dwordx4 v[168:171], v151, s[74:75] offset:256
	v_add_u32_e32 v151, 0x30000, v148
	global_load_dwordx4 v[172:175], v151, s[74:75]
	global_load_dwordx4 v[176:179], v151, s[74:75] offset:256
	s_waitcnt vmcnt(0)
	v_lshlrev_b32_e32 v180, 16, v212
	v_and_b32_e32 v181, 0xffff0000, v212
	v_lshlrev_b32_e32 v182, 16, v213
	v_and_b32_e32 v183, 0xffff0000, v213
	v_lshlrev_b32_e32 v184, 16, v214
	v_and_b32_e32 v185, 0xffff0000, v214
	v_lshlrev_b32_e32 v186, 16, v215
	v_and_b32_e32 v187, 0xffff0000, v215
	v_pk_fma_f32 v[124:125], v[124:125], v[196:197], v[180:181]
	v_pk_fma_f32 v[126:127], v[126:127], v[198:199], v[182:183]
	v_pk_fma_f32 v[120:121], v[120:121], v[200:201], v[184:185]
	v_pk_fma_f32 v[122:123], v[122:123], v[202:203], v[186:187]
	v_cvt_pk_bf16_f32 v123, v122, v123
	v_cvt_pk_bf16_f32 v122, v120, v121
	v_cvt_pk_bf16_f32 v121, v126, v127
	v_cvt_pk_bf16_f32 v120, v124, v125
	global_store_dwordx4 v148, v[120:123], s[42:43]
	v_lshlrev_b32_e32 v180, 16, v216
	v_and_b32_e32 v181, 0xffff0000, v216
	v_lshlrev_b32_e32 v182, 16, v217
	v_and_b32_e32 v183, 0xffff0000, v217
	v_lshlrev_b32_e32 v184, 16, v218
	v_and_b32_e32 v185, 0xffff0000, v218
	v_lshlrev_b32_e32 v186, 16, v219
	v_and_b32_e32 v187, 0xffff0000, v219
	v_pk_fma_f32 v[116:117], v[116:117], v[204:205], v[180:181]
	v_pk_fma_f32 v[118:119], v[118:119], v[206:207], v[182:183]
	v_pk_fma_f32 v[112:113], v[112:113], v[208:209], v[184:185]
	v_pk_fma_f32 v[114:115], v[114:115], v[210:211], v[186:187]
	v_cvt_pk_bf16_f32 v115, v114, v115
	v_cvt_pk_bf16_f32 v114, v112, v113
	v_cvt_pk_bf16_f32 v113, v118, v119
	v_cvt_pk_bf16_f32 v112, v116, v117
	global_store_dwordx4 v148, v[112:115], s[42:43] offset:256
	v_lshlrev_b32_e32 v180, 16, v220
	v_and_b32_e32 v181, 0xffff0000, v220
	v_lshlrev_b32_e32 v182, 16, v221
	v_and_b32_e32 v183, 0xffff0000, v221
	v_lshlrev_b32_e32 v184, 16, v222
	v_and_b32_e32 v185, 0xffff0000, v222
	v_lshlrev_b32_e32 v186, 16, v223
	v_and_b32_e32 v187, 0xffff0000, v223
	v_pk_fma_f32 v[108:109], v[108:109], v[196:197], v[180:181]
	v_pk_fma_f32 v[110:111], v[110:111], v[198:199], v[182:183]
	v_pk_fma_f32 v[104:105], v[104:105], v[200:201], v[184:185]
	v_pk_fma_f32 v[106:107], v[106:107], v[202:203], v[186:187]
	v_cvt_pk_bf16_f32 v107, v106, v107
	v_cvt_pk_bf16_f32 v106, v104, v105
	v_cvt_pk_bf16_f32 v105, v110, v111
	v_cvt_pk_bf16_f32 v104, v108, v109
	v_add_u32_e32 v151, 0x10000, v148
	global_store_dwordx4 v151, v[104:107], s[42:43]
	v_lshlrev_b32_e32 v180, 16, v224
	v_and_b32_e32 v181, 0xffff0000, v224
	v_lshlrev_b32_e32 v182, 16, v225
	v_and_b32_e32 v183, 0xffff0000, v225
	v_lshlrev_b32_e32 v184, 16, v226
	v_and_b32_e32 v185, 0xffff0000, v226
	v_lshlrev_b32_e32 v186, 16, v227
	v_and_b32_e32 v187, 0xffff0000, v227
	v_pk_fma_f32 v[100:101], v[100:101], v[204:205], v[180:181]
	v_pk_fma_f32 v[102:103], v[102:103], v[206:207], v[182:183]
	v_pk_fma_f32 v[96:97], v[96:97], v[208:209], v[184:185]
	v_pk_fma_f32 v[98:99], v[98:99], v[210:211], v[186:187]
	v_cvt_pk_bf16_f32 v99, v98, v99
	v_cvt_pk_bf16_f32 v98, v96, v97
	v_cvt_pk_bf16_f32 v97, v102, v103
	v_cvt_pk_bf16_f32 v96, v100, v101
	v_add_u32_e32 v151, 0x10000, v148
	global_store_dwordx4 v151, v[96:99], s[42:43] offset:256
	v_add_u32_e32 v151, 0x80000, v148
	global_load_dwordx4 v[212:215], v151, s[74:75]
	global_load_dwordx4 v[216:219], v151, s[74:75] offset:256
	v_add_u32_e32 v151, 0x90000, v148
	global_load_dwordx4 v[220:223], v151, s[74:75]
	global_load_dwordx4 v[224:227], v151, s[74:75] offset:256
	v_lshlrev_b32_e32 v180, 16, v164
	v_and_b32_e32 v181, 0xffff0000, v164
	v_lshlrev_b32_e32 v182, 16, v165
	v_and_b32_e32 v183, 0xffff0000, v165
	v_lshlrev_b32_e32 v184, 16, v166
	v_and_b32_e32 v185, 0xffff0000, v166
	v_lshlrev_b32_e32 v186, 16, v167
	v_and_b32_e32 v187, 0xffff0000, v167
	v_pk_fma_f32 v[92:93], v[92:93], v[196:197], v[180:181]
	v_pk_fma_f32 v[94:95], v[94:95], v[198:199], v[182:183]
	v_pk_fma_f32 v[88:89], v[88:89], v[200:201], v[184:185]
	v_pk_fma_f32 v[90:91], v[90:91], v[202:203], v[186:187]
	v_cvt_pk_bf16_f32 v91, v90, v91
	v_cvt_pk_bf16_f32 v90, v88, v89
	v_cvt_pk_bf16_f32 v89, v94, v95
	v_cvt_pk_bf16_f32 v88, v92, v93
	v_add_u32_e32 v151, 0x20000, v148
	global_store_dwordx4 v151, v[88:91], s[42:43]
	v_lshlrev_b32_e32 v180, 16, v168
	v_and_b32_e32 v181, 0xffff0000, v168
	v_lshlrev_b32_e32 v182, 16, v169
	v_and_b32_e32 v183, 0xffff0000, v169
	v_lshlrev_b32_e32 v184, 16, v170
	v_and_b32_e32 v185, 0xffff0000, v170
	v_lshlrev_b32_e32 v186, 16, v171
	v_and_b32_e32 v187, 0xffff0000, v171
	v_pk_fma_f32 v[84:85], v[84:85], v[204:205], v[180:181]
	v_pk_fma_f32 v[86:87], v[86:87], v[206:207], v[182:183]
	v_pk_fma_f32 v[80:81], v[80:81], v[208:209], v[184:185]
	v_pk_fma_f32 v[82:83], v[82:83], v[210:211], v[186:187]
	v_cvt_pk_bf16_f32 v83, v82, v83
	v_cvt_pk_bf16_f32 v82, v80, v81
	v_cvt_pk_bf16_f32 v81, v86, v87
	v_cvt_pk_bf16_f32 v80, v84, v85
	v_add_u32_e32 v151, 0x20000, v148
	global_store_dwordx4 v151, v[80:83], s[42:43] offset:256
	v_lshlrev_b32_e32 v180, 16, v172
	v_and_b32_e32 v181, 0xffff0000, v172
	v_lshlrev_b32_e32 v182, 16, v173
	v_and_b32_e32 v183, 0xffff0000, v173
	v_lshlrev_b32_e32 v184, 16, v174
	v_and_b32_e32 v185, 0xffff0000, v174
	v_lshlrev_b32_e32 v186, 16, v175
	v_and_b32_e32 v187, 0xffff0000, v175
	v_pk_fma_f32 v[76:77], v[76:77], v[196:197], v[180:181]
	v_pk_fma_f32 v[78:79], v[78:79], v[198:199], v[182:183]
	v_pk_fma_f32 v[72:73], v[72:73], v[200:201], v[184:185]
	v_pk_fma_f32 v[74:75], v[74:75], v[202:203], v[186:187]
	v_cvt_pk_bf16_f32 v75, v74, v75
	v_cvt_pk_bf16_f32 v74, v72, v73
	v_cvt_pk_bf16_f32 v73, v78, v79
	v_cvt_pk_bf16_f32 v72, v76, v77
	v_add_u32_e32 v151, 0x30000, v148
	global_store_dwordx4 v151, v[72:75], s[42:43]
	v_lshlrev_b32_e32 v180, 16, v176
	v_and_b32_e32 v181, 0xffff0000, v176
	v_lshlrev_b32_e32 v182, 16, v177
	v_and_b32_e32 v183, 0xffff0000, v177
	v_lshlrev_b32_e32 v184, 16, v178
	v_and_b32_e32 v185, 0xffff0000, v178
	v_lshlrev_b32_e32 v186, 16, v179
	v_and_b32_e32 v187, 0xffff0000, v179
	v_pk_fma_f32 v[68:69], v[68:69], v[204:205], v[180:181]
	v_pk_fma_f32 v[70:71], v[70:71], v[206:207], v[182:183]
	v_pk_fma_f32 v[64:65], v[64:65], v[208:209], v[184:185]
	v_pk_fma_f32 v[66:67], v[66:67], v[210:211], v[186:187]
	v_cvt_pk_bf16_f32 v67, v66, v67
	v_cvt_pk_bf16_f32 v66, v64, v65
	v_cvt_pk_bf16_f32 v65, v70, v71
	v_cvt_pk_bf16_f32 v64, v68, v69
	v_add_u32_e32 v151, 0x30000, v148
	global_store_dwordx4 v151, v[64:67], s[42:43] offset:256
	v_add_u32_e32 v151, 0xa0000, v148
	global_load_dwordx4 v[164:167], v151, s[74:75]
	global_load_dwordx4 v[168:171], v151, s[74:75] offset:256
	v_add_u32_e32 v151, 0xb0000, v148
	global_load_dwordx4 v[172:175], v151, s[74:75]
	global_load_dwordx4 v[176:179], v151, s[74:75] offset:256
	s_waitcnt vmcnt(0)
	v_lshlrev_b32_e32 v180, 16, v212
	v_and_b32_e32 v181, 0xffff0000, v212
	v_lshlrev_b32_e32 v182, 16, v213
	v_and_b32_e32 v183, 0xffff0000, v213
	v_lshlrev_b32_e32 v184, 16, v214
	v_and_b32_e32 v185, 0xffff0000, v214
	v_lshlrev_b32_e32 v186, 16, v215
	v_and_b32_e32 v187, 0xffff0000, v215
	v_pk_fma_f32 v[60:61], v[60:61], v[196:197], v[180:181]
	v_pk_fma_f32 v[62:63], v[62:63], v[198:199], v[182:183]
	v_pk_fma_f32 v[56:57], v[56:57], v[200:201], v[184:185]
	v_pk_fma_f32 v[58:59], v[58:59], v[202:203], v[186:187]
	v_cvt_pk_bf16_f32 v59, v58, v59
	v_cvt_pk_bf16_f32 v58, v56, v57
	v_cvt_pk_bf16_f32 v57, v62, v63
	v_cvt_pk_bf16_f32 v56, v60, v61
	v_add_u32_e32 v151, 0x80000, v148
	global_store_dwordx4 v151, v[56:59], s[42:43]
	v_lshlrev_b32_e32 v180, 16, v216
	v_and_b32_e32 v181, 0xffff0000, v216
	v_lshlrev_b32_e32 v182, 16, v217
	v_and_b32_e32 v183, 0xffff0000, v217
	v_lshlrev_b32_e32 v184, 16, v218
	v_and_b32_e32 v185, 0xffff0000, v218
	v_lshlrev_b32_e32 v186, 16, v219
	v_and_b32_e32 v187, 0xffff0000, v219
	v_pk_fma_f32 v[52:53], v[52:53], v[204:205], v[180:181]
	v_pk_fma_f32 v[54:55], v[54:55], v[206:207], v[182:183]
	v_pk_fma_f32 v[48:49], v[48:49], v[208:209], v[184:185]
	v_pk_fma_f32 v[50:51], v[50:51], v[210:211], v[186:187]
	v_cvt_pk_bf16_f32 v51, v50, v51
	v_cvt_pk_bf16_f32 v50, v48, v49
	v_cvt_pk_bf16_f32 v49, v54, v55
	v_cvt_pk_bf16_f32 v48, v52, v53
	v_add_u32_e32 v151, 0x80000, v148
	global_store_dwordx4 v151, v[48:51], s[42:43] offset:256
	v_lshlrev_b32_e32 v180, 16, v220
	v_and_b32_e32 v181, 0xffff0000, v220
	v_lshlrev_b32_e32 v182, 16, v221
	v_and_b32_e32 v183, 0xffff0000, v221
	v_lshlrev_b32_e32 v184, 16, v222
	v_and_b32_e32 v185, 0xffff0000, v222
	v_lshlrev_b32_e32 v186, 16, v223
	v_and_b32_e32 v187, 0xffff0000, v223
	v_pk_fma_f32 v[44:45], v[44:45], v[196:197], v[180:181]
	v_pk_fma_f32 v[46:47], v[46:47], v[198:199], v[182:183]
	v_pk_fma_f32 v[40:41], v[40:41], v[200:201], v[184:185]
	v_pk_fma_f32 v[42:43], v[42:43], v[202:203], v[186:187]
	v_cvt_pk_bf16_f32 v43, v42, v43
	v_cvt_pk_bf16_f32 v42, v40, v41
	v_cvt_pk_bf16_f32 v41, v46, v47
	v_cvt_pk_bf16_f32 v40, v44, v45
	v_add_u32_e32 v151, 0x90000, v148
	global_store_dwordx4 v151, v[40:43], s[42:43]
	v_lshlrev_b32_e32 v180, 16, v224
	v_and_b32_e32 v181, 0xffff0000, v224
	v_lshlrev_b32_e32 v182, 16, v225
	v_and_b32_e32 v183, 0xffff0000, v225
	v_lshlrev_b32_e32 v184, 16, v226
	v_and_b32_e32 v185, 0xffff0000, v226
	v_lshlrev_b32_e32 v186, 16, v227
	v_and_b32_e32 v187, 0xffff0000, v227
	v_pk_fma_f32 v[36:37], v[36:37], v[204:205], v[180:181]
	v_pk_fma_f32 v[38:39], v[38:39], v[206:207], v[182:183]
	v_pk_fma_f32 v[32:33], v[32:33], v[208:209], v[184:185]
	v_pk_fma_f32 v[34:35], v[34:35], v[210:211], v[186:187]
	v_cvt_pk_bf16_f32 v35, v34, v35
	v_cvt_pk_bf16_f32 v34, v32, v33
	v_cvt_pk_bf16_f32 v33, v38, v39
	v_cvt_pk_bf16_f32 v32, v36, v37
	v_add_u32_e32 v151, 0x90000, v148
	global_store_dwordx4 v151, v[32:35], s[42:43] offset:256
	v_lshlrev_b32_e32 v180, 16, v164
	v_and_b32_e32 v181, 0xffff0000, v164
	v_lshlrev_b32_e32 v182, 16, v165
	v_and_b32_e32 v183, 0xffff0000, v165
	v_lshlrev_b32_e32 v184, 16, v166
	v_and_b32_e32 v185, 0xffff0000, v166
	v_lshlrev_b32_e32 v186, 16, v167
	v_and_b32_e32 v187, 0xffff0000, v167
	v_pk_fma_f32 v[28:29], v[28:29], v[196:197], v[180:181]
	v_pk_fma_f32 v[30:31], v[30:31], v[198:199], v[182:183]
	v_pk_fma_f32 v[24:25], v[24:25], v[200:201], v[184:185]
	v_pk_fma_f32 v[26:27], v[26:27], v[202:203], v[186:187]
	v_cvt_pk_bf16_f32 v27, v26, v27
	v_cvt_pk_bf16_f32 v26, v24, v25
	v_cvt_pk_bf16_f32 v25, v30, v31
	v_cvt_pk_bf16_f32 v24, v28, v29
	v_add_u32_e32 v151, 0xa0000, v148
	global_store_dwordx4 v151, v[24:27], s[42:43]
	v_lshlrev_b32_e32 v180, 16, v168
	v_and_b32_e32 v181, 0xffff0000, v168
	v_lshlrev_b32_e32 v182, 16, v169
	v_and_b32_e32 v183, 0xffff0000, v169
	v_lshlrev_b32_e32 v184, 16, v170
	v_and_b32_e32 v185, 0xffff0000, v170
	v_lshlrev_b32_e32 v186, 16, v171
	v_and_b32_e32 v187, 0xffff0000, v171
	v_pk_fma_f32 v[20:21], v[20:21], v[204:205], v[180:181]
	v_pk_fma_f32 v[22:23], v[22:23], v[206:207], v[182:183]
	v_pk_fma_f32 v[16:17], v[16:17], v[208:209], v[184:185]
	v_pk_fma_f32 v[18:19], v[18:19], v[210:211], v[186:187]
	v_cvt_pk_bf16_f32 v19, v18, v19
	v_cvt_pk_bf16_f32 v18, v16, v17
	v_cvt_pk_bf16_f32 v17, v22, v23
	v_cvt_pk_bf16_f32 v16, v20, v21
	v_add_u32_e32 v151, 0xa0000, v148
	global_store_dwordx4 v151, v[16:19], s[42:43] offset:256
	v_lshlrev_b32_e32 v180, 16, v172
	v_and_b32_e32 v181, 0xffff0000, v172
	v_lshlrev_b32_e32 v182, 16, v173
	v_and_b32_e32 v183, 0xffff0000, v173
	v_lshlrev_b32_e32 v184, 16, v174
	v_and_b32_e32 v185, 0xffff0000, v174
	v_lshlrev_b32_e32 v186, 16, v175
	v_and_b32_e32 v187, 0xffff0000, v175
	v_pk_fma_f32 v[12:13], v[12:13], v[196:197], v[180:181]
	v_pk_fma_f32 v[14:15], v[14:15], v[198:199], v[182:183]
	v_pk_fma_f32 v[8:9], v[8:9], v[200:201], v[184:185]
	v_pk_fma_f32 v[10:11], v[10:11], v[202:203], v[186:187]
	v_cvt_pk_bf16_f32 v11, v10, v11
	v_cvt_pk_bf16_f32 v10, v8, v9
	v_cvt_pk_bf16_f32 v9, v14, v15
	v_cvt_pk_bf16_f32 v8, v12, v13
	v_add_u32_e32 v151, 0xb0000, v148
	global_store_dwordx4 v151, v[8:11], s[42:43]
	v_lshlrev_b32_e32 v180, 16, v176
	v_and_b32_e32 v181, 0xffff0000, v176
	v_lshlrev_b32_e32 v182, 16, v177
	v_and_b32_e32 v183, 0xffff0000, v177
	v_lshlrev_b32_e32 v184, 16, v178
	v_and_b32_e32 v185, 0xffff0000, v178
	v_lshlrev_b32_e32 v186, 16, v179
	v_and_b32_e32 v187, 0xffff0000, v179
	v_pk_fma_f32 v[4:5], v[4:5], v[204:205], v[180:181]
	v_pk_fma_f32 v[6:7], v[6:7], v[206:207], v[182:183]
	v_pk_fma_f32 v[0:1], v[0:1], v[208:209], v[184:185]
	v_pk_fma_f32 v[2:3], v[2:3], v[210:211], v[186:187]
	v_cvt_pk_bf16_f32 v3, v2, v3
	v_cvt_pk_bf16_f32 v2, v0, v1
	v_cvt_pk_bf16_f32 v1, v6, v7
	v_cvt_pk_bf16_f32 v0, v4, v5
	v_add_u32_e32 v151, 0xb0000, v148
	global_store_dwordx4 v151, v[0:3], s[42:43] offset:256
